# baseline (speedup 1.0000x reference)
; DEVI float silu(float x) { return x * __builtin_amdgcn_rcpf(1.f + __expf(-x)); }
; template <int EPI, int NRM>
; DEVI void epilogue(acc_t& acc, int pn, int trow, const EpiArgs& e, const float* rl, bf16* shmx) {
;     ...
;   const int fl0 = wr * 64 + fq * 4;
;   const int tk0 = trow + wc * 32 + fr;
;   float rs[2][2];
;   if constexpr (NRM) {
; #pragma unroll
;     for (int bj = 0; bj < 2; ++bj)
; #pragma unroll
;       for (int n = 0; n < 2; ++n) rs[bj][n] = rl[wc * 32 + fr + bj * 128 + n * 16];
;     ...
;   } else if constexpr (EPI == EPI_SWIGLU) {
; #pragma unroll
;     for (int bj = 0; bj < 2; ++bj)
; #pragma unroll
;       for (int m = 0; m < 4; ++m)
; #pragma unroll
;         for (int n = 0; n < 2; ++n) {
;           float r[4];
; #pragma unroll
;           for (int j = 0; j < 4; ++j) r[j] = silu(acc[0][bj][m][n][j] * rs[bj][n]) * (acc[1][bj][m][n][j] * rs[bj][n]);
;           uint2 o; o.x = pack2(r[0], r[1]); o.y = pack2(r[2], r[3]);
;           const unsigned off = (unsigned)((tk0 + bj * 128 + n * 16) * DFF + pn * 128 + m * 16 + fl0);
;           *reinterpret_cast<uint2*>(e.o0 + off) = o;
;         }
.LBB0_325:
	v_and_b32_e32 v170, 15, v136
	v_bfe_u32 v171, v136, 4, 2
	v_lshrrev_b32_e32 v172, 6, v136
	v_and_b32_e32 v173, 3, v172
	v_lshrrev_b32_e32 v174, 2, v172
	v_lshlrev_b32_e32 v175, 13, v173
	v_lshl_add_u32 v175, v174, 16, v175
	v_add_u32_e32 v175, 0x8000, v175
	v_lshl_add_u32 v176, v170, 7, v175
	v_and_b32_e32 v177, 1, v171
	v_lshl_add_u32 v176, v177, 3, v176
	v_lshrrev_b32_e32 v177, 1, v171
	v_and_b32_e32 v178, 7, v170
	v_add_u32_e32 v179, 0, v177
	v_xor_b32_e32 v179, v179, v178
	v_lshl_add_u32 v164, v179, 4, v176
	v_add_u32_e32 v179, 2, v177
	v_xor_b32_e32 v179, v179, v178
	v_lshl_add_u32 v165, v179, 4, v176
	v_add_u32_e32 v179, 4, v177
	v_xor_b32_e32 v179, v179, v178
	v_lshl_add_u32 v166, v179, 4, v176
	v_add_u32_e32 v179, 6, v177
	v_xor_b32_e32 v179, v179, v178
	v_lshl_add_u32 v167, v179, 4, v176
	v_and_b32_e32 v180, 63, v136
	v_lshl_add_u32 v168, v180, 4, v175
	v_lshrrev_b32_e32 v181, 3, v180
	v_and_b32_e32 v182, 7, v180
	v_xor_b32_e32 v182, v182, v181
	s_lshl_b32 s9, s12, 8
	v_lshl_add_u32 v183, v173, 5, v181
	v_add_u32_e32 v183, s9, v183
	v_mul_u32_u24_e32 v183, 0x1600, v183
	s_lshl_b32 s9, s14, 7
	v_lshl_add_u32 v179, v174, 6, s9
	v_lshl_add_u32 v179, v182, 3, v179
	v_add_lshl_u32 v169, v183, v179, 1
	v_mov_b32_e32 v130, v136
	s_lshl_b32 s11, s16, 10
	s_and_b32 s11, s11, 0x400
	v_and_b32_e32 v141, 15, v130
	v_ashrrev_i32_e32 v142, 2, v130
	v_lshrrev_b32_e32 v143, 2, v130
	v_lshrrev_b32_e32 v130, 1, v130
	s_add_i32 s11, s11, 0
	v_and_b32_e32 v130, 0x60, v130
	s_add_i32 s11, s11, 0x20000
	v_lshlrev_b32_e32 v132, 2, v130
	v_lshlrev_b32_e32 v133, 2, v141
	v_add3_u32 v132, s11, v132, v133
	ds_read2_b32 v[134:135], v132 offset1:16
	ds_read2_b32 v[132:133], v132 offset0:128 offset1:144
	s_lshl_b32 s9, s12, 8
	v_or3_b32 v130, v141, s9, v130
	s_lshl_b32 s9, s14, 7
	v_and_b32_e32 v142, 0xffffffc0, v142
	v_and_or_b32 v141, v143, 12, s9
	s_waitcnt lgkmcnt(1)
	v_pk_mul_f32 v[122:123], v[122:123], v[134:135] op_sel_hi:[1,0]
	v_add_u32_e32 v141, v141, v142
	v_mul_f32_e32 v142, 0xbfb8aa3b, v122
	v_mul_f32_e32 v143, 0xbfb8aa3b, v123
	v_exp_f32_e32 v142, v142
	v_exp_f32_e32 v143, v143
	v_pk_mul_f32 v[126:127], v[126:127], v[134:135] op_sel_hi:[1,0]
	s_movk_i32 s9, 0x1600
	v_add_f32_e32 v142, 1.0, v142
	v_add_f32_e32 v143, 1.0, v143
	v_rcp_f32_e32 v142, v142
	v_rcp_f32_e32 v143, v143
	v_pk_mul_f32 v[106:107], v[106:107], v[134:135] op_sel_hi:[1,0]
	v_pk_mul_f32 v[110:111], v[110:111], v[134:135] op_sel_hi:[1,0]
	v_pk_mul_f32 v[108:109], v[108:109], v[134:135] op_sel_hi:[1,0]
	v_pk_mul_f32 v[122:123], v[122:123], v[142:143]
	v_pk_mul_f32 v[90:91], v[90:91], v[134:135] op_sel_hi:[1,0]
	v_pk_mul_f32 v[122:123], v[126:127], v[122:123]
	v_pk_mul_f32 v[94:95], v[94:95], v[134:135] op_sel_hi:[1,0]
	v_cvt_pk_bf16_f32 v126, v122, v123
	v_pk_mul_f32 v[122:123], v[124:125], v[134:135] op_sel_hi:[1,0]
	v_pk_mul_f32 v[92:93], v[92:93], v[134:135] op_sel_hi:[1,0]
	v_mul_f32_e32 v124, 0xbfb8aa3b, v122
	v_mul_f32_e32 v125, 0xbfb8aa3b, v123
	v_exp_f32_e32 v124, v124
	v_exp_f32_e32 v125, v125
	v_pk_mul_f32 v[74:75], v[74:75], v[134:135] op_sel_hi:[1,0]
	v_pk_mul_f32 v[78:79], v[78:79], v[134:135] op_sel_hi:[1,0]
	v_add_f32_e32 v124, 1.0, v124
	v_add_f32_e32 v125, 1.0, v125
	v_rcp_f32_e32 v124, v124
	v_rcp_f32_e32 v125, v125
	v_pk_mul_f32 v[76:77], v[76:77], v[134:135] op_sel_hi:[1,0]
	s_waitcnt lgkmcnt(0)
	v_pk_mul_f32 v[58:59], v[58:59], v[132:133] op_sel_hi:[1,0]
	v_pk_mul_f32 v[62:63], v[62:63], v[132:133] op_sel_hi:[1,0]
	v_pk_mul_f32 v[122:123], v[122:123], v[124:125]
	v_pk_mul_f32 v[124:125], v[128:129], v[134:135] op_sel_hi:[1,0]
	v_pk_mul_f32 v[42:43], v[42:43], v[132:133] op_sel_hi:[1,0]
	v_pk_mul_f32 v[122:123], v[124:125], v[122:123]
	v_pk_mul_f32 v[46:47], v[46:47], v[132:133] op_sel_hi:[1,0]
	v_cvt_pk_bf16_f32 v127, v122, v123
	v_mul_lo_u32 v123, v130, s9
	v_add_u32_e32 v130, v141, v123
	v_mov_b32_e32 v122, v135
	v_lshl_add_u64 v[124:125], v[130:131], 1, s[2:3]
	v_pk_mul_f32 v[114:115], v[114:115], v[122:123] op_sel_hi:[1,0]
	ds_write_b64 v164, v[126:127]
	v_mul_f32_e32 v124, 0xbfb8aa3b, v114
	v_mul_f32_e32 v125, 0xbfb8aa3b, v115
	v_exp_f32_e32 v124, v124
	v_exp_f32_e32 v125, v125
	v_pk_mul_f32 v[118:119], v[118:119], v[122:123] op_sel_hi:[1,0]
	v_pk_mul_f32 v[98:99], v[98:99], v[122:123] op_sel_hi:[1,0]
	v_add_f32_e32 v124, 1.0, v124
	v_add_f32_e32 v125, 1.0, v125
	v_rcp_f32_e32 v124, v124
	v_rcp_f32_e32 v125, v125
	v_pk_mul_f32 v[102:103], v[102:103], v[122:123] op_sel_hi:[1,0]
	v_pk_mul_f32 v[100:101], v[100:101], v[122:123] op_sel_hi:[1,0]
	v_pk_mul_f32 v[82:83], v[82:83], v[122:123] op_sel_hi:[1,0]
	v_pk_mul_f32 v[114:115], v[114:115], v[124:125]
	v_pk_mul_f32 v[86:87], v[86:87], v[122:123] op_sel_hi:[1,0]
	v_pk_mul_f32 v[114:115], v[118:119], v[114:115]
	v_pk_mul_f32 v[84:85], v[84:85], v[122:123] op_sel_hi:[1,0]
	v_cvt_pk_bf16_f32 v118, v114, v115
	v_pk_mul_f32 v[114:115], v[116:117], v[122:123] op_sel_hi:[1,0]
	v_pk_mul_f32 v[66:67], v[66:67], v[122:123] op_sel_hi:[1,0]
	v_mul_f32_e32 v116, 0xbfb8aa3b, v114
	v_mul_f32_e32 v117, 0xbfb8aa3b, v115
	v_exp_f32_e32 v116, v116
	v_exp_f32_e32 v117, v117
	v_pk_mul_f32 v[70:71], v[70:71], v[122:123] op_sel_hi:[1,0]
	v_pk_mul_f32 v[68:69], v[68:69], v[122:123] op_sel_hi:[1,0]
	v_add_f32_e32 v116, 1.0, v116
	v_add_f32_e32 v117, 1.0, v117
	v_rcp_f32_e32 v116, v116
	v_rcp_f32_e32 v117, v117
	v_pk_mul_f32 v[44:45], v[44:45], v[132:133] op_sel_hi:[1,0]
	v_pk_mul_f32 v[26:27], v[26:27], v[132:133] op_sel_hi:[1,0]
	v_pk_mul_f32 v[30:31], v[30:31], v[132:133] op_sel_hi:[1,0]
	v_pk_mul_f32 v[114:115], v[114:115], v[116:117]
	v_pk_mul_f32 v[116:117], v[120:121], v[122:123] op_sel_hi:[1,0]
; DEVI float silu(float x) { return x * __builtin_amdgcn_rcpf(1.f + __expf(-x)); }
; template <int EPI, int NRM>
; DEVI void epilogue(acc_t& acc, int pn, int trow, const EpiArgs& e, const float* rl, bf16* shmx) {
;     ...
;   } else if constexpr (EPI == EPI_SWIGLU) {
; #pragma unroll
;     for (int bj = 0; bj < 2; ++bj)
; #pragma unroll
;       for (int m = 0; m < 4; ++m)
; #pragma unroll
;         for (int n = 0; n < 2; ++n) {
;           float r[4];
; #pragma unroll
;           for (int j = 0; j < 4; ++j) r[j] = silu(acc[0][bj][m][n][j] * rs[bj][n]) * (acc[1][bj][m][n][j] * rs[bj][n]);
;           uint2 o; o.x = pack2(r[0], r[1]); o.y = pack2(r[2], r[3]);
;           const unsigned off = (unsigned)((tk0 + bj * 128 + n * 16) * DFF + pn * 128 + m * 16 + fl0);
;           *reinterpret_cast<uint2*>(e.o0 + off) = o;
;         }
	v_pk_mul_f32 v[28:29], v[28:29], v[132:133] op_sel_hi:[1,0]
	v_pk_mul_f32 v[114:115], v[116:117], v[114:115]
	v_pk_mul_f32 v[10:11], v[10:11], v[132:133] op_sel_hi:[1,0]
	v_cvt_pk_bf16_f32 v119, v114, v115
	v_add_u32_e32 v115, 0x16000, v123
	v_add_u32_e32 v130, v115, v141
	v_lshl_add_u64 v[116:117], v[130:131], 1, s[2:3]
	ds_write_b64 v164, v[118:119] offset:2048
	v_mul_f32_e32 v116, 0xbfb8aa3b, v106
	v_mul_f32_e32 v117, 0xbfb8aa3b, v107
	v_exp_f32_e32 v116, v116
	v_exp_f32_e32 v117, v117
	v_or_b32_e32 v114, 16, v141
	v_add_u32_e32 v130, v114, v123
	v_add_f32_e32 v116, 1.0, v116
	v_add_f32_e32 v117, 1.0, v117
	v_rcp_f32_e32 v116, v116
	v_rcp_f32_e32 v117, v117
	v_pk_mul_f32 v[14:15], v[14:15], v[132:133] op_sel_hi:[1,0]
	v_pk_mul_f32 v[12:13], v[12:13], v[132:133] op_sel_hi:[1,0]
	s_add_i32 s16, s16, 1
	v_pk_mul_f32 v[106:107], v[106:107], v[116:117]
	s_andn2_b64 vcc, exec, s[4:5]
	v_pk_mul_f32 v[106:107], v[110:111], v[106:107]
	s_mov_b32 s14, s8
	v_cvt_pk_bf16_f32 v106, v106, v107
	v_mul_f32_e32 v107, 0xbfb8aa3b, v108
	v_exp_f32_e32 v107, v107
	s_mov_b32 s12, s10
	v_add_f32_e32 v107, 1.0, v107
	v_rcp_f32_e32 v110, v107
	v_mul_f32_e32 v107, 0xbfb8aa3b, v109
	v_exp_f32_e32 v107, v107
	s_nop 0
	v_add_f32_e32 v107, 1.0, v107
	v_rcp_f32_e32 v111, v107
	s_nop 0
	v_pk_mul_f32 v[108:109], v[108:109], v[110:111]
	v_pk_mul_f32 v[110:111], v[112:113], v[134:135] op_sel_hi:[1,0]
	s_nop 0
	v_pk_mul_f32 v[108:109], v[110:111], v[108:109]
	s_nop 0
	v_cvt_pk_bf16_f32 v107, v108, v109
	v_lshl_add_u64 v[108:109], v[130:131], 1, s[2:3]
	ds_write_b64 v165, v[106:107]
	v_mul_f32_e32 v106, 0xbfb8aa3b, v98
	v_mul_f32_e32 v107, 0xbfb8aa3b, v99
	v_exp_f32_e32 v106, v106
	v_exp_f32_e32 v107, v107
	v_add_u32_e32 v130, v114, v115
	v_add_f32_e32 v106, 1.0, v106
	v_add_f32_e32 v107, 1.0, v107
	v_rcp_f32_e32 v106, v106
	v_rcp_f32_e32 v107, v107
	s_nop 0
	v_pk_mul_f32 v[98:99], v[98:99], v[106:107]
	s_nop 0
	v_pk_mul_f32 v[98:99], v[102:103], v[98:99]
	s_nop 0
	v_cvt_pk_bf16_f32 v98, v98, v99
	v_mul_f32_e32 v99, 0xbfb8aa3b, v100
	v_exp_f32_e32 v99, v99
	s_nop 0
	v_add_f32_e32 v99, 1.0, v99
	v_rcp_f32_e32 v102, v99
	v_mul_f32_e32 v99, 0xbfb8aa3b, v101
	v_exp_f32_e32 v99, v99
	s_nop 0
	v_add_f32_e32 v99, 1.0, v99
	v_rcp_f32_e32 v103, v99
	s_nop 0
	v_pk_mul_f32 v[100:101], v[100:101], v[102:103]
	v_pk_mul_f32 v[102:103], v[104:105], v[122:123] op_sel_hi:[1,0]
	s_nop 0
	v_pk_mul_f32 v[100:101], v[102:103], v[100:101]
	s_nop 0
	v_cvt_pk_bf16_f32 v99, v100, v101
	v_lshl_add_u64 v[100:101], v[130:131], 1, s[2:3]
	ds_write_b64 v165, v[98:99] offset:2048
	v_mul_f32_e32 v99, 0xbfb8aa3b, v90
	v_exp_f32_e32 v99, v99
	v_or_b32_e32 v98, 32, v141
	v_add_u32_e32 v130, v98, v123
	v_add_f32_e32 v99, 1.0, v99
	v_rcp_f32_e32 v100, v99
	v_mul_f32_e32 v99, 0xbfb8aa3b, v91
	v_exp_f32_e32 v99, v99
	s_nop 0
	v_add_f32_e32 v99, 1.0, v99
	v_rcp_f32_e32 v101, v99
	s_nop 0
	v_pk_mul_f32 v[90:91], v[90:91], v[100:101]
	s_nop 0
	v_pk_mul_f32 v[90:91], v[94:95], v[90:91]
	s_nop 0
	v_cvt_pk_bf16_f32 v90, v90, v91
	v_mul_f32_e32 v91, 0xbfb8aa3b, v92
	v_exp_f32_e32 v91, v91
	s_nop 0
	v_add_f32_e32 v91, 1.0, v91
	v_rcp_f32_e32 v94, v91
	v_mul_f32_e32 v91, 0xbfb8aa3b, v93
	v_exp_f32_e32 v91, v91
	s_nop 0
	v_add_f32_e32 v91, 1.0, v91
	v_rcp_f32_e32 v95, v91
	s_nop 0
	v_pk_mul_f32 v[92:93], v[92:93], v[94:95]
	v_pk_mul_f32 v[94:95], v[96:97], v[134:135] op_sel_hi:[1,0]
	s_nop 0
	v_pk_mul_f32 v[92:93], v[94:95], v[92:93]
	s_nop 0
	v_cvt_pk_bf16_f32 v91, v92, v93
	v_lshl_add_u64 v[92:93], v[130:131], 1, s[2:3]
	ds_write_b64 v166, v[90:91]
	v_mul_f32_e32 v90, 0xbfb8aa3b, v82
	v_mul_f32_e32 v91, 0xbfb8aa3b, v83
	v_exp_f32_e32 v90, v90
	v_exp_f32_e32 v91, v91
	v_add_u32_e32 v130, v98, v115
	v_add_f32_e32 v90, 1.0, v90
	v_add_f32_e32 v91, 1.0, v91
	v_rcp_f32_e32 v90, v90
	v_rcp_f32_e32 v91, v91
	s_nop 0
	v_pk_mul_f32 v[82:83], v[82:83], v[90:91]
	s_nop 0
	v_pk_mul_f32 v[82:83], v[86:87], v[82:83]
	s_nop 0
	v_cvt_pk_bf16_f32 v82, v82, v83
	v_mul_f32_e32 v83, 0xbfb8aa3b, v84
	v_exp_f32_e32 v83, v83
	s_nop 0
	v_add_f32_e32 v83, 1.0, v83
	v_rcp_f32_e32 v86, v83
	v_mul_f32_e32 v83, 0xbfb8aa3b, v85
	v_exp_f32_e32 v83, v83
	s_nop 0
	v_add_f32_e32 v83, 1.0, v83
	v_rcp_f32_e32 v87, v83
	s_nop 0
	v_pk_mul_f32 v[84:85], v[84:85], v[86:87]
	v_pk_mul_f32 v[86:87], v[88:89], v[122:123] op_sel_hi:[1,0]
	s_nop 0
	v_pk_mul_f32 v[84:85], v[86:87], v[84:85]
	s_nop 0
	v_cvt_pk_bf16_f32 v83, v84, v85
	v_lshl_add_u64 v[84:85], v[130:131], 1, s[2:3]
	ds_write_b64 v166, v[82:83] offset:2048
	v_mul_f32_e32 v83, 0xbfb8aa3b, v74
	v_exp_f32_e32 v83, v83
	v_or_b32_e32 v82, 48, v141
	v_add_u32_e32 v130, v82, v123
	v_add_f32_e32 v83, 1.0, v83
	v_rcp_f32_e32 v84, v83
	v_mul_f32_e32 v83, 0xbfb8aa3b, v75
	v_exp_f32_e32 v83, v83
	s_nop 0
	v_add_f32_e32 v83, 1.0, v83
	v_rcp_f32_e32 v85, v83
	s_nop 0
	v_pk_mul_f32 v[74:75], v[74:75], v[84:85]
	s_nop 0
	v_pk_mul_f32 v[74:75], v[78:79], v[74:75]
	s_nop 0
	v_cvt_pk_bf16_f32 v74, v74, v75
	v_mul_f32_e32 v75, 0xbfb8aa3b, v76
	v_exp_f32_e32 v75, v75
	s_nop 0
	v_add_f32_e32 v75, 1.0, v75
	v_rcp_f32_e32 v78, v75
	v_mul_f32_e32 v75, 0xbfb8aa3b, v77
	v_exp_f32_e32 v75, v75
	s_nop 0
	v_add_f32_e32 v75, 1.0, v75
	v_rcp_f32_e32 v79, v75
	s_nop 0
	v_pk_mul_f32 v[76:77], v[76:77], v[78:79]
	v_pk_mul_f32 v[78:79], v[80:81], v[134:135] op_sel_hi:[1,0]
	s_nop 0
	v_pk_mul_f32 v[76:77], v[78:79], v[76:77]
	s_nop 0
	v_cvt_pk_bf16_f32 v75, v76, v77
	v_lshl_add_u64 v[76:77], v[130:131], 1, s[2:3]
	ds_write_b64 v167, v[74:75]
	v_mul_f32_e32 v74, 0xbfb8aa3b, v66
	v_mul_f32_e32 v75, 0xbfb8aa3b, v67
	v_exp_f32_e32 v74, v74
	v_exp_f32_e32 v75, v75
	v_add_u32_e32 v130, v82, v115
	v_add_f32_e32 v74, 1.0, v74
	v_add_f32_e32 v75, 1.0, v75
	v_rcp_f32_e32 v74, v74
	v_rcp_f32_e32 v75, v75
	s_nop 0
	v_pk_mul_f32 v[66:67], v[66:67], v[74:75]
	s_nop 0
	v_pk_mul_f32 v[66:67], v[70:71], v[66:67]
	s_nop 0
	v_cvt_pk_bf16_f32 v66, v66, v67
	v_mul_f32_e32 v67, 0xbfb8aa3b, v68
	v_exp_f32_e32 v67, v67
	s_nop 0
	v_add_f32_e32 v67, 1.0, v67
	v_rcp_f32_e32 v70, v67
	v_mul_f32_e32 v67, 0xbfb8aa3b, v69
	v_exp_f32_e32 v67, v67
	s_nop 0
	v_add_f32_e32 v67, 1.0, v67
	v_rcp_f32_e32 v71, v67
	s_nop 0
	v_pk_mul_f32 v[68:69], v[68:69], v[70:71]
	v_pk_mul_f32 v[70:71], v[72:73], v[122:123] op_sel_hi:[1,0]
	s_nop 0
	v_pk_mul_f32 v[68:69], v[70:71], v[68:69]
	s_nop 0
	v_cvt_pk_bf16_f32 v67, v68, v69
	v_lshl_add_u64 v[68:69], v[130:131], 1, s[2:3]
	ds_write_b64 v167, v[66:67] offset:2048
	s_waitcnt lgkmcnt(0)
; DEVI float silu(float x) { return x * __builtin_amdgcn_rcpf(1.f + __expf(-x)); }
; template <int EPI, int NRM>
; DEVI void epilogue(acc_t& acc, int pn, int trow, const EpiArgs& e, const float* rl, bf16* shmx) {
;     ...
;   } else if constexpr (EPI == EPI_SWIGLU) {
; #pragma unroll
;     for (int bj = 0; bj < 2; ++bj)
; #pragma unroll
;       for (int m = 0; m < 4; ++m)
; #pragma unroll
;         for (int n = 0; n < 2; ++n) {
;           float r[4];
; #pragma unroll
;           for (int j = 0; j < 4; ++j) r[j] = silu(acc[0][bj][m][n][j] * rs[bj][n]) * (acc[1][bj][m][n][j] * rs[bj][n]);
;           uint2 o; o.x = pack2(r[0], r[1]); o.y = pack2(r[2], r[3]);
;           const unsigned off = (unsigned)((tk0 + bj * 128 + n * 16) * DFF + pn * 128 + m * 16 + fl0);
;           *reinterpret_cast<uint2*>(e.o0 + off) = o;
;         }
	ds_read_b128 v[172:175], v168
	ds_read_b128 v[176:179], v168 offset:1024
	ds_read_b128 v[180:183], v168 offset:2048
	ds_read_b128 v[184:187], v168 offset:3072
	v_add_u32_e32 v204, 0x16000, v169
	v_add_u32_e32 v205, 0x2c000, v169
	v_add_u32_e32 v206, 0x42000, v169
	s_waitcnt lgkmcnt(3)
	global_store_dwordx4 v169, v[172:175], s[2:3] nt
	s_waitcnt lgkmcnt(2)
	global_store_dwordx4 v204, v[176:179], s[2:3] nt
	s_waitcnt lgkmcnt(1)
	global_store_dwordx4 v205, v[180:183], s[2:3] nt
	s_waitcnt lgkmcnt(0)
	global_store_dwordx4 v206, v[184:187], s[2:3] nt
	v_mul_f32_e32 v66, 0xbfb8aa3b, v58
	v_mul_f32_e32 v67, 0xbfb8aa3b, v59
	v_exp_f32_e32 v66, v66
	v_exp_f32_e32 v67, v67
	v_add_f32_e32 v66, 1.0, v66
	v_add_f32_e32 v67, 1.0, v67
	v_rcp_f32_e32 v66, v66
	v_rcp_f32_e32 v67, v67
	s_nop 0
	v_pk_mul_f32 v[58:59], v[58:59], v[66:67]
	s_nop 0
	v_pk_mul_f32 v[58:59], v[62:63], v[58:59]
	s_nop 0
	v_cvt_pk_bf16_f32 v62, v58, v59
	v_pk_mul_f32 v[58:59], v[60:61], v[132:133] op_sel_hi:[1,0]
	s_nop 0
	v_mul_f32_e32 v60, 0xbfb8aa3b, v58
	v_mul_f32_e32 v61, 0xbfb8aa3b, v59
	v_exp_f32_e32 v60, v60
	v_exp_f32_e32 v61, v61
	v_add_f32_e32 v60, 1.0, v60
	v_add_f32_e32 v61, 1.0, v61
	v_rcp_f32_e32 v60, v60
	v_rcp_f32_e32 v61, v61
	s_nop 0
	v_pk_mul_f32 v[58:59], v[58:59], v[60:61]
	v_pk_mul_f32 v[60:61], v[64:65], v[132:133] op_sel_hi:[1,0]
	s_nop 0
	v_pk_mul_f32 v[58:59], v[60:61], v[58:59]
	s_nop 0
	v_cvt_pk_bf16_f32 v63, v58, v59
	v_add_u32_e32 v59, 0xb0000, v123
	v_add_u32_e32 v130, v59, v141
	v_mov_b32_e32 v58, v133
	v_lshl_add_u64 v[60:61], v[130:131], 1, s[2:3]
	v_pk_mul_f32 v[50:51], v[50:51], v[58:59] op_sel_hi:[1,0]
	ds_write_b64 v164, v[62:63] offset:4096
	v_mul_f32_e32 v60, 0xbfb8aa3b, v50
	v_mul_f32_e32 v61, 0xbfb8aa3b, v51
	v_exp_f32_e32 v60, v60
	v_exp_f32_e32 v61, v61
	v_pk_mul_f32 v[54:55], v[54:55], v[58:59] op_sel_hi:[1,0]
	v_pk_mul_f32 v[34:35], v[34:35], v[58:59] op_sel_hi:[1,0]
	v_add_f32_e32 v60, 1.0, v60
	v_add_f32_e32 v61, 1.0, v61
	v_rcp_f32_e32 v60, v60
	v_rcp_f32_e32 v61, v61
	v_pk_mul_f32 v[38:39], v[38:39], v[58:59] op_sel_hi:[1,0]
	v_pk_mul_f32 v[36:37], v[36:37], v[58:59] op_sel_hi:[1,0]
	v_pk_mul_f32 v[18:19], v[18:19], v[58:59] op_sel_hi:[1,0]
	v_pk_mul_f32 v[50:51], v[50:51], v[60:61]
	v_pk_mul_f32 v[22:23], v[22:23], v[58:59] op_sel_hi:[1,0]
	v_pk_mul_f32 v[50:51], v[54:55], v[50:51]
	v_pk_mul_f32 v[20:21], v[20:21], v[58:59] op_sel_hi:[1,0]
	v_cvt_pk_bf16_f32 v54, v50, v51
	v_pk_mul_f32 v[50:51], v[52:53], v[58:59] op_sel_hi:[1,0]
	v_pk_mul_f32 v[2:3], v[2:3], v[58:59] op_sel_hi:[1,0]
	v_mul_f32_e32 v52, 0xbfb8aa3b, v50
	v_mul_f32_e32 v53, 0xbfb8aa3b, v51
	v_exp_f32_e32 v52, v52
	v_exp_f32_e32 v53, v53
	v_pk_mul_f32 v[6:7], v[6:7], v[58:59] op_sel_hi:[1,0]
	v_pk_mul_f32 v[4:5], v[4:5], v[58:59] op_sel_hi:[1,0]
	v_add_f32_e32 v52, 1.0, v52
	v_add_f32_e32 v53, 1.0, v53
	v_rcp_f32_e32 v52, v52
	v_rcp_f32_e32 v53, v53
	s_nop 0
	v_pk_mul_f32 v[50:51], v[50:51], v[52:53]
	v_pk_mul_f32 v[52:53], v[56:57], v[58:59] op_sel_hi:[1,0]
	s_nop 0
	v_pk_mul_f32 v[50:51], v[52:53], v[50:51]
	s_nop 0
	v_cvt_pk_bf16_f32 v55, v50, v51
	v_mul_f32_e32 v51, 0xbfb8aa3b, v42
	v_exp_f32_e32 v51, v51
	v_add_u32_e32 v50, 0xc6000, v123
	v_add_u32_e32 v130, v50, v141
	v_lshl_add_u64 v[52:53], v[130:131], 1, s[2:3]
	v_add_f32_e32 v51, 1.0, v51
	ds_write_b64 v164, v[54:55] offset:6144
	v_rcp_f32_e32 v52, v51
	v_mul_f32_e32 v51, 0xbfb8aa3b, v43
	v_exp_f32_e32 v51, v51
	v_add_u32_e32 v130, v114, v59
	v_add_f32_e32 v51, 1.0, v51
	v_rcp_f32_e32 v53, v51
	s_nop 0
	v_pk_mul_f32 v[42:43], v[42:43], v[52:53]
	s_nop 0
	v_pk_mul_f32 v[42:43], v[46:47], v[42:43]
	s_nop 0
	v_cvt_pk_bf16_f32 v42, v42, v43
	v_mul_f32_e32 v43, 0xbfb8aa3b, v44
	v_exp_f32_e32 v43, v43
	s_nop 0
	v_add_f32_e32 v43, 1.0, v43
	v_rcp_f32_e32 v46, v43
	v_mul_f32_e32 v43, 0xbfb8aa3b, v45
	v_exp_f32_e32 v43, v43
	s_nop 0
	v_add_f32_e32 v43, 1.0, v43
	v_rcp_f32_e32 v47, v43
	s_nop 0
	v_pk_mul_f32 v[44:45], v[44:45], v[46:47]
	v_pk_mul_f32 v[46:47], v[48:49], v[132:133] op_sel_hi:[1,0]
	s_nop 0
	v_pk_mul_f32 v[44:45], v[46:47], v[44:45]
	s_nop 0
	v_cvt_pk_bf16_f32 v43, v44, v45
	v_lshl_add_u64 v[44:45], v[130:131], 1, s[2:3]
	ds_write_b64 v165, v[42:43] offset:4096
	v_mul_f32_e32 v42, 0xbfb8aa3b, v34
	v_mul_f32_e32 v43, 0xbfb8aa3b, v35
	v_exp_f32_e32 v42, v42
	v_exp_f32_e32 v43, v43
	v_add_u32_e32 v130, v114, v50
	v_add_f32_e32 v42, 1.0, v42
	v_add_f32_e32 v43, 1.0, v43
	v_rcp_f32_e32 v42, v42
	v_rcp_f32_e32 v43, v43
	s_nop 0
	v_pk_mul_f32 v[34:35], v[34:35], v[42:43]
	s_nop 0
	v_pk_mul_f32 v[34:35], v[38:39], v[34:35]
	s_nop 0
	v_cvt_pk_bf16_f32 v34, v34, v35
	v_mul_f32_e32 v35, 0xbfb8aa3b, v36
	v_exp_f32_e32 v35, v35
	s_nop 0
	v_add_f32_e32 v35, 1.0, v35
	v_rcp_f32_e32 v38, v35
	v_mul_f32_e32 v35, 0xbfb8aa3b, v37
	v_exp_f32_e32 v35, v35
	s_nop 0
	v_add_f32_e32 v35, 1.0, v35
	v_rcp_f32_e32 v39, v35
	s_nop 0
	v_pk_mul_f32 v[36:37], v[36:37], v[38:39]
	v_pk_mul_f32 v[38:39], v[40:41], v[58:59] op_sel_hi:[1,0]
	s_nop 0
	v_pk_mul_f32 v[36:37], v[38:39], v[36:37]
	s_nop 0
	v_cvt_pk_bf16_f32 v35, v36, v37
	v_lshl_add_u64 v[36:37], v[130:131], 1, s[2:3]
	ds_write_b64 v165, v[34:35] offset:6144
	v_mul_f32_e32 v34, 0xbfb8aa3b, v26
	v_mul_f32_e32 v35, 0xbfb8aa3b, v27
	v_exp_f32_e32 v34, v34
	v_exp_f32_e32 v35, v35
	v_add_u32_e32 v130, v98, v59
	v_add_f32_e32 v34, 1.0, v34
	v_add_f32_e32 v35, 1.0, v35
	v_rcp_f32_e32 v34, v34
	v_rcp_f32_e32 v35, v35
	s_nop 0
	v_pk_mul_f32 v[26:27], v[26:27], v[34:35]
	s_nop 0
	v_pk_mul_f32 v[26:27], v[30:31], v[26:27]
	s_nop 0
	v_cvt_pk_bf16_f32 v26, v26, v27
	v_mul_f32_e32 v27, 0xbfb8aa3b, v28
	v_exp_f32_e32 v27, v27
	s_nop 0
	v_add_f32_e32 v27, 1.0, v27
	v_rcp_f32_e32 v30, v27
; DEVI float silu(float x) { return x * __builtin_amdgcn_rcpf(1.f + __expf(-x)); }
; template <int EPI, int NRM>
; DEVI void epilogue(acc_t& acc, int pn, int trow, const EpiArgs& e, const float* rl, bf16* shmx) {
;     ...
;   } else if constexpr (EPI == EPI_SWIGLU) {
; #pragma unroll
;     for (int bj = 0; bj < 2; ++bj)
; #pragma unroll
;       for (int m = 0; m < 4; ++m)
; #pragma unroll
;         for (int n = 0; n < 2; ++n) {
;           float r[4];
; #pragma unroll
;           for (int j = 0; j < 4; ++j) r[j] = silu(acc[0][bj][m][n][j] * rs[bj][n]) * (acc[1][bj][m][n][j] * rs[bj][n]);
;           uint2 o; o.x = pack2(r[0], r[1]); o.y = pack2(r[2], r[3]);
;           const unsigned off = (unsigned)((tk0 + bj * 128 + n * 16) * DFF + pn * 128 + m * 16 + fl0);
;           *reinterpret_cast<uint2*>(e.o0 + off) = o;
;         }
	v_mul_f32_e32 v27, 0xbfb8aa3b, v29
	v_exp_f32_e32 v27, v27
	s_nop 0
	v_add_f32_e32 v27, 1.0, v27
	v_rcp_f32_e32 v31, v27
	s_nop 0
	v_pk_mul_f32 v[28:29], v[28:29], v[30:31]
	v_pk_mul_f32 v[30:31], v[32:33], v[132:133] op_sel_hi:[1,0]
	s_nop 0
	v_pk_mul_f32 v[28:29], v[30:31], v[28:29]
	s_nop 0
	v_cvt_pk_bf16_f32 v27, v28, v29
	v_lshl_add_u64 v[28:29], v[130:131], 1, s[2:3]
	ds_write_b64 v166, v[26:27] offset:4096
	v_mul_f32_e32 v26, 0xbfb8aa3b, v18
	v_mul_f32_e32 v27, 0xbfb8aa3b, v19
	v_exp_f32_e32 v26, v26
	v_exp_f32_e32 v27, v27
	v_add_u32_e32 v130, v98, v50
	v_add_f32_e32 v26, 1.0, v26
	v_add_f32_e32 v27, 1.0, v27
	v_rcp_f32_e32 v26, v26
	v_rcp_f32_e32 v27, v27
	s_nop 0
	v_pk_mul_f32 v[18:19], v[18:19], v[26:27]
	s_nop 0
	v_pk_mul_f32 v[18:19], v[22:23], v[18:19]
	s_nop 0
	v_cvt_pk_bf16_f32 v18, v18, v19
	v_mul_f32_e32 v19, 0xbfb8aa3b, v20
	v_exp_f32_e32 v19, v19
	s_nop 0
	v_add_f32_e32 v19, 1.0, v19
	v_rcp_f32_e32 v22, v19
	v_mul_f32_e32 v19, 0xbfb8aa3b, v21
	v_exp_f32_e32 v19, v19
	s_nop 0
	v_add_f32_e32 v19, 1.0, v19
	v_rcp_f32_e32 v23, v19
	s_nop 0
	v_pk_mul_f32 v[20:21], v[20:21], v[22:23]
	v_pk_mul_f32 v[22:23], v[24:25], v[58:59] op_sel_hi:[1,0]
	s_nop 0
	v_pk_mul_f32 v[20:21], v[22:23], v[20:21]
	s_nop 0
	v_cvt_pk_bf16_f32 v19, v20, v21
	v_lshl_add_u64 v[20:21], v[130:131], 1, s[2:3]
	ds_write_b64 v166, v[18:19] offset:6144
	v_mul_f32_e32 v18, 0xbfb8aa3b, v10
	v_mul_f32_e32 v19, 0xbfb8aa3b, v11
	v_exp_f32_e32 v18, v18
	v_exp_f32_e32 v19, v19
	v_add_u32_e32 v130, v82, v59
	v_add_f32_e32 v18, 1.0, v18
	v_add_f32_e32 v19, 1.0, v19
	v_rcp_f32_e32 v18, v18
	v_rcp_f32_e32 v19, v19
	s_nop 0
	v_pk_mul_f32 v[10:11], v[10:11], v[18:19]
	s_nop 0
	v_pk_mul_f32 v[10:11], v[14:15], v[10:11]
	s_nop 0
	v_cvt_pk_bf16_f32 v10, v10, v11
	v_mul_f32_e32 v11, 0xbfb8aa3b, v12
	v_exp_f32_e32 v11, v11
	s_nop 0
	v_add_f32_e32 v11, 1.0, v11
	v_rcp_f32_e32 v14, v11
	v_mul_f32_e32 v11, 0xbfb8aa3b, v13
	v_exp_f32_e32 v11, v11
	s_nop 0
	v_add_f32_e32 v11, 1.0, v11
	v_rcp_f32_e32 v15, v11
	s_nop 0
	v_pk_mul_f32 v[12:13], v[12:13], v[14:15]
	v_pk_mul_f32 v[14:15], v[16:17], v[132:133] op_sel_hi:[1,0]
	s_nop 0
	v_pk_mul_f32 v[12:13], v[14:15], v[12:13]
	s_nop 0
	v_cvt_pk_bf16_f32 v11, v12, v13
	v_lshl_add_u64 v[12:13], v[130:131], 1, s[2:3]
	ds_write_b64 v167, v[10:11] offset:4096
	v_mul_f32_e32 v10, 0xbfb8aa3b, v2
	v_mul_f32_e32 v11, 0xbfb8aa3b, v3
	v_exp_f32_e32 v10, v10
	v_exp_f32_e32 v11, v11
	v_add_u32_e32 v130, v82, v50
	v_add_f32_e32 v10, 1.0, v10
	v_add_f32_e32 v11, 1.0, v11
	v_rcp_f32_e32 v10, v10
	v_rcp_f32_e32 v11, v11
	s_nop 0
	v_pk_mul_f32 v[2:3], v[2:3], v[10:11]
	s_nop 0
	v_pk_mul_f32 v[2:3], v[6:7], v[2:3]
	s_nop 0
	v_cvt_pk_bf16_f32 v2, v2, v3
	v_mul_f32_e32 v3, 0xbfb8aa3b, v4
	v_exp_f32_e32 v3, v3
	s_nop 0
	v_add_f32_e32 v3, 1.0, v3
	v_rcp_f32_e32 v6, v3
	v_mul_f32_e32 v3, 0xbfb8aa3b, v5
	v_exp_f32_e32 v3, v3
	s_nop 0
	v_add_f32_e32 v3, 1.0, v3
	v_rcp_f32_e32 v7, v3
	s_nop 0
	v_pk_mul_f32 v[4:5], v[4:5], v[6:7]
	v_pk_mul_f32 v[6:7], v[8:9], v[58:59] op_sel_hi:[1,0]
	s_nop 0
	v_pk_mul_f32 v[4:5], v[6:7], v[4:5]
	s_nop 0
	v_cvt_pk_bf16_f32 v3, v4, v5
	v_lshl_add_u64 v[4:5], v[130:131], 1, s[2:3]
	ds_write_b64 v167, v[2:3] offset:6144
	s_waitcnt lgkmcnt(0)
	ds_read_b128 v[172:175], v168
	ds_read_b128 v[176:179], v168 offset:1024
	ds_read_b128 v[180:183], v168 offset:2048
	ds_read_b128 v[184:187], v168 offset:3072
	ds_read_b128 v[188:191], v168 offset:4096
	ds_read_b128 v[192:195], v168 offset:5120
	ds_read_b128 v[196:199], v168 offset:6144
	ds_read_b128 v[200:203], v168 offset:7168
	v_add_u32_e32 v204, 0x16000, v169
	v_add_u32_e32 v205, 0x2c000, v169
	v_add_u32_e32 v206, 0x42000, v169
	v_add_u32_e32 v207, 0x160000, v169
	v_add_u32_e32 v208, 0x176000, v169
	v_add_u32_e32 v209, 0x18c000, v169
	v_add_u32_e32 v210, 0x1a2000, v169
	s_waitcnt lgkmcnt(7)
	global_store_dwordx4 v169, v[172:175], s[2:3] nt
	s_waitcnt lgkmcnt(6)
	global_store_dwordx4 v204, v[176:179], s[2:3] nt
	s_waitcnt lgkmcnt(5)
	global_store_dwordx4 v205, v[180:183], s[2:3] nt
	s_waitcnt lgkmcnt(4)
	global_store_dwordx4 v206, v[184:187], s[2:3] nt
	s_waitcnt lgkmcnt(3)
	global_store_dwordx4 v207, v[188:191], s[2:3] nt
	s_waitcnt lgkmcnt(2)
	global_store_dwordx4 v208, v[192:195], s[2:3] nt
	s_waitcnt lgkmcnt(1)
	global_store_dwordx4 v209, v[196:199], s[2:3] nt
	s_waitcnt lgkmcnt(0)
	global_store_dwordx4 v210, v[200:203], s[2:3] nt
	s_cbranch_vccz .LBB0_338
; template <int K, int LDA, int LDB>
; DEVI void gemm_tile(const bf16* __restrict__ A, const bf16* __restrict__ Bt, bf16* shm, acc_t& acc) {
;     ...
;   __amdgpu_buffer_rsrc_t rsA = __builtin_amdgcn_make_buffer_rsrc((void*)A, 0, 0x7fffffff, 0x00020000);
;   __amdgpu_buffer_rsrc_t rsBt = __builtin_amdgcn_make_buffer_rsrc((void*)Bt, 0, 0x7fffffff, 0x00020000);
;   unsigned offLDA[2], offLDB[2];
; #pragma unroll
;   for (int _i = 0; _i < 2; ++_i) {
;     int _r, _c; stage_rc(tid_ * 16 + _i * 8192, _r, _c);
;     offLDA[_i] = (unsigned)(_r * LDA + _c) * 2u; offLDB[_i] = (unsigned)(_r * LDB + _c) * 2u;
;   }
; template <int K, int LDA, int LDB, int EPI, int GRP, int NRM, int nTk = TOK / 256>
; DEVI void gemm_phase(const bf16* W, const bf16* X, int nF, const EpiArgs& e, bf16* shm) {
;     ...
;     if constexpr (NRM) {
;       if (threadIdx.x < 256) rsl[(it & 1) * 256 + threadIdx.x] = nxt;
;     }
	s_and_saveexec_b64 s[4:5], s[0:1]
	s_lshl_b32 s8, s16, 10
	s_and_b32 s8, s8, 0x400
	v_add_u32_e32 v2, s8, v137
	ds_write_b32 v2, v140
	s_or_b64 exec, exec, s[4:5]
	v_mov_b32_e32 v130, v136
	s_ashr_i32 s13, s12, 31
	v_bfe_i32 v4, v130, 27, 1
	v_lshlrev_b32_e32 v2, 4, v130
	v_lshrrev_b32_e32 v4, 22, v4
	v_add_u32_e32 v4, v2, v4
	v_and_b32_e32 v4, 0xfffffc00, v4
	v_sub_u32_e32 v4, v2, v4
	v_lshrrev_b32_e32 v5, 4, v4
	v_bitop3_b32 v4, v5, v4, 32 bitop3:0x6c
	s_waitcnt lgkmcnt(0)
	v_ashrrev_i32_e32 v3, 31, v130
	v_ashrrev_i32_e32 v6, 31, v4
	v_lshrrev_b32_e32 v3, 26, v3
	v_lshrrev_b32_e32 v6, 26, v6
	v_add_u32_e32 v3, v130, v3
	v_add_u32_e32 v6, v4, v6
	v_ashrrev_i32_e32 v3, 6, v3
	v_lshrrev_b32_e32 v7, 6, v6
	v_and_b32_e32 v6, 0xc0, v6
	v_lshlrev_b32_e32 v5, 3, v3
	v_lshlrev_b32_e32 v3, 5, v3
	v_sub_u32_e32 v4, v4, v6
	v_and_b32_e32 v5, 0xffff0, v5
	v_and_b32_e32 v3, 32, v3
	v_ashrrev_i16_sdwa v4, v139, sext(v4) dst_sel:DWORD dst_unused:UNUSED_PAD src0_sel:DWORD src1_sel:BYTE_0
	v_add_u32_sdwa v3, v3, sext(v4) dst_sel:DWORD dst_unused:UNUSED_PAD src0_sel:DWORD src1_sel:WORD_0
	v_add_lshl_u32 v4, v7, v5, 12
	v_lshl_add_u32 v141, v3, 1, v4
	v_add_u32_e32 v3, 0x2000, v2
	v_ashrrev_i32_e32 v4, 31, v3
	v_lshrrev_b32_e32 v4, 22, v4
	v_add_u32_e32 v4, v3, v4
	v_ashrrev_i32_e32 v4, 10, v4
	v_mul_i32_i24_e32 v5, 0x400, v4
	v_sub_u32_e32 v3, v3, v5
	v_lshrrev_b32_e32 v5, 4, v3
	v_bitop3_b32 v3, v5, v3, 32 bitop3:0x6c
	v_ashrrev_i32_e32 v6, 31, v3
	s_lshl_b64 s[4:5], s[12:13], 20
	v_lshrrev_b32_e32 v6, 26, v6
	s_add_u32 s4, s96, s4
	v_add_u32_e32 v6, v3, v6
	s_addc_u32 s5, s97, s5
	s_ashr_i32 s15, s14, 31
	v_lshrrev_b32_e32 v7, 6, v6
	v_and_b32_e32 v6, 0xc0, v6
	s_lshl_b64 s[8:9], s[14:15], 20
	v_lshlrev_b32_e32 v5, 3, v4
	v_lshlrev_b32_e32 v4, 5, v4
	v_sub_u32_e32 v3, v3, v6
	v_add_u32_e32 v145, s21, v2
	s_add_u32 s8, s19, s8
	v_and_b32_e32 v5, 0xffff0, v5
	v_and_b32_e32 v4, 32, v4
	v_ashrrev_i16_sdwa v3, v139, sext(v3) dst_sel:DWORD dst_unused:UNUSED_PAD src0_sel:DWORD src1_sel:BYTE_0
	v_readfirstlane_b32 s13, v145
	v_add_u32_e32 v146, 0x2000, v145
	s_addc_u32 s9, s20, s9
	v_add_u32_sdwa v3, v4, sext(v3) dst_sel:DWORD dst_unused:UNUSED_PAD src0_sel:DWORD src1_sel:WORD_0
	v_add_lshl_u32 v4, v7, v5, 12
	s_and_b32 s5, s5, 0xffff
	s_mov_b32 m0, s13
	v_readfirstlane_b32 s13, v146
	v_add_u32_e32 v147, 0, v2
	v_lshl_add_u32 v143, v3, 1, v4
	s_mov_b32 m0, s13
	v_readfirstlane_b32 s13, v147
	v_add_u32_e32 v148, 0x2000, v147
	s_and_b32 s9, s9, 0xffff
	s_mov_b32 s10, s6
	s_mov_b32 s11, s7
	s_mov_b32 m0, s13
	v_readfirstlane_b32 s13, v148
	v_add_u32_e32 v149, s22, v2
	s_mov_b32 m0, s13
	v_readfirstlane_b32 s13, v149
	v_add_u32_e32 v150, 0x2000, v149
	s_mov_b32 m0, s13
	v_readfirstlane_b32 s13, v150
	v_add_u32_e32 v151, 0x4000, v147
	s_mov_b32 m0, s13
	v_readfirstlane_b32 s13, v151
	v_add_u32_e32 v152, 0x6000, v147
	s_mov_b32 m0, s13
	v_readfirstlane_b32 s13, v152
	s_mov_b32 m0, s13
	v_ashrrev_i32_e32 v3, 8, v130
	s_branch .Lafter_loads_7740

; #define WAIT_V(n) asm volatile("s_waitcnt vmcnt(" #n ")" ::: "memory")
; #define BAR __builtin_amdgcn_s_barrier()
; template <int K, int LDA, int LDB>
; DEVI void gemm_tile(const bf16* __restrict__ A, const bf16* __restrict__ Bt, bf16* shm, acc_t& acc) {
;     ...
;   if (wr == 1) BAR;
;   WAIT_V(4); BAR;
.Lafter_loads_7740:
	v_cmp_eq_u32_e32 vcc, 1, v3
	s_and_saveexec_b64 s[10:11], vcc
	s_cbranch_execz .LBB0_330
	s_barrier

; #define STAGE(P, BASE, LD, br, kt) do { const int _so = (int)(((br) * (LD) + (kt) * BK) * 2); \
;     _Pragma("unroll") for (int _i = 0; _i < 2; ++_i) { \
;       __builtin_amdgcn_raw_ptr_buffer_load_lds(rs##BASE, (__attribute__((address_space(3))) unsigned*)((char*)(P) + tid_ * 16 + _i * 8192), 16, (int)off##LD[_i], _so, 0, 0); } } while (0)
; template <int K, int LDA, int LDB>
; DEVI void gemm_tile(const bf16* __restrict__ A, const bf16* __restrict__ Bt, bf16* shm, acc_t& acc) {
;     ...
;   __amdgpu_buffer_rsrc_t rsA = __builtin_amdgcn_make_buffer_rsrc((void*)A, 0, 0x7fffffff, 0x00020000);
;   __amdgpu_buffer_rsrc_t rsBt = __builtin_amdgcn_make_buffer_rsrc((void*)Bt, 0, 0x7fffffff, 0x00020000);
;   unsigned offLDA[2], offLDB[2];
; #pragma unroll
;   for (int _i = 0; _i < 2; ++_i) {
;     int _r, _c; stage_rc(tid_ * 16 + _i * 8192, _r, _c);
;     offLDA[_i] = (unsigned)(_r * LDA + _c) * 2u; offLDB[_i] = (unsigned)(_r * LDB + _c) * 2u;
;   }
;   STAGE(SB(0, 0), Bt, LDB, 0, 0); STAGE(SA(0, 0), A, LDA, 0, 0);
;   STAGE(SB(0, 1), Bt, LDB, HALF, 0); STAGE(SA(0, 1), A, LDA, HALF, 0);
.LBB0_334:
	s_or_b64 exec, exec, s[4:5]
	v_readlane_b32 s4, v250, 1
	v_readlane_b32 s5, v250, 2
	s_load_dword s4, s[4:5], 0x10
	s_waitcnt lgkmcnt(0)
	s_lshr_b32 s4, s4, 16
	s_cmp_lg_u32 s4, 0
	s_cselect_b64 s[4:5], -1, 0
	s_cmp_lg_u64 s[4:5], 0
	s_addc_u32 s39, s39, s33
	s_cmpk_gt_i32 s39, 0x15ff
	s_cselect_b64 s[4:5], -1, 0
	s_and_b64 vcc, exec, s[4:5]
	s_cbranch_vccnz .LBB0_337
	s_ashr_i32 s8, s39, 31
	s_lshr_b32 s8, s8, 29
	s_add_i32 s8, s39, s8
	s_ashr_i32 s9, s8, 3
	s_and_b32 s8, s8, -8
	s_sub_i32 s8, s39, s8
	s_cmp_lt_i32 s8, 0
	s_cselect_b32 s10, s17, 0x2c0
	s_mul_i32 s8, s10, s8
	s_add_i32 s8, s8, s9
	s_mul_hi_i32 s9, s8, 0x2e8ba2e9
	s_lshr_b32 s10, s9, 31
	s_ashr_i32 s9, s9, 6
	s_add_i32 s9, s9, s10
	s_lshl_b32 s10, s9, 3
	s_mulk_i32 s9, 0x160
	s_sub_i32 s8, s8, s9
	s_bfe_u32 s9, s8, 0x3001c
	s_add_i32 s11, s8, s9
	s_and_b32 s9, s11, 0xfff8
	s_sub_i32 s8, s8, s9
	s_sext_i32_i16 s8, s8
	s_add_i32 s10, s10, s8
	v_mov_b32_e32 v220, v136
	v_bfe_i32 v215, v220, 27, 1
	v_lshlrev_b32_e32 v213, 4, v220
	v_lshrrev_b32_e32 v215, 22, v215
	v_add_u32_e32 v215, v213, v215
	v_and_b32_e32 v215, 0xfffffc00, v215
	v_sub_u32_e32 v215, v213, v215
	v_lshrrev_b32_e32 v216, 4, v215
	v_bitop3_b32 v215, v216, v215, 32 bitop3:0x6c
	v_ashrrev_i32_e32 v214, 31, v220
	v_ashrrev_i32_e32 v217, 31, v215
	v_lshrrev_b32_e32 v214, 26, v214
	v_lshrrev_b32_e32 v217, 26, v217
	v_add_u32_e32 v214, v220, v214
	v_add_u32_e32 v217, v215, v217
	v_ashrrev_i32_e32 v214, 6, v214
	v_lshrrev_b32_e32 v218, 6, v217
	v_and_b32_e32 v217, 0xc0, v217
	v_lshlrev_b32_e32 v216, 3, v214
	v_lshlrev_b32_e32 v214, 5, v214
	v_sub_u32_e32 v215, v215, v217
	v_and_b32_e32 v216, 0xffff0, v216
	v_and_b32_e32 v214, 32, v214
	v_ashrrev_i16_sdwa v215, v139, sext(v215) dst_sel:DWORD dst_unused:UNUSED_PAD src0_sel:DWORD src1_sel:BYTE_0
	v_add_u32_sdwa v214, v214, sext(v215) dst_sel:DWORD dst_unused:UNUSED_PAD src0_sel:DWORD src1_sel:WORD_0
	v_add_lshl_u32 v215, v218, v216, 12
	v_lshl_add_u32 v141, v214, 1, v215
	v_add_u32_e32 v214, 0x2000, v213
	v_ashrrev_i32_e32 v215, 31, v214
	v_lshrrev_b32_e32 v215, 22, v215
	v_add_u32_e32 v215, v214, v215
	v_ashrrev_i32_e32 v215, 10, v215
	v_mul_i32_i24_e32 v216, 0x400, v215
	v_sub_u32_e32 v214, v214, v216
	v_lshrrev_b32_e32 v216, 4, v214
	v_bitop3_b32 v214, v216, v214, 32 bitop3:0x6c
	v_ashrrev_i32_e32 v217, 31, v214
	v_lshrrev_b32_e32 v217, 26, v217
	v_add_u32_e32 v217, v214, v217
	v_lshrrev_b32_e32 v218, 6, v217
	v_and_b32_e32 v217, 0xc0, v217
	v_lshlrev_b32_e32 v216, 3, v215
	v_lshlrev_b32_e32 v215, 5, v215
	v_sub_u32_e32 v214, v214, v217
	v_add_u32_e32 v145, s21, v213
	v_and_b32_e32 v216, 0xffff0, v216
	v_and_b32_e32 v215, 32, v215
	v_ashrrev_i16_sdwa v214, v139, sext(v214) dst_sel:DWORD dst_unused:UNUSED_PAD src0_sel:DWORD src1_sel:BYTE_0
	v_add_u32_e32 v146, 0x2000, v145
	v_add_u32_sdwa v214, v215, sext(v214) dst_sel:DWORD dst_unused:UNUSED_PAD src0_sel:DWORD src1_sel:WORD_0
	v_add_lshl_u32 v215, v218, v216, 12
	v_add_u32_e32 v147, 0, v213
	v_lshl_add_u32 v143, v214, 1, v215
	v_add_u32_e32 v148, 0x2000, v147
	v_add_u32_e32 v149, s22, v213
	v_add_u32_e32 v150, 0x2000, v149
	v_add_u32_e32 v151, 0x4000, v147
	v_add_u32_e32 v152, 0x6000, v147
	v_ashrrev_i32_e32 v214, 8, v220
	s_sext_i32_i16 s46, s11
	s_ashr_i32 s46, s46, 3
	s_mov_b32 s48, s10
	s_ashr_i32 s49, s10, 31
	s_lshl_b64 s[48:49], s[48:49], 20
	s_add_u32 s48, s96, s48
	s_addc_u32 s49, s97, s49
	s_and_b32 s49, s49, 0xffff
	s_mov_b32 s50, s6
	s_mov_b32 s51, s7
	v_readfirstlane_b32 s45, v145
	s_mov_b32 m0, s45
	s_nop 0
	buffer_load_dwordx4 v141, s[48:51], 0 offen lds
	v_readfirstlane_b32 s45, v146
	s_mov_b32 m0, s45
	s_nop 0
	buffer_load_dwordx4 v143, s[48:51], 0 offen lds
	v_readfirstlane_b32 s45, v149
	s_mov_b32 m0, s45
	s_nop 0
	buffer_load_dwordx4 v141, s[48:51], s23 offen lds
	v_readfirstlane_b32 s45, v150
	s_mov_b32 m0, s45
	s_nop 0
	buffer_load_dwordx4 v143, s[48:51], s23 offen lds
	s_mov_b32 s48, s46
	s_ashr_i32 s49, s46, 31
	s_lshl_b64 s[48:49], s[48:49], 20
	s_add_u32 s48, s19, s48
	s_addc_u32 s49, s20, s49
	s_and_b32 s49, s49, 0xffff
	s_mov_b32 s50, s6
	s_mov_b32 s51, s7
	v_readfirstlane_b32 s45, v147
	s_mov_b32 m0, s45
	s_nop 0
	buffer_load_dwordx4 v141, s[48:51], 0 offen lds
	v_readfirstlane_b32 s45, v148
	s_mov_b32 m0, s45
	s_nop 0
	buffer_load_dwordx4 v143, s[48:51], 0 offen lds
	v_readfirstlane_b32 s45, v151
	s_mov_b32 m0, s45
	s_nop 0
	buffer_load_dwordx4 v141, s[48:51], s23 offen lds
	v_readfirstlane_b32 s45, v152
	s_mov_b32 m0, s45
	s_nop 0
	buffer_load_dwordx4 v143, s[48:51], s23 offen lds
	s_and_saveexec_b64 s[8:9], s[0:1]
	s_cbranch_execz .LBB0_324
; template <int K, int LDA, int LDB, int EPI, int GRP, int NRM, int nTk = TOK / 256>
; DEVI void gemm_phase(const bf16* W, const bf16* X, int nF, const EpiArgs& e, bf16* shm) {
;     ...
;       if constexpr (NRM) {
;         if (threadIdx.x < 256) {
;           const int tok = pm2 * 256 + threadIdx.x;
;           float sum = 0.f;
; #pragma unroll
;           for (int i = 0; i < 16; ++i) sum += e.st[i * TOK + tok];
;           nxt = rsqrtf(sum * (1.f / DM) + 1e-6f);
;         }
	v_lshl_or_b32 v132, s10, 8, v136
	v_readlane_b32 s40, v250, 24
	v_ashrrev_i32_e32 v133, 31, v132
	v_readlane_b32 s41, v250, 25
	s_mov_b32 s13, 0x800000
	s_nop 0
	v_lshl_add_u64 v[132:133], v[132:133], 2, s[40:41]
	v_add_co_u32_e32 v134, vcc, 0x20000, v132
	global_load_dword v130, v[132:133], off
	s_nop 0
	v_addc_co_u32_e32 v135, vcc, 0, v133, vcc
	global_load_dword v134, v[134:135], off
	s_waitcnt vmcnt(1)
	v_add_f32_e32 v130, 0, v130
	s_waitcnt vmcnt(0)
	v_add_f32_e32 v130, v130, v134
	v_add_co_u32_e32 v134, vcc, 0x40000, v132
	s_nop 1
	v_addc_co_u32_e32 v135, vcc, 0, v133, vcc
	global_load_dword v134, v[134:135], off
	s_waitcnt vmcnt(0)
	v_add_f32_e32 v130, v130, v134
	v_add_co_u32_e32 v134, vcc, 0x60000, v132
	s_nop 1
	v_addc_co_u32_e32 v135, vcc, 0, v133, vcc
	global_load_dword v134, v[134:135], off
	s_waitcnt vmcnt(0)
	v_add_f32_e32 v130, v130, v134
	v_add_co_u32_e32 v134, vcc, s23, v132
	s_nop 1
	v_addc_co_u32_e32 v135, vcc, 0, v133, vcc
	global_load_dword v134, v[134:135], off
	s_waitcnt vmcnt(0)
	v_add_f32_e32 v130, v130, v134
	v_add_co_u32_e32 v134, vcc, 0xa0000, v132
	s_nop 1
	v_addc_co_u32_e32 v135, vcc, 0, v133, vcc
	global_load_dword v134, v[134:135], off
	s_waitcnt vmcnt(0)
	v_add_f32_e32 v130, v130, v134
	v_add_co_u32_e32 v134, vcc, 0xc0000, v132
	s_nop 1
	v_addc_co_u32_e32 v135, vcc, 0, v133, vcc
	global_load_dword v134, v[134:135], off
	s_waitcnt vmcnt(0)
	v_add_f32_e32 v130, v130, v134
	v_add_co_u32_e32 v134, vcc, 0xe0000, v132
	s_nop 1
	v_addc_co_u32_e32 v135, vcc, 0, v133, vcc
	global_load_dword v134, v[134:135], off
	s_waitcnt vmcnt(0)
	v_add_f32_e32 v130, v130, v134
	v_add_co_u32_e32 v134, vcc, 0x100000, v132
	s_nop 1
	v_addc_co_u32_e32 v135, vcc, 0, v133, vcc
	global_load_dword v134, v[134:135], off
	s_waitcnt vmcnt(0)
	v_add_f32_e32 v130, v130, v134
	v_add_co_u32_e32 v134, vcc, 0x120000, v132
	s_nop 1
	v_addc_co_u32_e32 v135, vcc, 0, v133, vcc
	global_load_dword v134, v[134:135], off
	s_waitcnt vmcnt(0)
	v_add_f32_e32 v130, v130, v134
	v_add_co_u32_e32 v134, vcc, 0x140000, v132
	s_nop 1
	v_addc_co_u32_e32 v135, vcc, 0, v133, vcc
	global_load_dword v134, v[134:135], off
	s_waitcnt vmcnt(0)
	v_add_f32_e32 v130, v130, v134
	v_add_co_u32_e32 v134, vcc, 0x160000, v132
	s_nop 1
	v_addc_co_u32_e32 v135, vcc, 0, v133, vcc
	global_load_dword v134, v[134:135], off
	s_waitcnt vmcnt(0)
	v_add_f32_e32 v130, v130, v134
	v_add_co_u32_e32 v134, vcc, 0x180000, v132
	s_nop 1
	v_addc_co_u32_e32 v135, vcc, 0, v133, vcc
	global_load_dword v134, v[134:135], off
	s_waitcnt vmcnt(0)
	v_add_f32_e32 v130, v130, v134
	v_add_co_u32_e32 v134, vcc, 0x1a0000, v132
	s_nop 1
	v_addc_co_u32_e32 v135, vcc, 0, v133, vcc
	global_load_dword v134, v[134:135], off
	s_waitcnt vmcnt(0)
	v_add_f32_e32 v130, v130, v134
	v_add_co_u32_e32 v134, vcc, 0x1c0000, v132
	s_nop 1
	v_addc_co_u32_e32 v135, vcc, 0, v133, vcc
	v_add_co_u32_e32 v132, vcc, 0x1e0000, v132
	global_load_dword v134, v[134:135], off
	s_nop 0
	v_addc_co_u32_e32 v133, vcc, 0, v133, vcc
	global_load_dword v132, v[132:133], off
	s_waitcnt vmcnt(1)
	v_add_f32_e32 v130, v130, v134
	s_waitcnt vmcnt(0)
	v_add_f32_e32 v130, v130, v132
	v_fmamk_f32 v130, v130, 0x3a000000, v138
	v_cmp_gt_f32_e32 vcc, s13, v130
	v_mul_f32_e32 v132, 0x4b800000, v130
	s_nop 0
	v_cndmask_b32_e32 v130, v130, v132, vcc
	v_rsq_f32_e32 v130, v130
	s_nop 0
	v_mul_f32_e32 v132, 0x45800000, v130
	v_cndmask_b32_e32 v140, v130, v132, vcc
	s_branch .LBB0_324

; DEVI float silu(float x) { return x * __builtin_amdgcn_rcpf(1.f + __expf(-x)); }
; template <int EPI, int NRM>
; DEVI void epilogue(acc_t& acc, int pn, int trow, const EpiArgs& e, const float* rl, bf16* shmx) {
;     ...
;   const int fl0 = wr * 64 + fq * 4;
;   const int tk0 = trow + wc * 32 + fr;
;   float rs[2][2];
;   if constexpr (NRM) {
; #pragma unroll
;     for (int bj = 0; bj < 2; ++bj)
; #pragma unroll
;       for (int n = 0; n < 2; ++n) rs[bj][n] = rl[wc * 32 + fr + bj * 128 + n * 16];
;     ...
;   } else if constexpr (EPI == EPI_SWIGLU) {
; #pragma unroll
;     for (int bj = 0; bj < 2; ++bj)
; #pragma unroll
;       for (int m = 0; m < 4; ++m)
; #pragma unroll
;         for (int n = 0; n < 2; ++n) {
;           float r[4];
; #pragma unroll
;           for (int j = 0; j < 4; ++j) r[j] = silu(acc[0][bj][m][n][j] * rs[bj][n]) * (acc[1][bj][m][n][j] * rs[bj][n]);
;           uint2 o; o.x = pack2(r[0], r[1]); o.y = pack2(r[2], r[3]);
;           const unsigned off = (unsigned)((tk0 + bj * 128 + n * 16) * DFF + pn * 128 + m * 16 + fl0);
;           *reinterpret_cast<uint2*>(e.o0 + off) = o;
;         }
.LBB0_1224:
	v_and_b32_e32 v170, 15, v136
	v_bfe_u32 v171, v136, 4, 2
	v_lshrrev_b32_e32 v172, 6, v136
	v_and_b32_e32 v173, 3, v172
	v_lshrrev_b32_e32 v174, 2, v172
	v_lshlrev_b32_e32 v175, 13, v173
	v_lshl_add_u32 v175, v174, 16, v175
	v_add_u32_e32 v175, 0x8000, v175
	v_lshl_add_u32 v176, v170, 7, v175
	v_and_b32_e32 v177, 1, v171
	v_lshl_add_u32 v176, v177, 3, v176
	v_lshrrev_b32_e32 v177, 1, v171
	v_and_b32_e32 v178, 7, v170
	v_add_u32_e32 v179, 0, v177
	v_xor_b32_e32 v179, v179, v178
	v_lshl_add_u32 v164, v179, 4, v176
	v_add_u32_e32 v179, 2, v177
	v_xor_b32_e32 v179, v179, v178
	v_lshl_add_u32 v165, v179, 4, v176
	v_add_u32_e32 v179, 4, v177
	v_xor_b32_e32 v179, v179, v178
	v_lshl_add_u32 v166, v179, 4, v176
	v_add_u32_e32 v179, 6, v177
	v_xor_b32_e32 v179, v179, v178
	v_lshl_add_u32 v167, v179, 4, v176
	v_and_b32_e32 v180, 63, v136
	v_lshl_add_u32 v168, v180, 4, v175
	v_lshrrev_b32_e32 v181, 3, v180
	v_and_b32_e32 v182, 7, v180
	v_xor_b32_e32 v182, v182, v181
	s_lshl_b32 s9, s12, 8
	v_lshl_add_u32 v183, v173, 5, v181
	v_add_u32_e32 v183, s9, v183
	v_mul_u32_u24_e32 v183, 0x1600, v183
	s_lshl_b32 s9, s14, 7
	v_lshl_add_u32 v179, v174, 6, s9
	v_lshl_add_u32 v179, v182, 3, v179
	v_add_lshl_u32 v169, v183, v179, 1
	v_mov_b32_e32 v130, v136
	s_lshl_b32 s11, s16, 10
	s_and_b32 s11, s11, 0x400
	v_and_b32_e32 v141, 15, v130
	v_ashrrev_i32_e32 v142, 2, v130
	v_lshrrev_b32_e32 v143, 2, v130
	v_lshrrev_b32_e32 v130, 1, v130
	s_add_i32 s11, s11, 0
	v_and_b32_e32 v130, 0x60, v130
	s_add_i32 s11, s11, 0x20000
	v_lshlrev_b32_e32 v132, 2, v130
	v_lshlrev_b32_e32 v133, 2, v141
	v_add3_u32 v132, s11, v132, v133
	ds_read2_b32 v[134:135], v132 offset1:16
	ds_read2_b32 v[132:133], v132 offset0:128 offset1:144
	s_lshl_b32 s9, s12, 8
	v_or3_b32 v130, v141, s9, v130
	s_lshl_b32 s9, s14, 7
	s_waitcnt lgkmcnt(1)
	v_pk_mul_f32 v[122:123], v[122:123], v[134:135] op_sel_hi:[1,0]
	v_and_or_b32 v141, v143, 12, s9
	v_mul_f32_e32 v143, 0xbfb8aa3b, v122
	v_mul_f32_e32 v144, 0xbfb8aa3b, v123
	v_exp_f32_e32 v143, v143
	v_exp_f32_e32 v144, v144
	v_and_b32_e32 v142, 0xffffffc0, v142
	v_pk_mul_f32 v[124:125], v[124:125], v[134:135] op_sel_hi:[1,0]
	v_add_u32_e32 v141, v141, v142
	v_add_f32_e32 v142, 1.0, v143
	v_add_f32_e32 v143, 1.0, v144
	v_mul_f32_e32 v144, 0xbfb8aa3b, v124
	v_mul_f32_e32 v145, 0xbfb8aa3b, v125
	v_rcp_f32_e32 v142, v142
	v_rcp_f32_e32 v143, v143
	v_exp_f32_e32 v144, v144
	v_exp_f32_e32 v145, v145
	v_pk_mul_f32 v[126:127], v[126:127], v[134:135] op_sel_hi:[1,0]
	v_pk_mul_f32 v[122:123], v[122:123], v[142:143]
	v_add_f32_e32 v142, 1.0, v144
	v_add_f32_e32 v143, 1.0, v145
	v_rcp_f32_e32 v142, v142
	v_rcp_f32_e32 v143, v143
	v_pk_mul_f32 v[122:123], v[126:127], v[122:123]
	v_pk_mul_f32 v[106:107], v[106:107], v[134:135] op_sel_hi:[1,0]
	v_cvt_pk_bf16_f32 v126, v122, v123
	v_pk_mul_f32 v[122:123], v[124:125], v[142:143]
	v_pk_mul_f32 v[124:125], v[128:129], v[134:135] op_sel_hi:[1,0]
	v_pk_mul_f32 v[108:109], v[108:109], v[134:135] op_sel_hi:[1,0]
	v_pk_mul_f32 v[122:123], v[124:125], v[122:123]
	v_pk_mul_f32 v[110:111], v[110:111], v[134:135] op_sel_hi:[1,0]
	v_cvt_pk_bf16_f32 v127, v122, v123
	v_mul_lo_u32 v123, v130, s41
	v_mov_b32_e32 v122, v135
	v_pk_mul_f32 v[114:115], v[114:115], v[122:123] op_sel_hi:[1,0]
	v_add_u32_e32 v130, v141, v123
	v_mul_f32_e32 v128, 0xbfb8aa3b, v114
	v_mul_f32_e32 v129, 0xbfb8aa3b, v115
	v_exp_f32_e32 v128, v128
	v_exp_f32_e32 v129, v129
	v_lshl_add_u64 v[124:125], v[130:131], 1, s[2:3]
	v_pk_mul_f32 v[116:117], v[116:117], v[122:123] op_sel_hi:[1,0]
	ds_write_b64 v164, v[126:127]
	v_add_f32_e32 v124, 1.0, v128
	v_add_f32_e32 v125, 1.0, v129
	v_mul_f32_e32 v126, 0xbfb8aa3b, v116
	v_mul_f32_e32 v127, 0xbfb8aa3b, v117
	v_rcp_f32_e32 v124, v124
	v_rcp_f32_e32 v125, v125
	v_exp_f32_e32 v126, v126
	v_exp_f32_e32 v127, v127
	v_pk_mul_f32 v[118:119], v[118:119], v[122:123] op_sel_hi:[1,0]
	v_pk_mul_f32 v[114:115], v[114:115], v[124:125]
	v_add_f32_e32 v124, 1.0, v126
	v_add_f32_e32 v125, 1.0, v127
	v_rcp_f32_e32 v124, v124
	v_rcp_f32_e32 v125, v125
	v_pk_mul_f32 v[114:115], v[118:119], v[114:115]
	v_pk_mul_f32 v[118:119], v[120:121], v[122:123] op_sel_hi:[1,0]
	v_cvt_pk_bf16_f32 v114, v114, v115
	v_pk_mul_f32 v[116:117], v[116:117], v[124:125]
	v_pk_mul_f32 v[98:99], v[98:99], v[122:123] op_sel_hi:[1,0]
	v_pk_mul_f32 v[116:117], v[118:119], v[116:117]
	v_add_u32_e32 v118, 0x16000, v123
	v_add_u32_e32 v130, v118, v141
	v_cvt_pk_bf16_f32 v115, v116, v117
	v_lshl_add_u64 v[116:117], v[130:131], 1, s[2:3]
	ds_write_b64 v164, v[114:115] offset:2048
	v_mul_f32_e32 v114, 0xbfb8aa3b, v106
	v_mul_f32_e32 v115, 0xbfb8aa3b, v107
	v_exp_f32_e32 v114, v114
	v_exp_f32_e32 v115, v115
	v_mul_f32_e32 v117, 0xbfb8aa3b, v108
	v_mul_f32_e32 v119, 0xbfb8aa3b, v109
	v_add_f32_e32 v114, 1.0, v114
	v_add_f32_e32 v115, 1.0, v115
	v_rcp_f32_e32 v114, v114
	v_rcp_f32_e32 v115, v115
	v_exp_f32_e32 v117, v117
	v_exp_f32_e32 v119, v119
	v_or_b32_e32 v116, 16, v141
	v_pk_mul_f32 v[106:107], v[106:107], v[114:115]
	v_add_f32_e32 v114, 1.0, v117
	v_add_f32_e32 v115, 1.0, v119
	v_rcp_f32_e32 v114, v114
	v_rcp_f32_e32 v115, v115
	v_pk_mul_f32 v[106:107], v[110:111], v[106:107]
	v_pk_mul_f32 v[110:111], v[112:113], v[134:135] op_sel_hi:[1,0]
	v_add_u32_e32 v130, v116, v123
	v_pk_mul_f32 v[108:109], v[108:109], v[114:115]
	v_cvt_pk_bf16_f32 v106, v106, v107
	v_pk_mul_f32 v[108:109], v[110:111], v[108:109]
	v_mul_f32_e32 v110, 0xbfb8aa3b, v98
	v_mul_f32_e32 v111, 0xbfb8aa3b, v99
	v_exp_f32_e32 v110, v110
	v_exp_f32_e32 v111, v111
	v_cvt_pk_bf16_f32 v107, v108, v109
	v_lshl_add_u64 v[108:109], v[130:131], 1, s[2:3]
	v_pk_mul_f32 v[100:101], v[100:101], v[122:123] op_sel_hi:[1,0]
; DEVI float silu(float x) { return x * __builtin_amdgcn_rcpf(1.f + __expf(-x)); }
; template <int EPI, int NRM>
; DEVI void epilogue(acc_t& acc, int pn, int trow, const EpiArgs& e, const float* rl, bf16* shmx) {
;     ...
;   } else if constexpr (EPI == EPI_SWIGLU) {
; #pragma unroll
;     for (int bj = 0; bj < 2; ++bj)
; #pragma unroll
;       for (int m = 0; m < 4; ++m)
; #pragma unroll
;         for (int n = 0; n < 2; ++n) {
;           float r[4];
; #pragma unroll
;           for (int j = 0; j < 4; ++j) r[j] = silu(acc[0][bj][m][n][j] * rs[bj][n]) * (acc[1][bj][m][n][j] * rs[bj][n]);
;           uint2 o; o.x = pack2(r[0], r[1]); o.y = pack2(r[2], r[3]);
;           const unsigned off = (unsigned)((tk0 + bj * 128 + n * 16) * DFF + pn * 128 + m * 16 + fl0);
;           *reinterpret_cast<uint2*>(e.o0 + off) = o;
;         }
	ds_write_b64 v165, v[106:107]
	v_add_f32_e32 v106, 1.0, v110
	v_add_f32_e32 v107, 1.0, v111
	v_mul_f32_e32 v108, 0xbfb8aa3b, v100
	v_mul_f32_e32 v109, 0xbfb8aa3b, v101
	v_rcp_f32_e32 v106, v106
	v_rcp_f32_e32 v107, v107
	v_exp_f32_e32 v108, v108
	v_exp_f32_e32 v109, v109
	v_pk_mul_f32 v[102:103], v[102:103], v[122:123] op_sel_hi:[1,0]
	v_pk_mul_f32 v[98:99], v[98:99], v[106:107]
	v_add_f32_e32 v106, 1.0, v108
	v_add_f32_e32 v107, 1.0, v109
	v_rcp_f32_e32 v106, v106
	v_rcp_f32_e32 v107, v107
	v_pk_mul_f32 v[98:99], v[102:103], v[98:99]
	v_pk_mul_f32 v[102:103], v[104:105], v[122:123] op_sel_hi:[1,0]
	v_add_u32_e32 v130, v116, v118
	v_pk_mul_f32 v[100:101], v[100:101], v[106:107]
	v_cvt_pk_bf16_f32 v98, v98, v99
	v_pk_mul_f32 v[100:101], v[102:103], v[100:101]
	v_pk_mul_f32 v[90:91], v[90:91], v[134:135] op_sel_hi:[1,0]
	v_cvt_pk_bf16_f32 v99, v100, v101
	v_lshl_add_u64 v[100:101], v[130:131], 1, s[2:3]
	ds_write_b64 v165, v[98:99] offset:2048
	v_mul_f32_e32 v98, 0xbfb8aa3b, v90
	v_mul_f32_e32 v99, 0xbfb8aa3b, v91
	v_exp_f32_e32 v98, v98
	v_exp_f32_e32 v99, v99
	v_pk_mul_f32 v[92:93], v[92:93], v[134:135] op_sel_hi:[1,0]
	v_pk_mul_f32 v[94:95], v[94:95], v[134:135] op_sel_hi:[1,0]
	v_add_f32_e32 v98, 1.0, v98
	v_add_f32_e32 v99, 1.0, v99
	v_mul_f32_e32 v101, 0xbfb8aa3b, v92
	v_mul_f32_e32 v102, 0xbfb8aa3b, v93
	v_rcp_f32_e32 v98, v98
	v_rcp_f32_e32 v99, v99
	v_exp_f32_e32 v101, v101
	v_exp_f32_e32 v102, v102
	v_pk_mul_f32 v[82:83], v[82:83], v[122:123] op_sel_hi:[1,0]
	v_pk_mul_f32 v[90:91], v[90:91], v[98:99]
	v_add_f32_e32 v98, 1.0, v101
	v_add_f32_e32 v99, 1.0, v102
	v_rcp_f32_e32 v98, v98
	v_rcp_f32_e32 v99, v99
	v_pk_mul_f32 v[90:91], v[94:95], v[90:91]
	v_pk_mul_f32 v[94:95], v[96:97], v[134:135] op_sel_hi:[1,0]
	v_or_b32_e32 v100, 32, v141
	v_pk_mul_f32 v[92:93], v[92:93], v[98:99]
	v_add_u32_e32 v130, v100, v123
	v_pk_mul_f32 v[92:93], v[94:95], v[92:93]
	v_mul_f32_e32 v94, 0xbfb8aa3b, v82
	v_mul_f32_e32 v95, 0xbfb8aa3b, v83
	v_exp_f32_e32 v94, v94
	v_exp_f32_e32 v95, v95
	v_cvt_pk_bf16_f32 v90, v90, v91
	v_cvt_pk_bf16_f32 v91, v92, v93
	v_lshl_add_u64 v[92:93], v[130:131], 1, s[2:3]
	v_pk_mul_f32 v[84:85], v[84:85], v[122:123] op_sel_hi:[1,0]
	ds_write_b64 v166, v[90:91]
	v_add_f32_e32 v90, 1.0, v94
	v_add_f32_e32 v91, 1.0, v95
	v_mul_f32_e32 v92, 0xbfb8aa3b, v84
	v_mul_f32_e32 v93, 0xbfb8aa3b, v85
	v_rcp_f32_e32 v90, v90
	v_rcp_f32_e32 v91, v91
	v_exp_f32_e32 v92, v92
	v_exp_f32_e32 v93, v93
	v_pk_mul_f32 v[86:87], v[86:87], v[122:123] op_sel_hi:[1,0]
	v_pk_mul_f32 v[82:83], v[82:83], v[90:91]
	v_add_f32_e32 v90, 1.0, v92
	v_add_f32_e32 v91, 1.0, v93
	v_rcp_f32_e32 v90, v90
	v_rcp_f32_e32 v91, v91
	v_pk_mul_f32 v[82:83], v[86:87], v[82:83]
	v_pk_mul_f32 v[86:87], v[88:89], v[122:123] op_sel_hi:[1,0]
	v_add_u32_e32 v130, v100, v118
	v_pk_mul_f32 v[84:85], v[84:85], v[90:91]
	v_cvt_pk_bf16_f32 v82, v82, v83
	v_pk_mul_f32 v[84:85], v[86:87], v[84:85]
	v_pk_mul_f32 v[74:75], v[74:75], v[134:135] op_sel_hi:[1,0]
	v_cvt_pk_bf16_f32 v83, v84, v85
	v_lshl_add_u64 v[84:85], v[130:131], 1, s[2:3]
	ds_write_b64 v166, v[82:83] offset:2048
	v_mul_f32_e32 v82, 0xbfb8aa3b, v74
	v_mul_f32_e32 v83, 0xbfb8aa3b, v75
	v_exp_f32_e32 v82, v82
	v_exp_f32_e32 v83, v83
	v_pk_mul_f32 v[76:77], v[76:77], v[134:135] op_sel_hi:[1,0]
	v_pk_mul_f32 v[78:79], v[78:79], v[134:135] op_sel_hi:[1,0]
	v_add_f32_e32 v82, 1.0, v82
	v_add_f32_e32 v83, 1.0, v83
	v_mul_f32_e32 v85, 0xbfb8aa3b, v76
	v_mul_f32_e32 v86, 0xbfb8aa3b, v77
	v_rcp_f32_e32 v82, v82
	v_rcp_f32_e32 v83, v83
	v_exp_f32_e32 v85, v85
	v_exp_f32_e32 v86, v86
	v_pk_mul_f32 v[66:67], v[66:67], v[122:123] op_sel_hi:[1,0]
	v_pk_mul_f32 v[74:75], v[74:75], v[82:83]
	v_add_f32_e32 v82, 1.0, v85
	v_add_f32_e32 v83, 1.0, v86
	v_rcp_f32_e32 v82, v82
	v_rcp_f32_e32 v83, v83
	v_pk_mul_f32 v[74:75], v[78:79], v[74:75]
	v_pk_mul_f32 v[78:79], v[80:81], v[134:135] op_sel_hi:[1,0]
	v_or_b32_e32 v84, 48, v141
	v_pk_mul_f32 v[76:77], v[76:77], v[82:83]
	v_add_u32_e32 v130, v84, v123
	v_pk_mul_f32 v[76:77], v[78:79], v[76:77]
	v_mul_f32_e32 v78, 0xbfb8aa3b, v66
	v_mul_f32_e32 v79, 0xbfb8aa3b, v67
	v_exp_f32_e32 v78, v78
	v_exp_f32_e32 v79, v79
	v_cvt_pk_bf16_f32 v74, v74, v75
	v_cvt_pk_bf16_f32 v75, v76, v77
	v_lshl_add_u64 v[76:77], v[130:131], 1, s[2:3]
	v_pk_mul_f32 v[68:69], v[68:69], v[122:123] op_sel_hi:[1,0]
	ds_write_b64 v167, v[74:75]
	v_add_f32_e32 v74, 1.0, v78
	v_add_f32_e32 v75, 1.0, v79
	v_mul_f32_e32 v76, 0xbfb8aa3b, v68
	v_mul_f32_e32 v77, 0xbfb8aa3b, v69
	v_rcp_f32_e32 v74, v74
	v_rcp_f32_e32 v75, v75
	v_exp_f32_e32 v76, v76
	v_exp_f32_e32 v77, v77
	v_pk_mul_f32 v[70:71], v[70:71], v[122:123] op_sel_hi:[1,0]
	v_pk_mul_f32 v[66:67], v[66:67], v[74:75]
	v_add_f32_e32 v74, 1.0, v76
	v_add_f32_e32 v75, 1.0, v77
	v_rcp_f32_e32 v74, v74
	v_rcp_f32_e32 v75, v75
	v_pk_mul_f32 v[66:67], v[70:71], v[66:67]
	v_pk_mul_f32 v[70:71], v[72:73], v[122:123] op_sel_hi:[1,0]
	s_waitcnt lgkmcnt(0)
	v_pk_mul_f32 v[58:59], v[58:59], v[132:133] op_sel_hi:[1,0]
	v_pk_mul_f32 v[68:69], v[68:69], v[74:75]
	v_add_u32_e32 v130, v84, v118
	v_pk_mul_f32 v[68:69], v[70:71], v[68:69]
	v_mul_f32_e32 v70, 0xbfb8aa3b, v58
	v_mul_f32_e32 v71, 0xbfb8aa3b, v59
	v_exp_f32_e32 v70, v70
	v_exp_f32_e32 v71, v71
	v_cvt_pk_bf16_f32 v66, v66, v67
	v_cvt_pk_bf16_f32 v67, v68, v69
	v_lshl_add_u64 v[68:69], v[130:131], 1, s[2:3]
	v_pk_mul_f32 v[60:61], v[60:61], v[132:133] op_sel_hi:[1,0]
	ds_write_b64 v167, v[66:67] offset:2048
	s_waitcnt lgkmcnt(0)
	ds_read_b128 v[172:175], v168
	ds_read_b128 v[176:179], v168 offset:1024
	ds_read_b128 v[180:183], v168 offset:2048
	ds_read_b128 v[184:187], v168 offset:3072
	v_add_u32_e32 v204, 0x16000, v169
	v_add_u32_e32 v205, 0x2c000, v169
	v_add_u32_e32 v206, 0x42000, v169
	s_waitcnt lgkmcnt(3)
; DEVI float silu(float x) { return x * __builtin_amdgcn_rcpf(1.f + __expf(-x)); }
; template <int EPI, int NRM>
; DEVI void epilogue(acc_t& acc, int pn, int trow, const EpiArgs& e, const float* rl, bf16* shmx) {
;     ...
;   } else if constexpr (EPI == EPI_SWIGLU) {
; #pragma unroll
;     for (int bj = 0; bj < 2; ++bj)
; #pragma unroll
;       for (int m = 0; m < 4; ++m)
; #pragma unroll
;         for (int n = 0; n < 2; ++n) {
;           float r[4];
; #pragma unroll
;           for (int j = 0; j < 4; ++j) r[j] = silu(acc[0][bj][m][n][j] * rs[bj][n]) * (acc[1][bj][m][n][j] * rs[bj][n]);
;           uint2 o; o.x = pack2(r[0], r[1]); o.y = pack2(r[2], r[3]);
;           const unsigned off = (unsigned)((tk0 + bj * 128 + n * 16) * DFF + pn * 128 + m * 16 + fl0);
;           *reinterpret_cast<uint2*>(e.o0 + off) = o;
;         }
	global_store_dwordx4 v169, v[172:175], s[2:3] nt
	s_waitcnt lgkmcnt(2)
	global_store_dwordx4 v204, v[176:179], s[2:3] nt
	s_waitcnt lgkmcnt(1)
	global_store_dwordx4 v205, v[180:183], s[2:3] nt
	s_waitcnt lgkmcnt(0)
	global_store_dwordx4 v206, v[184:187], s[2:3] nt
	v_add_f32_e32 v66, 1.0, v70
	v_add_f32_e32 v67, 1.0, v71
	v_mul_f32_e32 v68, 0xbfb8aa3b, v60
	v_mul_f32_e32 v69, 0xbfb8aa3b, v61
	v_rcp_f32_e32 v66, v66
	v_rcp_f32_e32 v67, v67
	v_exp_f32_e32 v68, v68
	v_exp_f32_e32 v69, v69
	v_pk_mul_f32 v[62:63], v[62:63], v[132:133] op_sel_hi:[1,0]
	v_pk_mul_f32 v[58:59], v[58:59], v[66:67]
	v_add_f32_e32 v66, 1.0, v68
	v_add_f32_e32 v67, 1.0, v69
	v_rcp_f32_e32 v66, v66
	v_rcp_f32_e32 v67, v67
	v_pk_mul_f32 v[58:59], v[62:63], v[58:59]
	v_pk_mul_f32 v[42:43], v[42:43], v[132:133] op_sel_hi:[1,0]
	v_cvt_pk_bf16_f32 v62, v58, v59
	v_pk_mul_f32 v[58:59], v[60:61], v[66:67]
	v_pk_mul_f32 v[60:61], v[64:65], v[132:133] op_sel_hi:[1,0]
	v_pk_mul_f32 v[44:45], v[44:45], v[132:133] op_sel_hi:[1,0]
	v_pk_mul_f32 v[58:59], v[60:61], v[58:59]
	v_pk_mul_f32 v[46:47], v[46:47], v[132:133] op_sel_hi:[1,0]
	v_cvt_pk_bf16_f32 v63, v58, v59
	v_add_u32_e32 v59, 0xb0000, v123
	v_mov_b32_e32 v58, v133
	v_pk_mul_f32 v[50:51], v[50:51], v[58:59] op_sel_hi:[1,0]
	v_add_u32_e32 v130, v59, v141
	v_mul_f32_e32 v64, 0xbfb8aa3b, v50
	v_mul_f32_e32 v65, 0xbfb8aa3b, v51
	v_exp_f32_e32 v64, v64
	v_exp_f32_e32 v65, v65
	v_lshl_add_u64 v[60:61], v[130:131], 1, s[2:3]
	v_pk_mul_f32 v[52:53], v[52:53], v[58:59] op_sel_hi:[1,0]
	ds_write_b64 v164, v[62:63] offset:4096
	v_add_f32_e32 v60, 1.0, v64
	v_add_f32_e32 v61, 1.0, v65
	v_mul_f32_e32 v62, 0xbfb8aa3b, v52
	v_mul_f32_e32 v63, 0xbfb8aa3b, v53
	v_rcp_f32_e32 v60, v60
	v_rcp_f32_e32 v61, v61
	v_exp_f32_e32 v62, v62
	v_exp_f32_e32 v63, v63
	v_pk_mul_f32 v[54:55], v[54:55], v[58:59] op_sel_hi:[1,0]
	v_pk_mul_f32 v[50:51], v[50:51], v[60:61]
	v_add_f32_e32 v60, 1.0, v62
	v_add_f32_e32 v61, 1.0, v63
	v_rcp_f32_e32 v60, v60
	v_rcp_f32_e32 v61, v61
	v_pk_mul_f32 v[50:51], v[54:55], v[50:51]
	v_pk_mul_f32 v[54:55], v[56:57], v[58:59] op_sel_hi:[1,0]
	v_mul_f32_e32 v56, 0xbfb8aa3b, v43
	v_pk_mul_f32 v[52:53], v[52:53], v[60:61]
	v_exp_f32_e32 v56, v56
	v_pk_mul_f32 v[52:53], v[54:55], v[52:53]
	v_mul_f32_e32 v55, 0xbfb8aa3b, v42
	v_exp_f32_e32 v55, v55
	v_add_u32_e32 v54, 0xc6000, v123
	v_add_u32_e32 v130, v54, v141
	v_cvt_pk_bf16_f32 v50, v50, v51
	v_cvt_pk_bf16_f32 v51, v52, v53
	v_lshl_add_u64 v[52:53], v[130:131], 1, s[2:3]
	ds_write_b64 v164, v[50:51] offset:6144
	v_add_f32_e32 v50, 1.0, v55
	v_add_f32_e32 v51, 1.0, v56
	v_mul_f32_e32 v52, 0xbfb8aa3b, v44
	v_mul_f32_e32 v53, 0xbfb8aa3b, v45
	v_rcp_f32_e32 v50, v50
	v_rcp_f32_e32 v51, v51
	v_exp_f32_e32 v52, v52
	v_exp_f32_e32 v53, v53
	v_pk_mul_f32 v[34:35], v[34:35], v[58:59] op_sel_hi:[1,0]
	v_pk_mul_f32 v[42:43], v[42:43], v[50:51]
	v_add_f32_e32 v50, 1.0, v52
	v_add_f32_e32 v51, 1.0, v53
	v_rcp_f32_e32 v50, v50
	v_rcp_f32_e32 v51, v51
	v_pk_mul_f32 v[42:43], v[46:47], v[42:43]
	v_pk_mul_f32 v[46:47], v[48:49], v[132:133] op_sel_hi:[1,0]
	v_add_u32_e32 v130, v116, v59
	v_pk_mul_f32 v[44:45], v[44:45], v[50:51]
	v_cvt_pk_bf16_f32 v42, v42, v43
	v_pk_mul_f32 v[44:45], v[46:47], v[44:45]
	v_mul_f32_e32 v46, 0xbfb8aa3b, v34
	v_mul_f32_e32 v47, 0xbfb8aa3b, v35
	v_exp_f32_e32 v46, v46
	v_exp_f32_e32 v47, v47
	v_cvt_pk_bf16_f32 v43, v44, v45
	v_lshl_add_u64 v[44:45], v[130:131], 1, s[2:3]
	v_pk_mul_f32 v[36:37], v[36:37], v[58:59] op_sel_hi:[1,0]
	ds_write_b64 v165, v[42:43] offset:4096
	v_add_f32_e32 v42, 1.0, v46
	v_add_f32_e32 v43, 1.0, v47
	v_mul_f32_e32 v44, 0xbfb8aa3b, v36
	v_mul_f32_e32 v45, 0xbfb8aa3b, v37
	v_rcp_f32_e32 v42, v42
	v_rcp_f32_e32 v43, v43
	v_exp_f32_e32 v44, v44
	v_exp_f32_e32 v45, v45
	v_pk_mul_f32 v[38:39], v[38:39], v[58:59] op_sel_hi:[1,0]
	v_pk_mul_f32 v[34:35], v[34:35], v[42:43]
	v_add_f32_e32 v42, 1.0, v44
	v_add_f32_e32 v43, 1.0, v45
	v_rcp_f32_e32 v42, v42
	v_rcp_f32_e32 v43, v43
	v_pk_mul_f32 v[34:35], v[38:39], v[34:35]
	v_pk_mul_f32 v[38:39], v[40:41], v[58:59] op_sel_hi:[1,0]
	v_pk_mul_f32 v[26:27], v[26:27], v[132:133] op_sel_hi:[1,0]
	v_pk_mul_f32 v[36:37], v[36:37], v[42:43]
	v_add_u32_e32 v130, v116, v54
	v_pk_mul_f32 v[36:37], v[38:39], v[36:37]
	v_mul_f32_e32 v38, 0xbfb8aa3b, v26
	v_mul_f32_e32 v39, 0xbfb8aa3b, v27
	v_exp_f32_e32 v38, v38
	v_exp_f32_e32 v39, v39
	v_cvt_pk_bf16_f32 v34, v34, v35
	v_cvt_pk_bf16_f32 v35, v36, v37
	v_lshl_add_u64 v[36:37], v[130:131], 1, s[2:3]
	v_pk_mul_f32 v[28:29], v[28:29], v[132:133] op_sel_hi:[1,0]
	ds_write_b64 v165, v[34:35] offset:6144
	v_add_f32_e32 v34, 1.0, v38
	v_add_f32_e32 v35, 1.0, v39
	v_mul_f32_e32 v36, 0xbfb8aa3b, v28
	v_mul_f32_e32 v37, 0xbfb8aa3b, v29
	v_rcp_f32_e32 v34, v34
	v_rcp_f32_e32 v35, v35
	v_exp_f32_e32 v36, v36
	v_exp_f32_e32 v37, v37
	v_pk_mul_f32 v[30:31], v[30:31], v[132:133] op_sel_hi:[1,0]
	v_pk_mul_f32 v[26:27], v[26:27], v[34:35]
	v_add_f32_e32 v34, 1.0, v36
	v_add_f32_e32 v35, 1.0, v37
	v_rcp_f32_e32 v34, v34
	v_rcp_f32_e32 v35, v35
	v_pk_mul_f32 v[26:27], v[30:31], v[26:27]
	v_pk_mul_f32 v[30:31], v[32:33], v[132:133] op_sel_hi:[1,0]
	v_pk_mul_f32 v[18:19], v[18:19], v[58:59] op_sel_hi:[1,0]
	v_pk_mul_f32 v[28:29], v[28:29], v[34:35]
	v_add_u32_e32 v130, v100, v59
	v_pk_mul_f32 v[28:29], v[30:31], v[28:29]
	v_mul_f32_e32 v30, 0xbfb8aa3b, v18
	v_mul_f32_e32 v31, 0xbfb8aa3b, v19
	v_exp_f32_e32 v30, v30
	v_exp_f32_e32 v31, v31
	v_cvt_pk_bf16_f32 v26, v26, v27
	v_cvt_pk_bf16_f32 v27, v28, v29
	v_lshl_add_u64 v[28:29], v[130:131], 1, s[2:3]
	v_pk_mul_f32 v[20:21], v[20:21], v[58:59] op_sel_hi:[1,0]
	ds_write_b64 v166, v[26:27] offset:4096
	v_add_f32_e32 v26, 1.0, v30
; DEVI float silu(float x) { return x * __builtin_amdgcn_rcpf(1.f + __expf(-x)); }
; template <int EPI, int NRM>
; DEVI void epilogue(acc_t& acc, int pn, int trow, const EpiArgs& e, const float* rl, bf16* shmx) {
;     ...
;   } else if constexpr (EPI == EPI_SWIGLU) {
; #pragma unroll
;     for (int bj = 0; bj < 2; ++bj)
; #pragma unroll
;       for (int m = 0; m < 4; ++m)
; #pragma unroll
;         for (int n = 0; n < 2; ++n) {
;           float r[4];
; #pragma unroll
;           for (int j = 0; j < 4; ++j) r[j] = silu(acc[0][bj][m][n][j] * rs[bj][n]) * (acc[1][bj][m][n][j] * rs[bj][n]);
;           uint2 o; o.x = pack2(r[0], r[1]); o.y = pack2(r[2], r[3]);
;           const unsigned off = (unsigned)((tk0 + bj * 128 + n * 16) * DFF + pn * 128 + m * 16 + fl0);
;           *reinterpret_cast<uint2*>(e.o0 + off) = o;
;         }
	v_add_f32_e32 v27, 1.0, v31
	v_mul_f32_e32 v28, 0xbfb8aa3b, v20
	v_mul_f32_e32 v29, 0xbfb8aa3b, v21
	v_rcp_f32_e32 v26, v26
	v_rcp_f32_e32 v27, v27
	v_exp_f32_e32 v28, v28
	v_exp_f32_e32 v29, v29
	v_pk_mul_f32 v[22:23], v[22:23], v[58:59] op_sel_hi:[1,0]
	v_pk_mul_f32 v[18:19], v[18:19], v[26:27]
	v_add_f32_e32 v26, 1.0, v28
	v_add_f32_e32 v27, 1.0, v29
	v_rcp_f32_e32 v26, v26
	v_rcp_f32_e32 v27, v27
	v_pk_mul_f32 v[18:19], v[22:23], v[18:19]
	v_pk_mul_f32 v[22:23], v[24:25], v[58:59] op_sel_hi:[1,0]
	v_pk_mul_f32 v[10:11], v[10:11], v[132:133] op_sel_hi:[1,0]
	v_pk_mul_f32 v[20:21], v[20:21], v[26:27]
	v_add_u32_e32 v130, v100, v54
	v_pk_mul_f32 v[20:21], v[22:23], v[20:21]
	v_mul_f32_e32 v22, 0xbfb8aa3b, v10
	v_mul_f32_e32 v23, 0xbfb8aa3b, v11
	v_exp_f32_e32 v22, v22
	v_exp_f32_e32 v23, v23
	v_cvt_pk_bf16_f32 v18, v18, v19
	v_cvt_pk_bf16_f32 v19, v20, v21
	v_lshl_add_u64 v[20:21], v[130:131], 1, s[2:3]
	v_pk_mul_f32 v[12:13], v[12:13], v[132:133] op_sel_hi:[1,0]
	ds_write_b64 v166, v[18:19] offset:6144
	v_add_f32_e32 v18, 1.0, v22
	v_add_f32_e32 v19, 1.0, v23
	v_mul_f32_e32 v20, 0xbfb8aa3b, v12
	v_mul_f32_e32 v21, 0xbfb8aa3b, v13
	v_rcp_f32_e32 v18, v18
	v_rcp_f32_e32 v19, v19
	v_exp_f32_e32 v20, v20
	v_exp_f32_e32 v21, v21
	v_pk_mul_f32 v[14:15], v[14:15], v[132:133] op_sel_hi:[1,0]
	v_pk_mul_f32 v[10:11], v[10:11], v[18:19]
	v_add_f32_e32 v18, 1.0, v20
	v_add_f32_e32 v19, 1.0, v21
	v_rcp_f32_e32 v18, v18
	v_rcp_f32_e32 v19, v19
	v_pk_mul_f32 v[10:11], v[14:15], v[10:11]
	v_pk_mul_f32 v[14:15], v[16:17], v[132:133] op_sel_hi:[1,0]
	v_pk_mul_f32 v[2:3], v[2:3], v[58:59] op_sel_hi:[1,0]
	v_pk_mul_f32 v[12:13], v[12:13], v[18:19]
	v_add_u32_e32 v130, v84, v59
	v_pk_mul_f32 v[12:13], v[14:15], v[12:13]
	v_mul_f32_e32 v14, 0xbfb8aa3b, v2
	v_mul_f32_e32 v15, 0xbfb8aa3b, v3
	v_exp_f32_e32 v14, v14
	v_exp_f32_e32 v15, v15
	v_cvt_pk_bf16_f32 v10, v10, v11
	v_cvt_pk_bf16_f32 v11, v12, v13
	v_lshl_add_u64 v[12:13], v[130:131], 1, s[2:3]
	v_pk_mul_f32 v[4:5], v[4:5], v[58:59] op_sel_hi:[1,0]
	ds_write_b64 v167, v[10:11] offset:4096
	v_add_f32_e32 v10, 1.0, v14
	v_add_f32_e32 v11, 1.0, v15
	v_mul_f32_e32 v12, 0xbfb8aa3b, v4
	v_mul_f32_e32 v13, 0xbfb8aa3b, v5
	v_rcp_f32_e32 v10, v10
	v_rcp_f32_e32 v11, v11
	v_exp_f32_e32 v12, v12
	v_exp_f32_e32 v13, v13
	v_pk_mul_f32 v[6:7], v[6:7], v[58:59] op_sel_hi:[1,0]
	v_pk_mul_f32 v[2:3], v[2:3], v[10:11]
	v_add_f32_e32 v10, 1.0, v12
	v_add_f32_e32 v11, 1.0, v13
	v_rcp_f32_e32 v10, v10
	v_rcp_f32_e32 v11, v11
	v_pk_mul_f32 v[2:3], v[6:7], v[2:3]
	v_pk_mul_f32 v[6:7], v[8:9], v[58:59] op_sel_hi:[1,0]
	v_add_u32_e32 v130, v84, v54
	v_pk_mul_f32 v[4:5], v[4:5], v[10:11]
	v_cvt_pk_bf16_f32 v2, v2, v3
	v_pk_mul_f32 v[4:5], v[6:7], v[4:5]
	s_add_i32 s16, s16, 1
	v_cvt_pk_bf16_f32 v3, v4, v5
	v_lshl_add_u64 v[4:5], v[130:131], 1, s[2:3]
	s_andn2_b64 vcc, exec, s[4:5]
	s_mov_b32 s14, s8
	s_mov_b32 s12, s10
	ds_write_b64 v167, v[2:3] offset:6144
	s_waitcnt lgkmcnt(0)
	ds_read_b128 v[172:175], v168
	ds_read_b128 v[176:179], v168 offset:1024
	ds_read_b128 v[180:183], v168 offset:2048
	ds_read_b128 v[184:187], v168 offset:3072
	ds_read_b128 v[188:191], v168 offset:4096
	ds_read_b128 v[192:195], v168 offset:5120
	ds_read_b128 v[196:199], v168 offset:6144
	ds_read_b128 v[200:203], v168 offset:7168
	v_add_u32_e32 v204, 0x16000, v169
	v_add_u32_e32 v205, 0x2c000, v169
	v_add_u32_e32 v206, 0x42000, v169
	v_add_u32_e32 v207, 0x160000, v169
	v_add_u32_e32 v208, 0x176000, v169
	v_add_u32_e32 v209, 0x18c000, v169
	v_add_u32_e32 v210, 0x1a2000, v169
	s_waitcnt lgkmcnt(7)
	global_store_dwordx4 v169, v[172:175], s[2:3] nt
	s_waitcnt lgkmcnt(6)
	global_store_dwordx4 v204, v[176:179], s[2:3] nt
	s_waitcnt lgkmcnt(5)
	global_store_dwordx4 v205, v[180:183], s[2:3] nt
	s_waitcnt lgkmcnt(4)
	global_store_dwordx4 v206, v[184:187], s[2:3] nt
	s_waitcnt lgkmcnt(3)
	global_store_dwordx4 v207, v[188:191], s[2:3] nt
	s_waitcnt lgkmcnt(2)
	global_store_dwordx4 v208, v[192:195], s[2:3] nt
	s_waitcnt lgkmcnt(1)
	global_store_dwordx4 v209, v[196:199], s[2:3] nt
	s_waitcnt lgkmcnt(0)
	global_store_dwordx4 v210, v[200:203], s[2:3] nt
	s_cbranch_vccz .LBB0_1237
; template <int K, int LDA, int LDB>
; DEVI void gemm_tile(const bf16* __restrict__ A, const bf16* __restrict__ Bt, bf16* shm, acc_t& acc) {
;     ...
;   __amdgpu_buffer_rsrc_t rsA = __builtin_amdgcn_make_buffer_rsrc((void*)A, 0, 0x7fffffff, 0x00020000);
;   __amdgpu_buffer_rsrc_t rsBt = __builtin_amdgcn_make_buffer_rsrc((void*)Bt, 0, 0x7fffffff, 0x00020000);
;   unsigned offLDA[2], offLDB[2];
; #pragma unroll
;   for (int _i = 0; _i < 2; ++_i) {
;     int _r, _c; stage_rc(tid_ * 16 + _i * 8192, _r, _c);
;     offLDA[_i] = (unsigned)(_r * LDA + _c) * 2u; offLDB[_i] = (unsigned)(_r * LDB + _c) * 2u;
;   }
; template <int K, int LDA, int LDB, int EPI, int GRP, int NRM, int nTk = TOK / 256>
; DEVI void gemm_phase(const bf16* W, const bf16* X, int nF, const EpiArgs& e, bf16* shm) {
;     ...
;     if constexpr (NRM) {
;       if (threadIdx.x < 256) rsl[(it & 1) * 256 + threadIdx.x] = nxt;
;     }
	s_and_saveexec_b64 s[4:5], s[0:1]
	s_lshl_b32 s8, s16, 10
	s_and_b32 s8, s8, 0x400
	v_add_u32_e32 v2, s8, v137
	ds_write_b32 v2, v140
	s_or_b64 exec, exec, s[4:5]
	v_mov_b32_e32 v130, v136
	s_ashr_i32 s13, s12, 31
	v_bfe_i32 v4, v130, 27, 1
	v_lshlrev_b32_e32 v2, 4, v130
	v_lshrrev_b32_e32 v4, 22, v4
	v_add_u32_e32 v4, v2, v4
	v_and_b32_e32 v4, 0xfffffc00, v4
	v_sub_u32_e32 v4, v2, v4
	v_lshrrev_b32_e32 v5, 4, v4
	v_bitop3_b32 v4, v5, v4, 32 bitop3:0x6c
	s_waitcnt lgkmcnt(0)
	v_ashrrev_i32_e32 v3, 31, v130
	v_ashrrev_i32_e32 v6, 31, v4
	v_lshrrev_b32_e32 v3, 26, v3
	v_lshrrev_b32_e32 v6, 26, v6
	v_add_u32_e32 v3, v130, v3
	v_add_u32_e32 v6, v4, v6
	v_ashrrev_i32_e32 v3, 6, v3
	v_lshrrev_b32_e32 v7, 6, v6
	v_and_b32_e32 v6, 0xc0, v6
	v_lshlrev_b32_e32 v5, 3, v3
	v_lshlrev_b32_e32 v3, 5, v3
	v_sub_u32_e32 v4, v4, v6
	v_and_b32_e32 v5, 0xffff0, v5
	v_and_b32_e32 v3, 32, v3
	v_ashrrev_i16_sdwa v4, v139, sext(v4) dst_sel:DWORD dst_unused:UNUSED_PAD src0_sel:DWORD src1_sel:BYTE_0
	v_add_u32_sdwa v3, v3, sext(v4) dst_sel:DWORD dst_unused:UNUSED_PAD src0_sel:DWORD src1_sel:WORD_0
	v_add_lshl_u32 v4, v7, v5, 12
	v_lshl_add_u32 v141, v3, 1, v4
	v_add_u32_e32 v3, 0x2000, v2
	v_ashrrev_i32_e32 v4, 31, v3
	v_lshrrev_b32_e32 v4, 22, v4
	v_add_u32_e32 v4, v3, v4
	v_ashrrev_i32_e32 v4, 10, v4
	v_mul_i32_i24_e32 v5, 0x400, v4
	v_sub_u32_e32 v3, v3, v5
	v_lshrrev_b32_e32 v5, 4, v3
	v_bitop3_b32 v3, v5, v3, 32 bitop3:0x6c
	v_ashrrev_i32_e32 v6, 31, v3
	s_lshl_b64 s[4:5], s[12:13], 20
	v_lshrrev_b32_e32 v6, 26, v6
	s_add_u32 s4, s96, s4
	v_add_u32_e32 v6, v3, v6
	s_addc_u32 s5, s97, s5
	s_ashr_i32 s15, s14, 31
	v_lshrrev_b32_e32 v7, 6, v6
	v_and_b32_e32 v6, 0xc0, v6
	s_lshl_b64 s[8:9], s[14:15], 20
	v_lshlrev_b32_e32 v5, 3, v4
	v_lshlrev_b32_e32 v4, 5, v4
	v_sub_u32_e32 v3, v3, v6
	v_add_u32_e32 v145, s21, v2
	s_add_u32 s8, s19, s8
	v_and_b32_e32 v5, 0xffff0, v5
	v_and_b32_e32 v4, 32, v4
	v_ashrrev_i16_sdwa v3, v139, sext(v3) dst_sel:DWORD dst_unused:UNUSED_PAD src0_sel:DWORD src1_sel:BYTE_0
	v_readfirstlane_b32 s13, v145
	v_add_u32_e32 v146, 0x2000, v145
	s_addc_u32 s9, s20, s9
	v_add_u32_sdwa v3, v4, sext(v3) dst_sel:DWORD dst_unused:UNUSED_PAD src0_sel:DWORD src1_sel:WORD_0
	v_add_lshl_u32 v4, v7, v5, 12
	s_and_b32 s5, s5, 0xffff
	s_mov_b32 m0, s13
	v_readfirstlane_b32 s13, v146
	v_add_u32_e32 v147, 0, v2
	v_lshl_add_u32 v143, v3, 1, v4
	s_mov_b32 m0, s13
	v_readfirstlane_b32 s13, v147
	v_add_u32_e32 v148, 0x2000, v147
	s_and_b32 s9, s9, 0xffff
	s_mov_b32 s10, s6
	s_mov_b32 s11, s7
	s_mov_b32 m0, s13
	v_readfirstlane_b32 s13, v148
	v_add_u32_e32 v149, s22, v2
	s_mov_b32 m0, s13
	v_readfirstlane_b32 s13, v149
	v_add_u32_e32 v150, 0x2000, v149
	s_mov_b32 m0, s13
	v_readfirstlane_b32 s13, v150
	v_add_u32_e32 v151, 0x4000, v147
	s_mov_b32 m0, s13
	v_readfirstlane_b32 s13, v151
	v_add_u32_e32 v152, 0x6000, v147
	s_mov_b32 m0, s13
	v_readfirstlane_b32 s13, v152
	s_mov_b32 m0, s13
	v_ashrrev_i32_e32 v3, 8, v130
	s_branch .Lafter_loads_23871

; #define STAGE(P, BASE, LD, br, kt) do { const int _so = (int)(((br) * (LD) + (kt) * BK) * 2); \
;     _Pragma("unroll") for (int _i = 0; _i < 2; ++_i) { \
;       __builtin_amdgcn_raw_ptr_buffer_load_lds(rs##BASE, (__attribute__((address_space(3))) unsigned*)((char*)(P) + tid_ * 16 + _i * 8192), 16, (int)off##LD[_i], _so, 0, 0); } } while (0)
; template <int K, int LDA, int LDB>
; DEVI void gemm_tile(const bf16* __restrict__ A, const bf16* __restrict__ Bt, bf16* shm, acc_t& acc) {
;     ...
;   __amdgpu_buffer_rsrc_t rsA = __builtin_amdgcn_make_buffer_rsrc((void*)A, 0, 0x7fffffff, 0x00020000);
;   __amdgpu_buffer_rsrc_t rsBt = __builtin_amdgcn_make_buffer_rsrc((void*)Bt, 0, 0x7fffffff, 0x00020000);
;   unsigned offLDA[2], offLDB[2];
; #pragma unroll
;   for (int _i = 0; _i < 2; ++_i) {
;     int _r, _c; stage_rc(tid_ * 16 + _i * 8192, _r, _c);
;     offLDA[_i] = (unsigned)(_r * LDA + _c) * 2u; offLDB[_i] = (unsigned)(_r * LDB + _c) * 2u;
;   }
;   STAGE(SB(0, 0), Bt, LDB, 0, 0); STAGE(SA(0, 0), A, LDA, 0, 0);
;   STAGE(SB(0, 1), Bt, LDB, HALF, 0); STAGE(SA(0, 1), A, LDA, HALF, 0);
.LBB0_1233:
	s_or_b64 exec, exec, s[4:5]
	s_load_dword s4, s[84:85], 0x10
	s_waitcnt lgkmcnt(0)
	s_lshr_b32 s4, s4, 16
	s_cmp_lg_u32 s4, 0
	s_cselect_b64 s[4:5], -1, 0
	s_cmp_lg_u64 s[4:5], 0
	s_addc_u32 s42, s42, s33
	s_cmpk_gt_i32 s42, 0x15ff
	s_cselect_b64 s[4:5], -1, 0
	s_and_b64 vcc, exec, s[4:5]
	s_cbranch_vccnz .LBB0_1236
	s_ashr_i32 s8, s42, 31
	s_lshr_b32 s8, s8, 29
	s_add_i32 s8, s42, s8
	s_ashr_i32 s9, s8, 3
	s_and_b32 s8, s8, -8
	s_sub_i32 s8, s42, s8
	s_cmp_lt_i32 s8, 0
	s_cselect_b32 s10, s17, 0x2c0
	s_mul_i32 s8, s10, s8
	s_add_i32 s8, s8, s9
	s_mul_hi_i32 s9, s8, 0x2e8ba2e9
	s_lshr_b32 s10, s9, 31
	s_ashr_i32 s9, s9, 6
	s_add_i32 s9, s9, s10
	s_lshl_b32 s10, s9, 3
	s_mulk_i32 s9, 0x160
	s_sub_i32 s8, s8, s9
	s_bfe_u32 s9, s8, 0x3001c
	s_add_i32 s11, s8, s9
	s_and_b32 s9, s11, 0xfff8
	s_sub_i32 s8, s8, s9
	s_sext_i32_i16 s8, s8
	s_add_i32 s10, s10, s8
	v_mov_b32_e32 v220, v136
	v_bfe_i32 v215, v220, 27, 1
	v_lshlrev_b32_e32 v213, 4, v220
	v_lshrrev_b32_e32 v215, 22, v215
	v_add_u32_e32 v215, v213, v215
	v_and_b32_e32 v215, 0xfffffc00, v215
	v_sub_u32_e32 v215, v213, v215
	v_lshrrev_b32_e32 v216, 4, v215
	v_bitop3_b32 v215, v216, v215, 32 bitop3:0x6c
	v_ashrrev_i32_e32 v214, 31, v220
	v_ashrrev_i32_e32 v217, 31, v215
	v_lshrrev_b32_e32 v214, 26, v214
	v_lshrrev_b32_e32 v217, 26, v217
	v_add_u32_e32 v214, v220, v214
	v_add_u32_e32 v217, v215, v217
	v_ashrrev_i32_e32 v214, 6, v214
	v_lshrrev_b32_e32 v218, 6, v217
	v_and_b32_e32 v217, 0xc0, v217
	v_lshlrev_b32_e32 v216, 3, v214
	v_lshlrev_b32_e32 v214, 5, v214
	v_sub_u32_e32 v215, v215, v217
	v_and_b32_e32 v216, 0xffff0, v216
	v_and_b32_e32 v214, 32, v214
	v_ashrrev_i16_sdwa v215, v139, sext(v215) dst_sel:DWORD dst_unused:UNUSED_PAD src0_sel:DWORD src1_sel:BYTE_0
	v_add_u32_sdwa v214, v214, sext(v215) dst_sel:DWORD dst_unused:UNUSED_PAD src0_sel:DWORD src1_sel:WORD_0
	v_add_lshl_u32 v215, v218, v216, 12
	v_lshl_add_u32 v141, v214, 1, v215
	v_add_u32_e32 v214, 0x2000, v213
	v_ashrrev_i32_e32 v215, 31, v214
	v_lshrrev_b32_e32 v215, 22, v215
	v_add_u32_e32 v215, v214, v215
	v_ashrrev_i32_e32 v215, 10, v215
	v_mul_i32_i24_e32 v216, 0x400, v215
	v_sub_u32_e32 v214, v214, v216
	v_lshrrev_b32_e32 v216, 4, v214
	v_bitop3_b32 v214, v216, v214, 32 bitop3:0x6c
	v_ashrrev_i32_e32 v217, 31, v214
	v_lshrrev_b32_e32 v217, 26, v217
	v_add_u32_e32 v217, v214, v217
	v_lshrrev_b32_e32 v218, 6, v217
	v_and_b32_e32 v217, 0xc0, v217
	v_lshlrev_b32_e32 v216, 3, v215
	v_lshlrev_b32_e32 v215, 5, v215
	v_sub_u32_e32 v214, v214, v217
	v_add_u32_e32 v145, s21, v213
	v_and_b32_e32 v216, 0xffff0, v216
	v_and_b32_e32 v215, 32, v215
	v_ashrrev_i16_sdwa v214, v139, sext(v214) dst_sel:DWORD dst_unused:UNUSED_PAD src0_sel:DWORD src1_sel:BYTE_0
	v_add_u32_e32 v146, 0x2000, v145
	v_add_u32_sdwa v214, v215, sext(v214) dst_sel:DWORD dst_unused:UNUSED_PAD src0_sel:DWORD src1_sel:WORD_0
	v_add_lshl_u32 v215, v218, v216, 12
	v_add_u32_e32 v147, 0, v213
	v_lshl_add_u32 v143, v214, 1, v215
	v_add_u32_e32 v148, 0x2000, v147
	v_add_u32_e32 v149, s22, v213
	v_add_u32_e32 v150, 0x2000, v149
	v_add_u32_e32 v151, 0x4000, v147
	v_add_u32_e32 v152, 0x6000, v147
	v_ashrrev_i32_e32 v214, 8, v220
	s_sext_i32_i16 s46, s11
	s_ashr_i32 s46, s46, 3
	s_mov_b32 s48, s10
	s_ashr_i32 s49, s10, 31
	s_lshl_b64 s[48:49], s[48:49], 20
	s_add_u32 s48, s96, s48
	s_addc_u32 s49, s97, s49
	s_and_b32 s49, s49, 0xffff
	s_mov_b32 s50, s6
	s_mov_b32 s51, s7
	v_readfirstlane_b32 s45, v145
	s_mov_b32 m0, s45
	s_nop 0
	buffer_load_dwordx4 v141, s[48:51], 0 offen lds
	v_readfirstlane_b32 s45, v146
	s_mov_b32 m0, s45
	s_nop 0
	buffer_load_dwordx4 v143, s[48:51], 0 offen lds
	v_readfirstlane_b32 s45, v149
	s_mov_b32 m0, s45
	s_nop 0
	buffer_load_dwordx4 v141, s[48:51], s23 offen lds
	v_readfirstlane_b32 s45, v150
	s_mov_b32 m0, s45
	s_nop 0
	buffer_load_dwordx4 v143, s[48:51], s23 offen lds
	s_mov_b32 s48, s46
	s_ashr_i32 s49, s46, 31
	s_lshl_b64 s[48:49], s[48:49], 20
	s_add_u32 s48, s19, s48
	s_addc_u32 s49, s20, s49
	s_and_b32 s49, s49, 0xffff
	s_mov_b32 s50, s6
	s_mov_b32 s51, s7
	v_readfirstlane_b32 s45, v147
	s_mov_b32 m0, s45
	s_nop 0
	buffer_load_dwordx4 v141, s[48:51], 0 offen lds
	v_readfirstlane_b32 s45, v148
	s_mov_b32 m0, s45
	s_nop 0
	buffer_load_dwordx4 v143, s[48:51], 0 offen lds
	v_readfirstlane_b32 s45, v151
	s_mov_b32 m0, s45
	s_nop 0
	buffer_load_dwordx4 v141, s[48:51], s23 offen lds
	v_readfirstlane_b32 s45, v152
	s_mov_b32 m0, s45
	s_nop 0
	buffer_load_dwordx4 v143, s[48:51], s23 offen lds
	s_and_saveexec_b64 s[8:9], s[0:1]
	s_cbranch_execz .LBB0_1223
; template <int K, int LDA, int LDB, int EPI, int GRP, int NRM, int nTk = TOK / 256>
; DEVI void gemm_phase(const bf16* W, const bf16* X, int nF, const EpiArgs& e, bf16* shm) {
;     ...
;       if constexpr (NRM) {
;         if (threadIdx.x < 256) {
;           const int tok = pm2 * 256 + threadIdx.x;
;           float sum = 0.f;
; #pragma unroll
;           for (int i = 0; i < 16; ++i) sum += e.st[i * TOK + tok];
;           nxt = rsqrtf(sum * (1.f / DM) + 1e-6f);
;         }
	v_lshl_or_b32 v132, s10, 8, v136
	v_ashrrev_i32_e32 v133, 31, v132
	v_lshl_add_u64 v[132:133], v[132:133], 2, s[94:95]
	v_add_co_u32_e32 v134, vcc, 0x20000, v132
	s_nop 1
	v_addc_co_u32_e32 v135, vcc, 0, v133, vcc
	v_add_co_u32_e32 v140, vcc, 0x40000, v132
	s_nop 1
	v_addc_co_u32_e32 v141, vcc, 0, v133, vcc
	v_add_co_u32_e32 v142, vcc, 0x60000, v132
	s_nop 1
	v_addc_co_u32_e32 v143, vcc, 0, v133, vcc
	v_add_co_u32_e32 v144, vcc, s23, v132
	s_nop 1
	v_addc_co_u32_e32 v145, vcc, 0, v133, vcc
	v_add_co_u32_e32 v146, vcc, 0xa0000, v132
	s_nop 1
	v_addc_co_u32_e32 v147, vcc, 0, v133, vcc
	v_add_co_u32_e32 v148, vcc, 0xc0000, v132
	s_nop 1
	v_addc_co_u32_e32 v149, vcc, 0, v133, vcc
	v_add_co_u32_e32 v150, vcc, 0xe0000, v132
	s_nop 1
	v_addc_co_u32_e32 v151, vcc, 0, v133, vcc
	global_load_dword v130, v[132:133], off
	global_load_dword v152, v[134:135], off
	global_load_dword v153, v[140:141], off
	global_load_dword v154, v[142:143], off
	global_load_dword v155, v[144:145], off
	global_load_dword v156, v[146:147], off
	global_load_dword v157, v[148:149], off
	global_load_dword v158, v[150:151], off
	v_add_co_u32_e32 v134, vcc, 0x100000, v132
	s_waitcnt vmcnt(7)
	v_add_f32_e32 v130, 0, v130
	v_addc_co_u32_e32 v135, vcc, 0, v133, vcc
	v_add_co_u32_e32 v140, vcc, 0x120000, v132
	s_waitcnt vmcnt(6)
	v_add_f32_e32 v130, v130, v152
	v_addc_co_u32_e32 v141, vcc, 0, v133, vcc
	v_add_co_u32_e32 v142, vcc, 0x140000, v132
	s_waitcnt vmcnt(5)
	v_add_f32_e32 v130, v130, v153
	v_addc_co_u32_e32 v143, vcc, 0, v133, vcc
	v_add_co_u32_e32 v144, vcc, 0x160000, v132
	s_waitcnt vmcnt(4)
	v_add_f32_e32 v130, v130, v154
	v_addc_co_u32_e32 v145, vcc, 0, v133, vcc
	v_add_co_u32_e32 v146, vcc, 0x180000, v132
	s_waitcnt vmcnt(3)
	v_add_f32_e32 v130, v130, v155
	v_addc_co_u32_e32 v147, vcc, 0, v133, vcc
	v_add_co_u32_e32 v148, vcc, 0x1a0000, v132
	s_waitcnt vmcnt(2)
	v_add_f32_e32 v130, v130, v156
	v_addc_co_u32_e32 v149, vcc, 0, v133, vcc
	v_add_co_u32_e32 v150, vcc, 0x1c0000, v132
	s_waitcnt vmcnt(1)
	v_add_f32_e32 v130, v130, v157
	v_addc_co_u32_e32 v151, vcc, 0, v133, vcc
	v_add_co_u32_e32 v132, vcc, 0x1e0000, v132
	s_waitcnt vmcnt(0)
	v_add_f32_e32 v130, v130, v158
	v_addc_co_u32_e32 v133, vcc, 0, v133, vcc
	global_load_dword v134, v[134:135], off
	s_nop 0
	global_load_dword v135, v[140:141], off
	s_nop 0
	global_load_dword v140, v[142:143], off
	global_load_dword v141, v[144:145], off
	s_nop 0
	global_load_dword v142, v[146:147], off
	global_load_dword v143, v[148:149], off
	global_load_dword v144, v[150:151], off
	s_nop 0
	global_load_dword v132, v[132:133], off
	s_waitcnt vmcnt(7)
	v_add_f32_e32 v130, v130, v134
	s_waitcnt vmcnt(6)
	v_add_f32_e32 v130, v130, v135
	s_waitcnt vmcnt(5)
	v_add_f32_e32 v130, v130, v140
	s_waitcnt vmcnt(4)
	v_add_f32_e32 v130, v130, v141
	s_waitcnt vmcnt(3)
	v_add_f32_e32 v130, v130, v142
	s_waitcnt vmcnt(2)
	v_add_f32_e32 v130, v130, v143
	s_waitcnt vmcnt(1)
	v_add_f32_e32 v130, v130, v144
	s_waitcnt vmcnt(0)
	v_add_f32_e32 v130, v130, v132
	v_fmamk_f32 v130, v130, 0x3a000000, v138
	v_mul_f32_e32 v132, 0x4b800000, v130
	v_cmp_gt_f32_e32 vcc, s40, v130
	s_nop 1
	v_cndmask_b32_e32 v130, v130, v132, vcc
	v_rsq_f32_e32 v130, v130
	s_nop 0
	v_mul_f32_e32 v132, 0x45800000, v130
	v_cndmask_b32_e32 v140, v130, v132, vcc
	s_branch .LBB0_1223

; DEVI float silu(float x) { return x * __builtin_amdgcn_rcpf(1.f + __expf(-x)); }
; template <int EPI, int NRM>
; DEVI void epilogue(acc_t& acc, int pn, int trow, const EpiArgs& e, const float* rl, bf16* shmx) {
;     ...
;   const int fl0 = wr * 64 + fq * 4;
;   const int tk0 = trow + wc * 32 + fr;
;   float rs[2][2];
;   if constexpr (NRM) {
; #pragma unroll
;     for (int bj = 0; bj < 2; ++bj)
; #pragma unroll
;       for (int n = 0; n < 2; ++n) rs[bj][n] = rl[wc * 32 + fr + bj * 128 + n * 16];
;     ...
;   } else if constexpr (EPI == EPI_SWIGLU) {
; #pragma unroll
;     for (int bj = 0; bj < 2; ++bj)
; #pragma unroll
;       for (int m = 0; m < 4; ++m)
; #pragma unroll
;         for (int n = 0; n < 2; ++n) {
;           float r[4];
; #pragma unroll
;           for (int j = 0; j < 4; ++j) r[j] = silu(acc[0][bj][m][n][j] * rs[bj][n]) * (acc[1][bj][m][n][j] * rs[bj][n]);
;           uint2 o; o.x = pack2(r[0], r[1]); o.y = pack2(r[2], r[3]);
;           const unsigned off = (unsigned)((tk0 + bj * 128 + n * 16) * DFF + pn * 128 + m * 16 + fl0);
;           *reinterpret_cast<uint2*>(e.o0 + off) = o;
;         }
.LBB0_1655:
	v_and_b32_e32 v170, 15, v131
	v_bfe_u32 v171, v131, 4, 2
	v_lshrrev_b32_e32 v172, 6, v131
	v_and_b32_e32 v173, 3, v172
	v_lshrrev_b32_e32 v174, 2, v172
	v_lshlrev_b32_e32 v175, 13, v173
	v_lshl_add_u32 v175, v174, 16, v175
	v_add_u32_e32 v175, 0x8000, v175
	v_lshl_add_u32 v176, v170, 7, v175
	v_and_b32_e32 v177, 1, v171
	v_lshl_add_u32 v176, v177, 3, v176
	v_lshrrev_b32_e32 v177, 1, v171
	v_and_b32_e32 v178, 7, v170
	v_add_u32_e32 v179, 0, v177
	v_xor_b32_e32 v179, v179, v178
	v_lshl_add_u32 v164, v179, 4, v176
	v_add_u32_e32 v179, 2, v177
	v_xor_b32_e32 v179, v179, v178
	v_lshl_add_u32 v165, v179, 4, v176
	v_add_u32_e32 v179, 4, v177
	v_xor_b32_e32 v179, v179, v178
	v_lshl_add_u32 v166, v179, 4, v176
	v_add_u32_e32 v179, 6, v177
	v_xor_b32_e32 v179, v179, v178
	v_lshl_add_u32 v167, v179, 4, v176
	v_and_b32_e32 v180, 63, v131
	v_lshl_add_u32 v168, v180, 4, v175
	v_lshrrev_b32_e32 v181, 3, v180
	v_and_b32_e32 v182, 7, v180
	v_xor_b32_e32 v182, v182, v181
	s_lshl_b32 s9, s12, 8
	v_lshl_add_u32 v183, v173, 5, v181
	v_add_u32_e32 v183, s9, v183
	v_mul_u32_u24_e32 v183, 0x1600, v183
	s_lshl_b32 s9, s14, 7
	v_lshl_add_u32 v179, v174, 6, s9
	v_lshl_add_u32 v179, v182, 3, v179
	v_add_lshl_u32 v169, v183, v179, 1
	v_mov_b32_e32 v132, v131
	s_lshl_b32 s11, s16, 10
	s_and_b32 s11, s11, 0x400
	v_and_b32_e32 v142, 15, v132
	v_ashrrev_i32_e32 v143, 2, v132
	v_lshrrev_b32_e32 v144, 2, v132
	v_lshrrev_b32_e32 v132, 1, v132
	s_add_i32 s11, s11, 0
	v_and_b32_e32 v132, 0x60, v132
	s_add_i32 s11, s11, 0x20000
	v_lshlrev_b32_e32 v134, 2, v132
	v_lshlrev_b32_e32 v135, 2, v142
	v_add3_u32 v134, s11, v134, v135
	ds_read2_b32 v[136:137], v134 offset1:16
	ds_read2_b32 v[134:135], v134 offset0:128 offset1:144
	s_lshl_b32 s9, s12, 8
	v_or3_b32 v132, v142, s9, v132
	s_lshl_b32 s9, s14, 7
	s_waitcnt lgkmcnt(1)
	v_pk_mul_f32 v[122:123], v[122:123], v[136:137] op_sel_hi:[1,0]
	v_and_or_b32 v142, v144, 12, s9
	v_mul_f32_e32 v144, 0xbfb8aa3b, v122
	v_mul_f32_e32 v145, 0xbfb8aa3b, v123
	v_exp_f32_e32 v144, v144
	v_exp_f32_e32 v145, v145
	v_and_b32_e32 v143, 0xffffffc0, v143
	v_pk_mul_f32 v[124:125], v[124:125], v[136:137] op_sel_hi:[1,0]
	v_add_u32_e32 v146, v142, v143
	v_add_f32_e32 v142, 1.0, v144
	v_add_f32_e32 v143, 1.0, v145
	v_mul_f32_e32 v144, 0xbfb8aa3b, v124
	v_mul_f32_e32 v145, 0xbfb8aa3b, v125
	v_rcp_f32_e32 v142, v142
	v_rcp_f32_e32 v143, v143
	v_exp_f32_e32 v144, v144
	v_exp_f32_e32 v145, v145
	v_pk_mul_f32 v[126:127], v[126:127], v[136:137] op_sel_hi:[1,0]
	v_pk_mul_f32 v[122:123], v[122:123], v[142:143]
	v_add_f32_e32 v142, 1.0, v144
	v_add_f32_e32 v143, 1.0, v145
	v_rcp_f32_e32 v142, v142
	v_rcp_f32_e32 v143, v143
	v_pk_mul_f32 v[122:123], v[126:127], v[122:123]
	v_pk_mul_f32 v[106:107], v[106:107], v[136:137] op_sel_hi:[1,0]
	v_cvt_pk_bf16_f32 v126, v122, v123
	v_pk_mul_f32 v[122:123], v[124:125], v[142:143]
	v_pk_mul_f32 v[124:125], v[128:129], v[136:137] op_sel_hi:[1,0]
	v_pk_mul_f32 v[108:109], v[108:109], v[136:137] op_sel_hi:[1,0]
	v_pk_mul_f32 v[122:123], v[124:125], v[122:123]
	v_pk_mul_f32 v[110:111], v[110:111], v[136:137] op_sel_hi:[1,0]
	v_cvt_pk_bf16_f32 v127, v122, v123
	v_mul_lo_u32 v123, v132, s41
	v_mov_b32_e32 v122, v137
	v_pk_mul_f32 v[114:115], v[114:115], v[122:123] op_sel_hi:[1,0]
	v_add_u32_e32 v132, v146, v123
	v_mul_f32_e32 v128, 0xbfb8aa3b, v114
	v_mul_f32_e32 v129, 0xbfb8aa3b, v115
	v_exp_f32_e32 v128, v128
	v_exp_f32_e32 v129, v129
	v_lshl_add_u64 v[124:125], v[132:133], 1, s[2:3]
	v_pk_mul_f32 v[116:117], v[116:117], v[122:123] op_sel_hi:[1,0]
	ds_write_b64 v164, v[126:127]
	v_add_f32_e32 v124, 1.0, v128
	v_add_f32_e32 v125, 1.0, v129
	v_mul_f32_e32 v126, 0xbfb8aa3b, v116
	v_mul_f32_e32 v127, 0xbfb8aa3b, v117
	v_rcp_f32_e32 v124, v124
	v_rcp_f32_e32 v125, v125
	v_exp_f32_e32 v126, v126
	v_exp_f32_e32 v127, v127
	v_pk_mul_f32 v[118:119], v[118:119], v[122:123] op_sel_hi:[1,0]
	v_pk_mul_f32 v[114:115], v[114:115], v[124:125]
	v_add_f32_e32 v124, 1.0, v126
	v_add_f32_e32 v125, 1.0, v127
	v_rcp_f32_e32 v124, v124
	v_rcp_f32_e32 v125, v125
	v_pk_mul_f32 v[114:115], v[118:119], v[114:115]
	v_pk_mul_f32 v[118:119], v[120:121], v[122:123] op_sel_hi:[1,0]
	v_cvt_pk_bf16_f32 v114, v114, v115
	v_pk_mul_f32 v[116:117], v[116:117], v[124:125]
	v_pk_mul_f32 v[98:99], v[98:99], v[122:123] op_sel_hi:[1,0]
	v_pk_mul_f32 v[116:117], v[118:119], v[116:117]
	v_add_u32_e32 v118, 0x16000, v123
	v_add_u32_e32 v132, v118, v146
	v_cvt_pk_bf16_f32 v115, v116, v117
	v_lshl_add_u64 v[116:117], v[132:133], 1, s[2:3]
	ds_write_b64 v164, v[114:115] offset:2048
	v_mul_f32_e32 v114, 0xbfb8aa3b, v106
	v_mul_f32_e32 v115, 0xbfb8aa3b, v107
	v_exp_f32_e32 v114, v114
	v_exp_f32_e32 v115, v115
	v_mul_f32_e32 v117, 0xbfb8aa3b, v108
	v_mul_f32_e32 v119, 0xbfb8aa3b, v109
	v_add_f32_e32 v114, 1.0, v114
	v_add_f32_e32 v115, 1.0, v115
	v_rcp_f32_e32 v114, v114
	v_rcp_f32_e32 v115, v115
	v_exp_f32_e32 v117, v117
	v_exp_f32_e32 v119, v119
	v_or_b32_e32 v116, 16, v146
	v_pk_mul_f32 v[106:107], v[106:107], v[114:115]
	v_add_f32_e32 v114, 1.0, v117
	v_add_f32_e32 v115, 1.0, v119
	v_rcp_f32_e32 v114, v114
	v_rcp_f32_e32 v115, v115
	v_pk_mul_f32 v[106:107], v[110:111], v[106:107]
	v_pk_mul_f32 v[110:111], v[112:113], v[136:137] op_sel_hi:[1,0]
	v_add_u32_e32 v132, v116, v123
	v_pk_mul_f32 v[108:109], v[108:109], v[114:115]
	v_cvt_pk_bf16_f32 v106, v106, v107
	v_pk_mul_f32 v[108:109], v[110:111], v[108:109]
	v_mul_f32_e32 v110, 0xbfb8aa3b, v98
	v_mul_f32_e32 v111, 0xbfb8aa3b, v99
	v_exp_f32_e32 v110, v110
	v_exp_f32_e32 v111, v111
	v_cvt_pk_bf16_f32 v107, v108, v109
	v_lshl_add_u64 v[108:109], v[132:133], 1, s[2:3]
	v_pk_mul_f32 v[100:101], v[100:101], v[122:123] op_sel_hi:[1,0]
; DEVI float silu(float x) { return x * __builtin_amdgcn_rcpf(1.f + __expf(-x)); }
; template <int EPI, int NRM>
; DEVI void epilogue(acc_t& acc, int pn, int trow, const EpiArgs& e, const float* rl, bf16* shmx) {
;     ...
;   } else if constexpr (EPI == EPI_SWIGLU) {
; #pragma unroll
;     for (int bj = 0; bj < 2; ++bj)
; #pragma unroll
;       for (int m = 0; m < 4; ++m)
; #pragma unroll
;         for (int n = 0; n < 2; ++n) {
;           float r[4];
; #pragma unroll
;           for (int j = 0; j < 4; ++j) r[j] = silu(acc[0][bj][m][n][j] * rs[bj][n]) * (acc[1][bj][m][n][j] * rs[bj][n]);
;           uint2 o; o.x = pack2(r[0], r[1]); o.y = pack2(r[2], r[3]);
;           const unsigned off = (unsigned)((tk0 + bj * 128 + n * 16) * DFF + pn * 128 + m * 16 + fl0);
;           *reinterpret_cast<uint2*>(e.o0 + off) = o;
;         }
	ds_write_b64 v165, v[106:107]
	v_add_f32_e32 v106, 1.0, v110
	v_add_f32_e32 v107, 1.0, v111
	v_mul_f32_e32 v108, 0xbfb8aa3b, v100
	v_mul_f32_e32 v109, 0xbfb8aa3b, v101
	v_rcp_f32_e32 v106, v106
	v_rcp_f32_e32 v107, v107
	v_exp_f32_e32 v108, v108
	v_exp_f32_e32 v109, v109
	v_pk_mul_f32 v[102:103], v[102:103], v[122:123] op_sel_hi:[1,0]
	v_pk_mul_f32 v[98:99], v[98:99], v[106:107]
	v_add_f32_e32 v106, 1.0, v108
	v_add_f32_e32 v107, 1.0, v109
	v_rcp_f32_e32 v106, v106
	v_rcp_f32_e32 v107, v107
	v_pk_mul_f32 v[98:99], v[102:103], v[98:99]
	v_pk_mul_f32 v[102:103], v[104:105], v[122:123] op_sel_hi:[1,0]
	v_add_u32_e32 v132, v116, v118
	v_pk_mul_f32 v[100:101], v[100:101], v[106:107]
	v_cvt_pk_bf16_f32 v98, v98, v99
	v_pk_mul_f32 v[100:101], v[102:103], v[100:101]
	v_pk_mul_f32 v[90:91], v[90:91], v[136:137] op_sel_hi:[1,0]
	v_cvt_pk_bf16_f32 v99, v100, v101
	v_lshl_add_u64 v[100:101], v[132:133], 1, s[2:3]
	ds_write_b64 v165, v[98:99] offset:2048
	v_mul_f32_e32 v98, 0xbfb8aa3b, v90
	v_mul_f32_e32 v99, 0xbfb8aa3b, v91
	v_exp_f32_e32 v98, v98
	v_exp_f32_e32 v99, v99
	v_pk_mul_f32 v[92:93], v[92:93], v[136:137] op_sel_hi:[1,0]
	v_pk_mul_f32 v[94:95], v[94:95], v[136:137] op_sel_hi:[1,0]
	v_add_f32_e32 v98, 1.0, v98
	v_add_f32_e32 v99, 1.0, v99
	v_mul_f32_e32 v101, 0xbfb8aa3b, v92
	v_mul_f32_e32 v102, 0xbfb8aa3b, v93
	v_rcp_f32_e32 v98, v98
	v_rcp_f32_e32 v99, v99
	v_exp_f32_e32 v101, v101
	v_exp_f32_e32 v102, v102
	v_pk_mul_f32 v[82:83], v[82:83], v[122:123] op_sel_hi:[1,0]
	v_pk_mul_f32 v[90:91], v[90:91], v[98:99]
	v_add_f32_e32 v98, 1.0, v101
	v_add_f32_e32 v99, 1.0, v102
	v_rcp_f32_e32 v98, v98
	v_rcp_f32_e32 v99, v99
	v_pk_mul_f32 v[90:91], v[94:95], v[90:91]
	v_pk_mul_f32 v[94:95], v[96:97], v[136:137] op_sel_hi:[1,0]
	v_or_b32_e32 v100, 32, v146
	v_pk_mul_f32 v[92:93], v[92:93], v[98:99]
	v_add_u32_e32 v132, v100, v123
	v_pk_mul_f32 v[92:93], v[94:95], v[92:93]
	v_mul_f32_e32 v94, 0xbfb8aa3b, v82
	v_mul_f32_e32 v95, 0xbfb8aa3b, v83
	v_exp_f32_e32 v94, v94
	v_exp_f32_e32 v95, v95
	v_cvt_pk_bf16_f32 v90, v90, v91
	v_cvt_pk_bf16_f32 v91, v92, v93
	v_lshl_add_u64 v[92:93], v[132:133], 1, s[2:3]
	v_pk_mul_f32 v[84:85], v[84:85], v[122:123] op_sel_hi:[1,0]
	ds_write_b64 v166, v[90:91]
	v_add_f32_e32 v90, 1.0, v94
	v_add_f32_e32 v91, 1.0, v95
	v_mul_f32_e32 v92, 0xbfb8aa3b, v84
	v_mul_f32_e32 v93, 0xbfb8aa3b, v85
	v_rcp_f32_e32 v90, v90
	v_rcp_f32_e32 v91, v91
	v_exp_f32_e32 v92, v92
	v_exp_f32_e32 v93, v93
	v_pk_mul_f32 v[86:87], v[86:87], v[122:123] op_sel_hi:[1,0]
	v_pk_mul_f32 v[82:83], v[82:83], v[90:91]
	v_add_f32_e32 v90, 1.0, v92
	v_add_f32_e32 v91, 1.0, v93
	v_rcp_f32_e32 v90, v90
	v_rcp_f32_e32 v91, v91
	v_pk_mul_f32 v[82:83], v[86:87], v[82:83]
	v_pk_mul_f32 v[86:87], v[88:89], v[122:123] op_sel_hi:[1,0]
	v_add_u32_e32 v132, v100, v118
	v_pk_mul_f32 v[84:85], v[84:85], v[90:91]
	v_cvt_pk_bf16_f32 v82, v82, v83
	v_pk_mul_f32 v[84:85], v[86:87], v[84:85]
	v_pk_mul_f32 v[74:75], v[74:75], v[136:137] op_sel_hi:[1,0]
	v_cvt_pk_bf16_f32 v83, v84, v85
	v_lshl_add_u64 v[84:85], v[132:133], 1, s[2:3]
	ds_write_b64 v166, v[82:83] offset:2048
	v_mul_f32_e32 v82, 0xbfb8aa3b, v74
	v_mul_f32_e32 v83, 0xbfb8aa3b, v75
	v_exp_f32_e32 v82, v82
	v_exp_f32_e32 v83, v83
	v_pk_mul_f32 v[76:77], v[76:77], v[136:137] op_sel_hi:[1,0]
	v_pk_mul_f32 v[78:79], v[78:79], v[136:137] op_sel_hi:[1,0]
	v_add_f32_e32 v82, 1.0, v82
	v_add_f32_e32 v83, 1.0, v83
	v_mul_f32_e32 v85, 0xbfb8aa3b, v76
	v_mul_f32_e32 v86, 0xbfb8aa3b, v77
	v_rcp_f32_e32 v82, v82
	v_rcp_f32_e32 v83, v83
	v_exp_f32_e32 v85, v85
	v_exp_f32_e32 v86, v86
	v_pk_mul_f32 v[66:67], v[66:67], v[122:123] op_sel_hi:[1,0]
	v_pk_mul_f32 v[74:75], v[74:75], v[82:83]
	v_add_f32_e32 v82, 1.0, v85
	v_add_f32_e32 v83, 1.0, v86
	v_rcp_f32_e32 v82, v82
	v_rcp_f32_e32 v83, v83
	v_pk_mul_f32 v[74:75], v[78:79], v[74:75]
	v_pk_mul_f32 v[78:79], v[80:81], v[136:137] op_sel_hi:[1,0]
	v_or_b32_e32 v84, 48, v146
	v_pk_mul_f32 v[76:77], v[76:77], v[82:83]
	v_add_u32_e32 v132, v84, v123
	v_pk_mul_f32 v[76:77], v[78:79], v[76:77]
	v_mul_f32_e32 v78, 0xbfb8aa3b, v66
	v_mul_f32_e32 v79, 0xbfb8aa3b, v67
	v_exp_f32_e32 v78, v78
	v_exp_f32_e32 v79, v79
	v_cvt_pk_bf16_f32 v74, v74, v75
	v_cvt_pk_bf16_f32 v75, v76, v77
	v_lshl_add_u64 v[76:77], v[132:133], 1, s[2:3]
	v_pk_mul_f32 v[68:69], v[68:69], v[122:123] op_sel_hi:[1,0]
	ds_write_b64 v167, v[74:75]
	v_add_f32_e32 v74, 1.0, v78
	v_add_f32_e32 v75, 1.0, v79
	v_mul_f32_e32 v76, 0xbfb8aa3b, v68
	v_mul_f32_e32 v77, 0xbfb8aa3b, v69
	v_rcp_f32_e32 v74, v74
	v_rcp_f32_e32 v75, v75
	v_exp_f32_e32 v76, v76
	v_exp_f32_e32 v77, v77
	v_pk_mul_f32 v[70:71], v[70:71], v[122:123] op_sel_hi:[1,0]
	v_pk_mul_f32 v[66:67], v[66:67], v[74:75]
	v_add_f32_e32 v74, 1.0, v76
	v_add_f32_e32 v75, 1.0, v77
	v_rcp_f32_e32 v74, v74
	v_rcp_f32_e32 v75, v75
	v_pk_mul_f32 v[66:67], v[70:71], v[66:67]
	v_pk_mul_f32 v[70:71], v[72:73], v[122:123] op_sel_hi:[1,0]
	s_waitcnt lgkmcnt(0)
	v_pk_mul_f32 v[58:59], v[58:59], v[134:135] op_sel_hi:[1,0]
	v_pk_mul_f32 v[68:69], v[68:69], v[74:75]
	v_add_u32_e32 v132, v84, v118
	v_pk_mul_f32 v[68:69], v[70:71], v[68:69]
	v_mul_f32_e32 v70, 0xbfb8aa3b, v58
	v_mul_f32_e32 v71, 0xbfb8aa3b, v59
	v_exp_f32_e32 v70, v70
	v_exp_f32_e32 v71, v71
	v_cvt_pk_bf16_f32 v66, v66, v67
	v_cvt_pk_bf16_f32 v67, v68, v69
	v_lshl_add_u64 v[68:69], v[132:133], 1, s[2:3]
	v_pk_mul_f32 v[60:61], v[60:61], v[134:135] op_sel_hi:[1,0]
	ds_write_b64 v167, v[66:67] offset:2048
	s_waitcnt lgkmcnt(0)
	ds_read_b128 v[172:175], v168
	ds_read_b128 v[176:179], v168 offset:1024
	ds_read_b128 v[180:183], v168 offset:2048
	ds_read_b128 v[184:187], v168 offset:3072
	v_add_u32_e32 v204, 0x16000, v169
	v_add_u32_e32 v205, 0x2c000, v169
	v_add_u32_e32 v206, 0x42000, v169
	s_waitcnt lgkmcnt(3)
; DEVI float silu(float x) { return x * __builtin_amdgcn_rcpf(1.f + __expf(-x)); }
; template <int EPI, int NRM>
; DEVI void epilogue(acc_t& acc, int pn, int trow, const EpiArgs& e, const float* rl, bf16* shmx) {
;     ...
; #pragma unroll
;     for (int bj = 0; bj < 2; ++bj)
; #pragma unroll
;       for (int m = 0; m < 4; ++m)
; #pragma unroll
;         for (int n = 0; n < 2; ++n) {
;           float r[4];
; #pragma unroll
;           for (int j = 0; j < 4; ++j) r[j] = silu(acc[0][bj][m][n][j] * rs[bj][n]) * (acc[1][bj][m][n][j] * rs[bj][n]);
;           uint2 o; o.x = pack2(r[0], r[1]); o.y = pack2(r[2], r[3]);
;           const unsigned off = (unsigned)((tk0 + bj * 128 + n * 16) * DFF + pn * 128 + m * 16 + fl0);
;           *reinterpret_cast<uint2*>(e.o0 + off) = o;
;         }
	global_store_dwordx4 v169, v[172:175], s[2:3] nt
	s_waitcnt lgkmcnt(2)
	global_store_dwordx4 v204, v[176:179], s[2:3] nt
	s_waitcnt lgkmcnt(1)
	global_store_dwordx4 v205, v[180:183], s[2:3] nt
	s_waitcnt lgkmcnt(0)
	global_store_dwordx4 v206, v[184:187], s[2:3] nt
	v_add_f32_e32 v66, 1.0, v70
	v_add_f32_e32 v67, 1.0, v71
	v_mul_f32_e32 v68, 0xbfb8aa3b, v60
	v_mul_f32_e32 v69, 0xbfb8aa3b, v61
	v_rcp_f32_e32 v66, v66
	v_rcp_f32_e32 v67, v67
	v_exp_f32_e32 v68, v68
	v_exp_f32_e32 v69, v69
	v_pk_mul_f32 v[62:63], v[62:63], v[134:135] op_sel_hi:[1,0]
	v_pk_mul_f32 v[58:59], v[58:59], v[66:67]
	v_add_f32_e32 v66, 1.0, v68
	v_add_f32_e32 v67, 1.0, v69
	v_rcp_f32_e32 v66, v66
	v_rcp_f32_e32 v67, v67
	v_pk_mul_f32 v[58:59], v[62:63], v[58:59]
	v_pk_mul_f32 v[42:43], v[42:43], v[134:135] op_sel_hi:[1,0]
	v_cvt_pk_bf16_f32 v62, v58, v59
	v_pk_mul_f32 v[58:59], v[60:61], v[66:67]
	v_pk_mul_f32 v[60:61], v[64:65], v[134:135] op_sel_hi:[1,0]
	v_pk_mul_f32 v[44:45], v[44:45], v[134:135] op_sel_hi:[1,0]
	v_pk_mul_f32 v[58:59], v[60:61], v[58:59]
	v_pk_mul_f32 v[46:47], v[46:47], v[134:135] op_sel_hi:[1,0]
	v_cvt_pk_bf16_f32 v63, v58, v59
	v_add_u32_e32 v59, 0xb0000, v123
	v_mov_b32_e32 v58, v135
	v_pk_mul_f32 v[50:51], v[50:51], v[58:59] op_sel_hi:[1,0]
	v_add_u32_e32 v132, v59, v146
	v_mul_f32_e32 v64, 0xbfb8aa3b, v50
	v_mul_f32_e32 v65, 0xbfb8aa3b, v51
	v_exp_f32_e32 v64, v64
	v_exp_f32_e32 v65, v65
	v_lshl_add_u64 v[60:61], v[132:133], 1, s[2:3]
	v_pk_mul_f32 v[52:53], v[52:53], v[58:59] op_sel_hi:[1,0]
	ds_write_b64 v164, v[62:63] offset:4096
	v_add_f32_e32 v60, 1.0, v64
	v_add_f32_e32 v61, 1.0, v65
	v_mul_f32_e32 v62, 0xbfb8aa3b, v52
	v_mul_f32_e32 v63, 0xbfb8aa3b, v53
	v_rcp_f32_e32 v60, v60
	v_rcp_f32_e32 v61, v61
	v_exp_f32_e32 v62, v62
	v_exp_f32_e32 v63, v63
	v_pk_mul_f32 v[54:55], v[54:55], v[58:59] op_sel_hi:[1,0]
	v_pk_mul_f32 v[50:51], v[50:51], v[60:61]
	v_add_f32_e32 v60, 1.0, v62
	v_add_f32_e32 v61, 1.0, v63
	v_rcp_f32_e32 v60, v60
	v_rcp_f32_e32 v61, v61
	v_pk_mul_f32 v[50:51], v[54:55], v[50:51]
	v_pk_mul_f32 v[54:55], v[56:57], v[58:59] op_sel_hi:[1,0]
	v_mul_f32_e32 v56, 0xbfb8aa3b, v43
	v_pk_mul_f32 v[52:53], v[52:53], v[60:61]
	v_exp_f32_e32 v56, v56
	v_pk_mul_f32 v[52:53], v[54:55], v[52:53]
	v_mul_f32_e32 v55, 0xbfb8aa3b, v42
	v_exp_f32_e32 v55, v55
	v_add_u32_e32 v54, 0xc6000, v123
	v_add_u32_e32 v132, v54, v146
	v_cvt_pk_bf16_f32 v50, v50, v51
	v_cvt_pk_bf16_f32 v51, v52, v53
	v_lshl_add_u64 v[52:53], v[132:133], 1, s[2:3]
	ds_write_b64 v164, v[50:51] offset:6144
	v_add_f32_e32 v50, 1.0, v55
	v_add_f32_e32 v51, 1.0, v56
	v_mul_f32_e32 v52, 0xbfb8aa3b, v44
	v_mul_f32_e32 v53, 0xbfb8aa3b, v45
	v_rcp_f32_e32 v50, v50
	v_rcp_f32_e32 v51, v51
	v_exp_f32_e32 v52, v52
	v_exp_f32_e32 v53, v53
	v_pk_mul_f32 v[34:35], v[34:35], v[58:59] op_sel_hi:[1,0]
	v_pk_mul_f32 v[42:43], v[42:43], v[50:51]
	v_add_f32_e32 v50, 1.0, v52
	v_add_f32_e32 v51, 1.0, v53
	v_rcp_f32_e32 v50, v50
	v_rcp_f32_e32 v51, v51
	v_pk_mul_f32 v[42:43], v[46:47], v[42:43]
	v_pk_mul_f32 v[46:47], v[48:49], v[134:135] op_sel_hi:[1,0]
	v_add_u32_e32 v132, v116, v59
	v_pk_mul_f32 v[44:45], v[44:45], v[50:51]
	v_cvt_pk_bf16_f32 v42, v42, v43
	v_pk_mul_f32 v[44:45], v[46:47], v[44:45]
	v_mul_f32_e32 v46, 0xbfb8aa3b, v34
	v_mul_f32_e32 v47, 0xbfb8aa3b, v35
	v_exp_f32_e32 v46, v46
	v_exp_f32_e32 v47, v47
	v_cvt_pk_bf16_f32 v43, v44, v45
	v_lshl_add_u64 v[44:45], v[132:133], 1, s[2:3]
	v_pk_mul_f32 v[36:37], v[36:37], v[58:59] op_sel_hi:[1,0]
	ds_write_b64 v165, v[42:43] offset:4096
	v_add_f32_e32 v42, 1.0, v46
	v_add_f32_e32 v43, 1.0, v47
	v_mul_f32_e32 v44, 0xbfb8aa3b, v36
	v_mul_f32_e32 v45, 0xbfb8aa3b, v37
	v_rcp_f32_e32 v42, v42
	v_rcp_f32_e32 v43, v43
	v_exp_f32_e32 v44, v44
	v_exp_f32_e32 v45, v45
	v_pk_mul_f32 v[38:39], v[38:39], v[58:59] op_sel_hi:[1,0]
	v_pk_mul_f32 v[34:35], v[34:35], v[42:43]
	v_add_f32_e32 v42, 1.0, v44
	v_add_f32_e32 v43, 1.0, v45
	v_rcp_f32_e32 v42, v42
	v_rcp_f32_e32 v43, v43
	v_pk_mul_f32 v[34:35], v[38:39], v[34:35]
	v_pk_mul_f32 v[38:39], v[40:41], v[58:59] op_sel_hi:[1,0]
	v_pk_mul_f32 v[26:27], v[26:27], v[134:135] op_sel_hi:[1,0]
	v_pk_mul_f32 v[36:37], v[36:37], v[42:43]
	v_add_u32_e32 v132, v116, v54
	v_pk_mul_f32 v[36:37], v[38:39], v[36:37]
	v_mul_f32_e32 v38, 0xbfb8aa3b, v26
	v_mul_f32_e32 v39, 0xbfb8aa3b, v27
	v_exp_f32_e32 v38, v38
	v_exp_f32_e32 v39, v39
	v_cvt_pk_bf16_f32 v34, v34, v35
	v_cvt_pk_bf16_f32 v35, v36, v37
	v_lshl_add_u64 v[36:37], v[132:133], 1, s[2:3]
	v_pk_mul_f32 v[28:29], v[28:29], v[134:135] op_sel_hi:[1,0]
	ds_write_b64 v165, v[34:35] offset:6144
	v_add_f32_e32 v34, 1.0, v38
	v_add_f32_e32 v35, 1.0, v39
	v_mul_f32_e32 v36, 0xbfb8aa3b, v28
	v_mul_f32_e32 v37, 0xbfb8aa3b, v29
	v_rcp_f32_e32 v34, v34
	v_rcp_f32_e32 v35, v35
	v_exp_f32_e32 v36, v36
	v_exp_f32_e32 v37, v37
	v_pk_mul_f32 v[30:31], v[30:31], v[134:135] op_sel_hi:[1,0]
	v_pk_mul_f32 v[26:27], v[26:27], v[34:35]
	v_add_f32_e32 v34, 1.0, v36
	v_add_f32_e32 v35, 1.0, v37
	v_rcp_f32_e32 v34, v34
	v_rcp_f32_e32 v35, v35
	v_pk_mul_f32 v[26:27], v[30:31], v[26:27]
	v_pk_mul_f32 v[30:31], v[32:33], v[134:135] op_sel_hi:[1,0]
	v_pk_mul_f32 v[18:19], v[18:19], v[58:59] op_sel_hi:[1,0]
	v_pk_mul_f32 v[28:29], v[28:29], v[34:35]
	v_add_u32_e32 v132, v100, v59
	v_pk_mul_f32 v[28:29], v[30:31], v[28:29]
	v_mul_f32_e32 v30, 0xbfb8aa3b, v18
	v_mul_f32_e32 v31, 0xbfb8aa3b, v19
	v_exp_f32_e32 v30, v30
	v_exp_f32_e32 v31, v31
	v_cvt_pk_bf16_f32 v26, v26, v27
	v_cvt_pk_bf16_f32 v27, v28, v29
	v_lshl_add_u64 v[28:29], v[132:133], 1, s[2:3]
	v_pk_mul_f32 v[20:21], v[20:21], v[58:59] op_sel_hi:[1,0]
	ds_write_b64 v166, v[26:27] offset:4096
	v_add_f32_e32 v26, 1.0, v30
; DEVI float silu(float x) { return x * __builtin_amdgcn_rcpf(1.f + __expf(-x)); }
; template <int EPI, int NRM>
; DEVI void epilogue(acc_t& acc, int pn, int trow, const EpiArgs& e, const float* rl, bf16* shmx) {
;     ...
; #pragma unroll
;     for (int bj = 0; bj < 2; ++bj)
; #pragma unroll
;       for (int m = 0; m < 4; ++m)
; #pragma unroll
;         for (int n = 0; n < 2; ++n) {
;           float r[4];
; #pragma unroll
;           for (int j = 0; j < 4; ++j) r[j] = silu(acc[0][bj][m][n][j] * rs[bj][n]) * (acc[1][bj][m][n][j] * rs[bj][n]);
;           uint2 o; o.x = pack2(r[0], r[1]); o.y = pack2(r[2], r[3]);
;           const unsigned off = (unsigned)((tk0 + bj * 128 + n * 16) * DFF + pn * 128 + m * 16 + fl0);
;           *reinterpret_cast<uint2*>(e.o0 + off) = o;
;         }
	v_add_f32_e32 v27, 1.0, v31
	v_mul_f32_e32 v28, 0xbfb8aa3b, v20
	v_mul_f32_e32 v29, 0xbfb8aa3b, v21
	v_rcp_f32_e32 v26, v26
	v_rcp_f32_e32 v27, v27
	v_exp_f32_e32 v28, v28
	v_exp_f32_e32 v29, v29
	v_pk_mul_f32 v[22:23], v[22:23], v[58:59] op_sel_hi:[1,0]
	v_pk_mul_f32 v[18:19], v[18:19], v[26:27]
	v_add_f32_e32 v26, 1.0, v28
	v_add_f32_e32 v27, 1.0, v29
	v_rcp_f32_e32 v26, v26
	v_rcp_f32_e32 v27, v27
	v_pk_mul_f32 v[18:19], v[22:23], v[18:19]
	v_pk_mul_f32 v[22:23], v[24:25], v[58:59] op_sel_hi:[1,0]
	v_pk_mul_f32 v[10:11], v[10:11], v[134:135] op_sel_hi:[1,0]
	v_pk_mul_f32 v[20:21], v[20:21], v[26:27]
	v_add_u32_e32 v132, v100, v54
	v_pk_mul_f32 v[20:21], v[22:23], v[20:21]
	v_mul_f32_e32 v22, 0xbfb8aa3b, v10
	v_mul_f32_e32 v23, 0xbfb8aa3b, v11
	v_exp_f32_e32 v22, v22
	v_exp_f32_e32 v23, v23
	v_cvt_pk_bf16_f32 v18, v18, v19
	v_cvt_pk_bf16_f32 v19, v20, v21
	v_lshl_add_u64 v[20:21], v[132:133], 1, s[2:3]
	v_pk_mul_f32 v[12:13], v[12:13], v[134:135] op_sel_hi:[1,0]
	ds_write_b64 v166, v[18:19] offset:6144
	v_add_f32_e32 v18, 1.0, v22
	v_add_f32_e32 v19, 1.0, v23
	v_mul_f32_e32 v20, 0xbfb8aa3b, v12
	v_mul_f32_e32 v21, 0xbfb8aa3b, v13
	v_rcp_f32_e32 v18, v18
	v_rcp_f32_e32 v19, v19
	v_exp_f32_e32 v20, v20
	v_exp_f32_e32 v21, v21
	v_pk_mul_f32 v[14:15], v[14:15], v[134:135] op_sel_hi:[1,0]
	v_pk_mul_f32 v[10:11], v[10:11], v[18:19]
	v_add_f32_e32 v18, 1.0, v20
	v_add_f32_e32 v19, 1.0, v21
	v_rcp_f32_e32 v18, v18
	v_rcp_f32_e32 v19, v19
	v_pk_mul_f32 v[10:11], v[14:15], v[10:11]
	v_pk_mul_f32 v[14:15], v[16:17], v[134:135] op_sel_hi:[1,0]
	v_pk_mul_f32 v[2:3], v[2:3], v[58:59] op_sel_hi:[1,0]
	v_pk_mul_f32 v[12:13], v[12:13], v[18:19]
	v_add_u32_e32 v132, v84, v59
	v_pk_mul_f32 v[12:13], v[14:15], v[12:13]
	v_mul_f32_e32 v14, 0xbfb8aa3b, v2
	v_mul_f32_e32 v15, 0xbfb8aa3b, v3
	v_exp_f32_e32 v14, v14
	v_exp_f32_e32 v15, v15
	v_cvt_pk_bf16_f32 v10, v10, v11
	v_cvt_pk_bf16_f32 v11, v12, v13
	v_lshl_add_u64 v[12:13], v[132:133], 1, s[2:3]
	v_pk_mul_f32 v[4:5], v[4:5], v[58:59] op_sel_hi:[1,0]
	ds_write_b64 v167, v[10:11] offset:4096
	v_add_f32_e32 v10, 1.0, v14
	v_add_f32_e32 v11, 1.0, v15
	v_mul_f32_e32 v12, 0xbfb8aa3b, v4
	v_mul_f32_e32 v13, 0xbfb8aa3b, v5
	v_rcp_f32_e32 v10, v10
	v_rcp_f32_e32 v11, v11
	v_exp_f32_e32 v12, v12
	v_exp_f32_e32 v13, v13
	v_pk_mul_f32 v[6:7], v[6:7], v[58:59] op_sel_hi:[1,0]
	v_pk_mul_f32 v[2:3], v[2:3], v[10:11]
	v_add_f32_e32 v10, 1.0, v12
	v_add_f32_e32 v11, 1.0, v13
	v_rcp_f32_e32 v10, v10
	v_rcp_f32_e32 v11, v11
	v_pk_mul_f32 v[2:3], v[6:7], v[2:3]
	v_pk_mul_f32 v[6:7], v[8:9], v[58:59] op_sel_hi:[1,0]
	v_add_u32_e32 v132, v84, v54
	v_pk_mul_f32 v[4:5], v[4:5], v[10:11]
	v_cvt_pk_bf16_f32 v2, v2, v3
	v_pk_mul_f32 v[4:5], v[6:7], v[4:5]
	s_add_i32 s16, s16, 1
	v_cvt_pk_bf16_f32 v3, v4, v5
	v_lshl_add_u64 v[4:5], v[132:133], 1, s[2:3]
	s_andn2_b64 vcc, exec, s[4:5]
	s_mov_b32 s14, s8
	s_mov_b32 s12, s10
	ds_write_b64 v167, v[2:3] offset:6144
	s_waitcnt lgkmcnt(0)
	ds_read_b128 v[172:175], v168
	ds_read_b128 v[176:179], v168 offset:1024
	ds_read_b128 v[180:183], v168 offset:2048
	ds_read_b128 v[184:187], v168 offset:3072
	ds_read_b128 v[188:191], v168 offset:4096
	ds_read_b128 v[192:195], v168 offset:5120
	ds_read_b128 v[196:199], v168 offset:6144
	ds_read_b128 v[200:203], v168 offset:7168
	v_add_u32_e32 v204, 0x16000, v169
	v_add_u32_e32 v205, 0x2c000, v169
	v_add_u32_e32 v206, 0x42000, v169
	v_add_u32_e32 v207, 0x160000, v169
	v_add_u32_e32 v208, 0x176000, v169
	v_add_u32_e32 v209, 0x18c000, v169
	v_add_u32_e32 v210, 0x1a2000, v169
	s_waitcnt lgkmcnt(7)
	global_store_dwordx4 v169, v[172:175], s[2:3] nt
	s_waitcnt lgkmcnt(6)
	global_store_dwordx4 v204, v[176:179], s[2:3] nt
	s_waitcnt lgkmcnt(5)
	global_store_dwordx4 v205, v[180:183], s[2:3] nt
	s_waitcnt lgkmcnt(4)
	global_store_dwordx4 v206, v[184:187], s[2:3] nt
	s_waitcnt lgkmcnt(3)
	global_store_dwordx4 v207, v[188:191], s[2:3] nt
	s_waitcnt lgkmcnt(2)
	global_store_dwordx4 v208, v[192:195], s[2:3] nt
	s_waitcnt lgkmcnt(1)
	global_store_dwordx4 v209, v[196:199], s[2:3] nt
	s_waitcnt lgkmcnt(0)
	global_store_dwordx4 v210, v[200:203], s[2:3] nt
	s_cbranch_vccz .LBB0_1668
; #define STAGE(P, BASE, LD, br, kt) do { const int _so = (int)(((br) * (LD) + (kt) * BK) * 2); \
;     _Pragma("unroll") for (int _i = 0; _i < 2; ++_i) { \
;       __builtin_amdgcn_raw_ptr_buffer_load_lds(rs##BASE, (__attribute__((address_space(3))) unsigned*)((char*)(P) + tid_ * 16 + _i * 8192), 16, (int)off##LD[_i], _so, 0, 0); } } while (0)
; template <int K, int LDA, int LDB>
; DEVI void gemm_tile(const bf16* __restrict__ A, const bf16* __restrict__ Bt, bf16* shm, acc_t& acc) {
;     ...
;   __amdgpu_buffer_rsrc_t rsA = __builtin_amdgcn_make_buffer_rsrc((void*)A, 0, 0x7fffffff, 0x00020000);
;   __amdgpu_buffer_rsrc_t rsBt = __builtin_amdgcn_make_buffer_rsrc((void*)Bt, 0, 0x7fffffff, 0x00020000);
;   unsigned offLDA[2], offLDB[2];
; #pragma unroll
;   for (int _i = 0; _i < 2; ++_i) {
;     int _r, _c; stage_rc(tid_ * 16 + _i * 8192, _r, _c);
;     offLDA[_i] = (unsigned)(_r * LDA + _c) * 2u; offLDB[_i] = (unsigned)(_r * LDB + _c) * 2u;
;   }
;   STAGE(SB(0, 0), Bt, LDB, 0, 0); STAGE(SA(0, 0), A, LDA, 0, 0);
;   STAGE(SB(0, 1), Bt, LDB, HALF, 0); STAGE(SA(0, 1), A, LDA, HALF, 0);
; template <int K, int LDA, int LDB, int EPI, int GRP, int NRM, int nTk = TOK / 256>
; DEVI void gemm_phase(const bf16* W, const bf16* X, int nF, const EpiArgs& e, bf16* shm) {
;     ...
;       if (threadIdx.x < 256) rsl[(it & 1) * 256 + threadIdx.x] = nxt;
;     }
;     acc_t acc;
;     const bf16* Xp = X + (long)pm * 256 * LDB + (GRP ? (pn >> 1) * 512 : 0);
;     gemm_tile<K, LDA, LDB>(W + (long)pn * 256 * LDA, Xp, shm, acc);
	s_and_saveexec_b64 s[4:5], s[0:1]
	s_lshl_b32 s8, s16, 10
	s_and_b32 s8, s8, 0x400
	v_add_u32_e32 v2, s8, v138
	ds_write_b32 v2, v141
	s_or_b64 exec, exec, s[4:5]
	v_mov_b32_e32 v132, v131
	s_ashr_i32 s13, s12, 31
	v_bfe_i32 v4, v132, 27, 1
	v_lshlrev_b32_e32 v2, 4, v132
	v_lshrrev_b32_e32 v4, 22, v4
	v_add_u32_e32 v4, v2, v4
	v_and_b32_e32 v4, 0xfffffc00, v4
	v_sub_u32_e32 v4, v2, v4
	v_lshrrev_b32_e32 v5, 4, v4
	v_bitop3_b32 v4, v5, v4, 32 bitop3:0x6c
	s_waitcnt lgkmcnt(0)
	v_ashrrev_i32_e32 v3, 31, v132
	v_ashrrev_i32_e32 v6, 31, v4
	v_lshrrev_b32_e32 v3, 26, v3
	v_lshrrev_b32_e32 v6, 26, v6
	v_add_u32_e32 v3, v132, v3
	v_add_u32_e32 v6, v4, v6
	v_ashrrev_i32_e32 v3, 6, v3
	v_lshrrev_b32_e32 v7, 6, v6
	v_and_b32_e32 v6, 0xc0, v6
	v_lshlrev_b32_e32 v5, 3, v3
	v_lshlrev_b32_e32 v3, 5, v3
	v_sub_u32_e32 v4, v4, v6
	v_and_b32_e32 v5, 0xffff0, v5
	v_and_b32_e32 v3, 32, v3
	v_ashrrev_i16_sdwa v4, v140, sext(v4) dst_sel:DWORD dst_unused:UNUSED_PAD src0_sel:DWORD src1_sel:BYTE_0
	v_add_u32_sdwa v3, v3, sext(v4) dst_sel:DWORD dst_unused:UNUSED_PAD src0_sel:DWORD src1_sel:WORD_0
	v_add_lshl_u32 v4, v7, v5, 12
	v_lshl_add_u32 v142, v3, 1, v4
	v_add_u32_e32 v3, 0x2000, v2
	v_ashrrev_i32_e32 v4, 31, v3
	v_lshrrev_b32_e32 v4, 22, v4
	v_add_u32_e32 v4, v3, v4
	v_ashrrev_i32_e32 v4, 10, v4
	v_mul_i32_i24_e32 v5, 0x400, v4
	v_sub_u32_e32 v3, v3, v5
	v_lshrrev_b32_e32 v5, 4, v3
	v_bitop3_b32 v3, v5, v3, 32 bitop3:0x6c
	v_ashrrev_i32_e32 v6, 31, v3
	s_lshl_b64 s[4:5], s[12:13], 20
	v_lshrrev_b32_e32 v6, 26, v6
	s_add_u32 s4, s96, s4
	v_add_u32_e32 v6, v3, v6
	s_addc_u32 s5, s97, s5
	s_ashr_i32 s15, s14, 31
	v_lshrrev_b32_e32 v7, 6, v6
	v_and_b32_e32 v6, 0xc0, v6
	s_lshl_b64 s[8:9], s[14:15], 20
	v_lshlrev_b32_e32 v5, 3, v4
	v_lshlrev_b32_e32 v4, 5, v4
	v_sub_u32_e32 v3, v3, v6
	v_add_u32_e32 v146, s21, v2
	s_add_u32 s8, s19, s8
	v_and_b32_e32 v5, 0xffff0, v5
	v_and_b32_e32 v4, 32, v4
	v_ashrrev_i16_sdwa v3, v140, sext(v3) dst_sel:DWORD dst_unused:UNUSED_PAD src0_sel:DWORD src1_sel:BYTE_0
	v_readfirstlane_b32 s13, v146
	v_add_u32_e32 v147, 0x2000, v146
	s_addc_u32 s9, s20, s9
	v_add_u32_sdwa v3, v4, sext(v3) dst_sel:DWORD dst_unused:UNUSED_PAD src0_sel:DWORD src1_sel:WORD_0
	v_add_lshl_u32 v4, v7, v5, 12
	s_and_b32 s5, s5, 0xffff
	s_mov_b32 m0, s13
	v_readfirstlane_b32 s13, v147
	v_add_u32_e32 v148, 0, v2
	v_lshl_add_u32 v144, v3, 1, v4
	s_mov_b32 m0, s13
	v_readfirstlane_b32 s13, v148
	v_add_u32_e32 v149, 0x2000, v148
	s_and_b32 s9, s9, 0xffff
	s_mov_b32 s10, s6
	s_mov_b32 s11, s7
	s_mov_b32 m0, s13
	v_readfirstlane_b32 s13, v149
	v_add_u32_e32 v150, s22, v2
	s_mov_b32 m0, s13
	v_readfirstlane_b32 s13, v150
	v_add_u32_e32 v151, 0x2000, v150
	s_mov_b32 m0, s13
	v_readfirstlane_b32 s13, v151
	v_add_u32_e32 v152, 0x4000, v148
	s_mov_b32 m0, s13
	v_readfirstlane_b32 s13, v152
	v_add_u32_e32 v153, 0x6000, v148
	s_mov_b32 m0, s13
	v_readfirstlane_b32 s13, v153
	s_mov_b32 m0, s13
	v_ashrrev_i32_e32 v3, 8, v132
	s_branch .Lafter_loads_35357

; #define STAGE(P, BASE, LD, br, kt) do { const int _so = (int)(((br) * (LD) + (kt) * BK) * 2); \
;     _Pragma("unroll") for (int _i = 0; _i < 2; ++_i) { \
;       __builtin_amdgcn_raw_ptr_buffer_load_lds(rs##BASE, (__attribute__((address_space(3))) unsigned*)((char*)(P) + tid_ * 16 + _i * 8192), 16, (int)off##LD[_i], _so, 0, 0); } } while (0)
; template <int K, int LDA, int LDB>
; DEVI void gemm_tile(const bf16* __restrict__ A, const bf16* __restrict__ Bt, bf16* shm, acc_t& acc) {
;     ...
;   __amdgpu_buffer_rsrc_t rsA = __builtin_amdgcn_make_buffer_rsrc((void*)A, 0, 0x7fffffff, 0x00020000);
;   __amdgpu_buffer_rsrc_t rsBt = __builtin_amdgcn_make_buffer_rsrc((void*)Bt, 0, 0x7fffffff, 0x00020000);
;   unsigned offLDA[2], offLDB[2];
; #pragma unroll
;   for (int _i = 0; _i < 2; ++_i) {
;     int _r, _c; stage_rc(tid_ * 16 + _i * 8192, _r, _c);
;     offLDA[_i] = (unsigned)(_r * LDA + _c) * 2u; offLDB[_i] = (unsigned)(_r * LDB + _c) * 2u;
;   }
;   STAGE(SB(0, 0), Bt, LDB, 0, 0); STAGE(SA(0, 0), A, LDA, 0, 0);
;   STAGE(SB(0, 1), Bt, LDB, HALF, 0); STAGE(SA(0, 1), A, LDA, HALF, 0);
.LBB0_1664:
	s_or_b64 exec, exec, s[4:5]
	s_load_dword s4, s[84:85], 0x10
	s_waitcnt lgkmcnt(0)
	s_lshr_b32 s4, s4, 16
	s_cmp_lg_u32 s4, 0
	s_cselect_b64 s[4:5], -1, 0
	s_cmp_lg_u64 s[4:5], 0
	s_addc_u32 s42, s42, s33
	s_cmpk_gt_i32 s42, 0x15ff
	s_cselect_b64 s[4:5], -1, 0
	s_and_b64 vcc, exec, s[4:5]
	s_cbranch_vccnz .LBB0_1667
	s_ashr_i32 s8, s42, 31
	s_lshr_b32 s8, s8, 29
	s_add_i32 s8, s42, s8
	s_ashr_i32 s9, s8, 3
	s_and_b32 s8, s8, -8
	s_sub_i32 s8, s42, s8
	s_cmp_lt_i32 s8, 0
	s_cselect_b32 s10, s17, 0x2c0
	s_mul_i32 s8, s10, s8
	s_add_i32 s8, s8, s9
	s_mul_hi_i32 s9, s8, 0x2e8ba2e9
	s_lshr_b32 s10, s9, 31
	s_ashr_i32 s9, s9, 6
	s_add_i32 s9, s9, s10
	s_lshl_b32 s10, s9, 3
	s_mulk_i32 s9, 0x160
	s_sub_i32 s8, s8, s9
	s_bfe_u32 s9, s8, 0x3001c
	s_add_i32 s11, s8, s9
	s_and_b32 s9, s11, 0xfff8
	s_sub_i32 s8, s8, s9
	s_sext_i32_i16 s8, s8
	s_add_i32 s10, s10, s8
	v_mov_b32_e32 v132, v131
	v_bfe_i32 v215, v132, 27, 1
	v_lshlrev_b32_e32 v213, 4, v132
	v_lshrrev_b32_e32 v215, 22, v215
	v_add_u32_e32 v215, v213, v215
	v_and_b32_e32 v215, 0xfffffc00, v215
	v_sub_u32_e32 v215, v213, v215
	v_lshrrev_b32_e32 v216, 4, v215
	v_bitop3_b32 v215, v216, v215, 32 bitop3:0x6c
	v_ashrrev_i32_e32 v214, 31, v132
	v_ashrrev_i32_e32 v217, 31, v215
	v_lshrrev_b32_e32 v214, 26, v214
	v_lshrrev_b32_e32 v217, 26, v217
	v_add_u32_e32 v214, v132, v214
	v_add_u32_e32 v217, v215, v217
	v_ashrrev_i32_e32 v214, 6, v214
	v_lshrrev_b32_e32 v218, 6, v217
	v_and_b32_e32 v217, 0xc0, v217
	v_lshlrev_b32_e32 v216, 3, v214
	v_lshlrev_b32_e32 v214, 5, v214
	v_sub_u32_e32 v215, v215, v217
	v_and_b32_e32 v216, 0xffff0, v216
	v_and_b32_e32 v214, 32, v214
	v_ashrrev_i16_sdwa v215, v140, sext(v215) dst_sel:DWORD dst_unused:UNUSED_PAD src0_sel:DWORD src1_sel:BYTE_0
	v_add_u32_sdwa v214, v214, sext(v215) dst_sel:DWORD dst_unused:UNUSED_PAD src0_sel:DWORD src1_sel:WORD_0
	v_add_lshl_u32 v215, v218, v216, 12
	v_lshl_add_u32 v142, v214, 1, v215
	v_add_u32_e32 v214, 0x2000, v213
	v_ashrrev_i32_e32 v215, 31, v214
	v_lshrrev_b32_e32 v215, 22, v215
	v_add_u32_e32 v215, v214, v215
	v_ashrrev_i32_e32 v215, 10, v215
	v_mul_i32_i24_e32 v216, 0x400, v215
	v_sub_u32_e32 v214, v214, v216
	v_lshrrev_b32_e32 v216, 4, v214
	v_bitop3_b32 v214, v216, v214, 32 bitop3:0x6c
	v_ashrrev_i32_e32 v217, 31, v214
	v_lshrrev_b32_e32 v217, 26, v217
	v_add_u32_e32 v217, v214, v217
	v_lshrrev_b32_e32 v218, 6, v217
	v_and_b32_e32 v217, 0xc0, v217
	v_lshlrev_b32_e32 v216, 3, v215
	v_lshlrev_b32_e32 v215, 5, v215
	v_sub_u32_e32 v214, v214, v217
	v_add_u32_e32 v146, s21, v213
	v_and_b32_e32 v216, 0xffff0, v216
	v_and_b32_e32 v215, 32, v215
	v_ashrrev_i16_sdwa v214, v140, sext(v214) dst_sel:DWORD dst_unused:UNUSED_PAD src0_sel:DWORD src1_sel:BYTE_0
	v_add_u32_e32 v147, 0x2000, v146
	v_add_u32_sdwa v214, v215, sext(v214) dst_sel:DWORD dst_unused:UNUSED_PAD src0_sel:DWORD src1_sel:WORD_0
	v_add_lshl_u32 v215, v218, v216, 12
	v_add_u32_e32 v148, 0, v213
	v_lshl_add_u32 v144, v214, 1, v215
	v_add_u32_e32 v149, 0x2000, v148
	v_add_u32_e32 v150, s22, v213
	v_add_u32_e32 v151, 0x2000, v150
	v_add_u32_e32 v152, 0x4000, v148
	v_add_u32_e32 v153, 0x6000, v148
	v_ashrrev_i32_e32 v214, 8, v132
	s_sext_i32_i16 s46, s11
	s_ashr_i32 s46, s46, 3
	s_mov_b32 s48, s10
	s_ashr_i32 s49, s10, 31
	s_lshl_b64 s[48:49], s[48:49], 20
	s_add_u32 s48, s96, s48
	s_addc_u32 s49, s97, s49
	s_and_b32 s49, s49, 0xffff
	s_mov_b32 s50, s6
	s_mov_b32 s51, s7
	v_readfirstlane_b32 s45, v146
	s_mov_b32 m0, s45
	s_nop 0
	buffer_load_dwordx4 v142, s[48:51], 0 offen lds
	v_readfirstlane_b32 s45, v147
	s_mov_b32 m0, s45
	s_nop 0
	buffer_load_dwordx4 v144, s[48:51], 0 offen lds
	v_readfirstlane_b32 s45, v150
	s_mov_b32 m0, s45
	s_nop 0
	buffer_load_dwordx4 v142, s[48:51], s23 offen lds
	v_readfirstlane_b32 s45, v151
	s_mov_b32 m0, s45
	s_nop 0
	buffer_load_dwordx4 v144, s[48:51], s23 offen lds
	s_mov_b32 s48, s46
	s_ashr_i32 s49, s46, 31
	s_lshl_b64 s[48:49], s[48:49], 20
	s_add_u32 s48, s19, s48
	s_addc_u32 s49, s20, s49
	s_and_b32 s49, s49, 0xffff
	s_mov_b32 s50, s6
	s_mov_b32 s51, s7
	v_readfirstlane_b32 s45, v148
	s_mov_b32 m0, s45
	s_nop 0
	buffer_load_dwordx4 v142, s[48:51], 0 offen lds
	v_readfirstlane_b32 s45, v149
	s_mov_b32 m0, s45
	s_nop 0
	buffer_load_dwordx4 v144, s[48:51], 0 offen lds
	v_readfirstlane_b32 s45, v152
	s_mov_b32 m0, s45
	s_nop 0
	buffer_load_dwordx4 v142, s[48:51], s23 offen lds
	v_readfirstlane_b32 s45, v153
	s_mov_b32 m0, s45
	s_nop 0
	buffer_load_dwordx4 v144, s[48:51], s23 offen lds
	s_and_saveexec_b64 s[8:9], s[0:1]
	s_cbranch_execz .LBB0_1654
; template <int K, int LDA, int LDB, int EPI, int GRP, int NRM, int nTk = TOK / 256>
; DEVI void gemm_phase(const bf16* W, const bf16* X, int nF, const EpiArgs& e, bf16* shm) {
;     ...
;       if constexpr (NRM) {
;         if (threadIdx.x < 256) {
;           const int tok = pm2 * 256 + threadIdx.x;
;           float sum = 0.f;
; #pragma unroll
;           for (int i = 0; i < 16; ++i) sum += e.st[i * TOK + tok];
;           nxt = rsqrtf(sum * (1.f / DM) + 1e-6f);
;         }
;       }
	v_lshl_or_b32 v134, s10, 8, v131
	v_ashrrev_i32_e32 v135, 31, v134
	v_lshl_add_u64 v[134:135], v[134:135], 2, s[94:95]
	v_add_co_u32_e32 v136, vcc, 0x20000, v134
	s_nop 1
	v_addc_co_u32_e32 v137, vcc, 0, v135, vcc
	v_add_co_u32_e32 v142, vcc, 0x40000, v134
	s_nop 1
	v_addc_co_u32_e32 v143, vcc, 0, v135, vcc
	v_add_co_u32_e32 v144, vcc, 0x60000, v134
	s_nop 1
	v_addc_co_u32_e32 v145, vcc, 0, v135, vcc
	v_add_co_u32_e32 v146, vcc, s23, v134
	s_nop 1
	v_addc_co_u32_e32 v147, vcc, 0, v135, vcc
	v_add_co_u32_e32 v148, vcc, 0xa0000, v134
	s_nop 1
	v_addc_co_u32_e32 v149, vcc, 0, v135, vcc
	v_add_co_u32_e32 v150, vcc, 0xc0000, v134
	s_nop 1
	v_addc_co_u32_e32 v151, vcc, 0, v135, vcc
	v_add_co_u32_e32 v152, vcc, 0xe0000, v134
	s_nop 1
	v_addc_co_u32_e32 v153, vcc, 0, v135, vcc
	global_load_dword v132, v[134:135], off
	global_load_dword v141, v[136:137], off
	global_load_dword v154, v[142:143], off
	global_load_dword v155, v[144:145], off
	global_load_dword v156, v[146:147], off
	global_load_dword v157, v[148:149], off
	global_load_dword v158, v[150:151], off
	global_load_dword v159, v[152:153], off
	v_add_co_u32_e32 v136, vcc, 0x100000, v134
	s_waitcnt vmcnt(7)
	v_add_f32_e32 v132, 0, v132
	v_addc_co_u32_e32 v137, vcc, 0, v135, vcc
	v_add_co_u32_e32 v142, vcc, 0x120000, v134
	s_waitcnt vmcnt(6)
	v_add_f32_e32 v132, v132, v141
	v_addc_co_u32_e32 v143, vcc, 0, v135, vcc
	v_add_co_u32_e32 v144, vcc, 0x140000, v134
	s_waitcnt vmcnt(5)
	v_add_f32_e32 v132, v132, v154
	v_addc_co_u32_e32 v145, vcc, 0, v135, vcc
	v_add_co_u32_e32 v146, vcc, 0x160000, v134
	s_waitcnt vmcnt(4)
	v_add_f32_e32 v132, v132, v155
	v_addc_co_u32_e32 v147, vcc, 0, v135, vcc
	v_add_co_u32_e32 v148, vcc, 0x180000, v134
	s_waitcnt vmcnt(3)
	v_add_f32_e32 v132, v132, v156
	v_addc_co_u32_e32 v149, vcc, 0, v135, vcc
	v_add_co_u32_e32 v150, vcc, 0x1a0000, v134
	s_waitcnt vmcnt(2)
	v_add_f32_e32 v132, v132, v157
	v_addc_co_u32_e32 v151, vcc, 0, v135, vcc
	v_add_co_u32_e32 v152, vcc, 0x1c0000, v134
	s_waitcnt vmcnt(1)
	v_add_f32_e32 v132, v132, v158
	v_addc_co_u32_e32 v153, vcc, 0, v135, vcc
	v_add_co_u32_e32 v134, vcc, 0x1e0000, v134
	s_waitcnt vmcnt(0)
	v_add_f32_e32 v132, v132, v159
	v_addc_co_u32_e32 v135, vcc, 0, v135, vcc
	global_load_dword v136, v[136:137], off
	s_nop 0
	global_load_dword v137, v[142:143], off
	s_nop 0
	global_load_dword v142, v[144:145], off
	global_load_dword v143, v[146:147], off
	s_nop 0
	global_load_dword v144, v[148:149], off
	global_load_dword v145, v[150:151], off
	global_load_dword v146, v[152:153], off
	s_nop 0
	global_load_dword v134, v[134:135], off
	s_waitcnt vmcnt(7)
	v_add_f32_e32 v132, v132, v136
	s_waitcnt vmcnt(6)
	v_add_f32_e32 v132, v132, v137
	s_waitcnt vmcnt(5)
	v_add_f32_e32 v132, v132, v142
	s_waitcnt vmcnt(4)
	v_add_f32_e32 v132, v132, v143
	s_waitcnt vmcnt(3)
	v_add_f32_e32 v132, v132, v144
	s_waitcnt vmcnt(2)
	v_add_f32_e32 v132, v132, v145
	s_waitcnt vmcnt(1)
	v_add_f32_e32 v132, v132, v146
	s_waitcnt vmcnt(0)
	v_add_f32_e32 v132, v132, v134
	v_fmamk_f32 v132, v132, 0x3a000000, v139
	v_mul_f32_e32 v134, 0x4b800000, v132
	v_cmp_gt_f32_e32 vcc, s40, v132
	s_nop 1
	v_cndmask_b32_e32 v132, v132, v134, vcc
	v_rsq_f32_e32 v132, v132
	s_nop 0
	v_mul_f32_e32 v134, 0x45800000, v132
	v_cndmask_b32_e32 v141, v132, v134, vcc
	s_branch .LBB0_1654

; DEVI float silu(float x) { return x * __builtin_amdgcn_rcpf(1.f + __expf(-x)); }
; template <int EPI, int NRM>
; DEVI void epilogue(acc_t& acc, int pn, int trow, const EpiArgs& e, const float* rl, bf16* shmx) {
;   int tid_ = threadIdx.x; asm volatile("" : "+v"(tid_));
;   const int wid = tid_ >> 6, lane = tid_ & 63, wr = wid >> 2, wc = wid & 3, fr = lane & 15, fq = lane >> 4;
;   const int fl0 = wr * 64 + fq * 4;
;   const int tk0 = trow + wc * 32 + fr;
;   float rs[2][2];
;   if constexpr (NRM) {
; #pragma unroll
;     for (int bj = 0; bj < 2; ++bj)
; #pragma unroll
;       for (int n = 0; n < 2; ++n) rs[bj][n] = rl[wc * 32 + fr + bj * 128 + n * 16];
;     ...
; #pragma unroll
;     for (int bj = 0; bj < 2; ++bj)
; #pragma unroll
;       for (int m = 0; m < 4; ++m)
; #pragma unroll
;         for (int n = 0; n < 2; ++n) {
;           float r[4];
; #pragma unroll
;           for (int j = 0; j < 4; ++j) r[j] = silu(acc[0][bj][m][n][j] * rs[bj][n]) * (acc[1][bj][m][n][j] * rs[bj][n]);
;           uint2 o; o.x = pack2(r[0], r[1]); o.y = pack2(r[2], r[3]);
;           const unsigned off = (unsigned)((tk0 + bj * 128 + n * 16) * DFF + pn * 128 + m * 16 + fl0);
;           *reinterpret_cast<uint2*>(e.o0 + off) = o;
;         }
.LBB0_2055:
	v_and_b32_e32 v170, 15, v1
	v_bfe_u32 v171, v1, 4, 2
	v_lshrrev_b32_e32 v172, 6, v1
	v_and_b32_e32 v173, 3, v172
	v_lshrrev_b32_e32 v174, 2, v172
	v_lshlrev_b32_e32 v175, 13, v173
	v_lshl_add_u32 v175, v174, 16, v175
	v_add_u32_e32 v175, 0x8000, v175
	v_lshl_add_u32 v176, v170, 7, v175
	v_and_b32_e32 v177, 1, v171
	v_lshl_add_u32 v176, v177, 3, v176
	v_lshrrev_b32_e32 v177, 1, v171
	v_and_b32_e32 v178, 7, v170
	v_add_u32_e32 v179, 0, v177
	v_xor_b32_e32 v179, v179, v178
	v_lshl_add_u32 v164, v179, 4, v176
	v_add_u32_e32 v179, 2, v177
	v_xor_b32_e32 v179, v179, v178
	v_lshl_add_u32 v165, v179, 4, v176
	v_add_u32_e32 v179, 4, v177
	v_xor_b32_e32 v179, v179, v178
	v_lshl_add_u32 v166, v179, 4, v176
	v_add_u32_e32 v179, 6, v177
	v_xor_b32_e32 v179, v179, v178
	v_lshl_add_u32 v167, v179, 4, v176
	v_and_b32_e32 v180, 63, v1
	v_lshl_add_u32 v168, v180, 4, v175
	v_lshrrev_b32_e32 v181, 3, v180
	v_and_b32_e32 v182, 7, v180
	v_xor_b32_e32 v182, v182, v181
	s_lshl_b32 s9, s12, 8
	v_lshl_add_u32 v183, v173, 5, v181
	v_add_u32_e32 v183, s9, v183
	v_mul_u32_u24_e32 v183, 0x1600, v183
	s_lshl_b32 s9, s14, 7
	v_lshl_add_u32 v179, v174, 6, s9
	v_lshl_add_u32 v179, v182, 3, v179
	v_add_lshl_u32 v169, v183, v179, 1
	v_mov_b32_e32 v132, v1
	s_lshl_b32 s11, s16, 10
	s_and_b32 s11, s11, 0x400
	v_and_b32_e32 v141, 15, v132
	v_ashrrev_i32_e32 v142, 2, v132
	v_lshrrev_b32_e32 v143, 2, v132
	v_lshrrev_b32_e32 v132, 1, v132
	s_add_i32 s11, s11, 0
	v_and_b32_e32 v132, 0x60, v132
	s_add_i32 s11, s11, 0x20000
	v_lshlrev_b32_e32 v134, 2, v132
	v_lshlrev_b32_e32 v135, 2, v141
	v_add3_u32 v134, s11, v134, v135
	ds_read2_b32 v[136:137], v134 offset1:16
	ds_read2_b32 v[134:135], v134 offset0:128 offset1:144
	s_lshl_b32 s9, s12, 8
	v_or3_b32 v132, v141, s9, v132
	s_lshl_b32 s9, s14, 7
	s_waitcnt lgkmcnt(1)
	v_pk_mul_f32 v[122:123], v[122:123], v[136:137] op_sel_hi:[1,0]
	v_and_or_b32 v141, v143, 12, s9
	v_mul_f32_e32 v143, 0xbfb8aa3b, v122
	v_mul_f32_e32 v144, 0xbfb8aa3b, v123
	v_exp_f32_e32 v143, v143
	v_exp_f32_e32 v144, v144
	v_and_b32_e32 v142, 0xffffffc0, v142
	v_pk_mul_f32 v[124:125], v[124:125], v[136:137] op_sel_hi:[1,0]
	v_add_u32_e32 v141, v141, v142
	v_add_f32_e32 v142, 1.0, v143
	v_add_f32_e32 v143, 1.0, v144
	v_mul_f32_e32 v144, 0xbfb8aa3b, v124
	v_mul_f32_e32 v145, 0xbfb8aa3b, v125
	v_rcp_f32_e32 v142, v142
	v_rcp_f32_e32 v143, v143
	v_exp_f32_e32 v144, v144
	v_exp_f32_e32 v145, v145
	v_pk_mul_f32 v[126:127], v[126:127], v[136:137] op_sel_hi:[1,0]
	v_pk_mul_f32 v[122:123], v[122:123], v[142:143]
	v_add_f32_e32 v142, 1.0, v144
	v_add_f32_e32 v143, 1.0, v145
	v_rcp_f32_e32 v142, v142
	v_rcp_f32_e32 v143, v143
	v_pk_mul_f32 v[122:123], v[126:127], v[122:123]
	v_pk_mul_f32 v[106:107], v[106:107], v[136:137] op_sel_hi:[1,0]
	v_cvt_pk_bf16_f32 v126, v122, v123
	v_pk_mul_f32 v[122:123], v[124:125], v[142:143]
	v_pk_mul_f32 v[124:125], v[128:129], v[136:137] op_sel_hi:[1,0]
	v_pk_mul_f32 v[108:109], v[108:109], v[136:137] op_sel_hi:[1,0]
	v_pk_mul_f32 v[122:123], v[124:125], v[122:123]
	v_pk_mul_f32 v[110:111], v[110:111], v[136:137] op_sel_hi:[1,0]
	v_cvt_pk_bf16_f32 v127, v122, v123
	v_mul_lo_u32 v123, v132, s41
	v_mov_b32_e32 v122, v137
	v_pk_mul_f32 v[114:115], v[114:115], v[122:123] op_sel_hi:[1,0]
	v_add_u32_e32 v132, v141, v123
	v_mul_f32_e32 v128, 0xbfb8aa3b, v114
	v_mul_f32_e32 v129, 0xbfb8aa3b, v115
	v_exp_f32_e32 v128, v128
	v_exp_f32_e32 v129, v129
	v_lshl_add_u64 v[124:125], v[132:133], 1, s[2:3]
	v_pk_mul_f32 v[116:117], v[116:117], v[122:123] op_sel_hi:[1,0]
	ds_write_b64 v164, v[126:127]
	v_add_f32_e32 v124, 1.0, v128
	v_add_f32_e32 v125, 1.0, v129
	v_mul_f32_e32 v126, 0xbfb8aa3b, v116
	v_mul_f32_e32 v127, 0xbfb8aa3b, v117
	v_rcp_f32_e32 v124, v124
	v_rcp_f32_e32 v125, v125
	v_exp_f32_e32 v126, v126
	v_exp_f32_e32 v127, v127
	v_pk_mul_f32 v[118:119], v[118:119], v[122:123] op_sel_hi:[1,0]
	v_pk_mul_f32 v[114:115], v[114:115], v[124:125]
	v_add_f32_e32 v124, 1.0, v126
	v_add_f32_e32 v125, 1.0, v127
	v_rcp_f32_e32 v124, v124
	v_rcp_f32_e32 v125, v125
	v_pk_mul_f32 v[114:115], v[118:119], v[114:115]
	v_pk_mul_f32 v[118:119], v[120:121], v[122:123] op_sel_hi:[1,0]
	v_cvt_pk_bf16_f32 v114, v114, v115
	v_pk_mul_f32 v[116:117], v[116:117], v[124:125]
	v_pk_mul_f32 v[98:99], v[98:99], v[122:123] op_sel_hi:[1,0]
	v_pk_mul_f32 v[116:117], v[118:119], v[116:117]
	v_add_u32_e32 v118, 0x16000, v123
	v_add_u32_e32 v132, v118, v141
	v_cvt_pk_bf16_f32 v115, v116, v117
	v_lshl_add_u64 v[116:117], v[132:133], 1, s[2:3]
	ds_write_b64 v164, v[114:115] offset:2048
	v_mul_f32_e32 v114, 0xbfb8aa3b, v106
	v_mul_f32_e32 v115, 0xbfb8aa3b, v107
	v_exp_f32_e32 v114, v114
	v_exp_f32_e32 v115, v115
	v_mul_f32_e32 v117, 0xbfb8aa3b, v108
	v_mul_f32_e32 v119, 0xbfb8aa3b, v109
	v_add_f32_e32 v114, 1.0, v114
	v_add_f32_e32 v115, 1.0, v115
	v_rcp_f32_e32 v114, v114
	v_rcp_f32_e32 v115, v115
	v_exp_f32_e32 v117, v117
	v_exp_f32_e32 v119, v119
	v_or_b32_e32 v116, 16, v141
	v_pk_mul_f32 v[106:107], v[106:107], v[114:115]
	v_add_f32_e32 v114, 1.0, v117
	v_add_f32_e32 v115, 1.0, v119
	v_rcp_f32_e32 v114, v114
	v_rcp_f32_e32 v115, v115
	v_pk_mul_f32 v[106:107], v[110:111], v[106:107]
	v_pk_mul_f32 v[110:111], v[112:113], v[136:137] op_sel_hi:[1,0]
	v_add_u32_e32 v132, v116, v123
	v_pk_mul_f32 v[108:109], v[108:109], v[114:115]
	v_cvt_pk_bf16_f32 v106, v106, v107
	v_pk_mul_f32 v[108:109], v[110:111], v[108:109]
	v_mul_f32_e32 v110, 0xbfb8aa3b, v98
	v_mul_f32_e32 v111, 0xbfb8aa3b, v99
	v_exp_f32_e32 v110, v110
	v_exp_f32_e32 v111, v111
	v_cvt_pk_bf16_f32 v107, v108, v109
	v_lshl_add_u64 v[108:109], v[132:133], 1, s[2:3]
	v_pk_mul_f32 v[100:101], v[100:101], v[122:123] op_sel_hi:[1,0]
; DEVI float silu(float x) { return x * __builtin_amdgcn_rcpf(1.f + __expf(-x)); }
; template <int EPI, int NRM>
; DEVI void epilogue(acc_t& acc, int pn, int trow, const EpiArgs& e, const float* rl, bf16* shmx) {
;     ...
; #pragma unroll
;     for (int bj = 0; bj < 2; ++bj)
; #pragma unroll
;       for (int m = 0; m < 4; ++m)
; #pragma unroll
;         for (int n = 0; n < 2; ++n) {
;           float r[4];
; #pragma unroll
;           for (int j = 0; j < 4; ++j) r[j] = silu(acc[0][bj][m][n][j] * rs[bj][n]) * (acc[1][bj][m][n][j] * rs[bj][n]);
;           uint2 o; o.x = pack2(r[0], r[1]); o.y = pack2(r[2], r[3]);
;           const unsigned off = (unsigned)((tk0 + bj * 128 + n * 16) * DFF + pn * 128 + m * 16 + fl0);
;           *reinterpret_cast<uint2*>(e.o0 + off) = o;
;         }
	ds_write_b64 v165, v[106:107]
	v_add_f32_e32 v106, 1.0, v110
	v_add_f32_e32 v107, 1.0, v111
	v_mul_f32_e32 v108, 0xbfb8aa3b, v100
	v_mul_f32_e32 v109, 0xbfb8aa3b, v101
	v_rcp_f32_e32 v106, v106
	v_rcp_f32_e32 v107, v107
	v_exp_f32_e32 v108, v108
	v_exp_f32_e32 v109, v109
	v_pk_mul_f32 v[102:103], v[102:103], v[122:123] op_sel_hi:[1,0]
	v_pk_mul_f32 v[98:99], v[98:99], v[106:107]
	v_add_f32_e32 v106, 1.0, v108
	v_add_f32_e32 v107, 1.0, v109
	v_rcp_f32_e32 v106, v106
	v_rcp_f32_e32 v107, v107
	v_pk_mul_f32 v[98:99], v[102:103], v[98:99]
	v_pk_mul_f32 v[102:103], v[104:105], v[122:123] op_sel_hi:[1,0]
	v_add_u32_e32 v132, v116, v118
	v_pk_mul_f32 v[100:101], v[100:101], v[106:107]
	v_cvt_pk_bf16_f32 v98, v98, v99
	v_pk_mul_f32 v[100:101], v[102:103], v[100:101]
	v_pk_mul_f32 v[90:91], v[90:91], v[136:137] op_sel_hi:[1,0]
	v_cvt_pk_bf16_f32 v99, v100, v101
	v_lshl_add_u64 v[100:101], v[132:133], 1, s[2:3]
	ds_write_b64 v165, v[98:99] offset:2048
	v_mul_f32_e32 v98, 0xbfb8aa3b, v90
	v_mul_f32_e32 v99, 0xbfb8aa3b, v91
	v_exp_f32_e32 v98, v98
	v_exp_f32_e32 v99, v99
	v_pk_mul_f32 v[92:93], v[92:93], v[136:137] op_sel_hi:[1,0]
	v_pk_mul_f32 v[94:95], v[94:95], v[136:137] op_sel_hi:[1,0]
	v_add_f32_e32 v98, 1.0, v98
	v_add_f32_e32 v99, 1.0, v99
	v_mul_f32_e32 v101, 0xbfb8aa3b, v92
	v_mul_f32_e32 v102, 0xbfb8aa3b, v93
	v_rcp_f32_e32 v98, v98
	v_rcp_f32_e32 v99, v99
	v_exp_f32_e32 v101, v101
	v_exp_f32_e32 v102, v102
	v_pk_mul_f32 v[82:83], v[82:83], v[122:123] op_sel_hi:[1,0]
	v_pk_mul_f32 v[90:91], v[90:91], v[98:99]
	v_add_f32_e32 v98, 1.0, v101
	v_add_f32_e32 v99, 1.0, v102
	v_rcp_f32_e32 v98, v98
	v_rcp_f32_e32 v99, v99
	v_pk_mul_f32 v[90:91], v[94:95], v[90:91]
	v_pk_mul_f32 v[94:95], v[96:97], v[136:137] op_sel_hi:[1,0]
	v_or_b32_e32 v100, 32, v141
	v_pk_mul_f32 v[92:93], v[92:93], v[98:99]
	v_add_u32_e32 v132, v100, v123
	v_pk_mul_f32 v[92:93], v[94:95], v[92:93]
	v_mul_f32_e32 v94, 0xbfb8aa3b, v82
	v_mul_f32_e32 v95, 0xbfb8aa3b, v83
	v_exp_f32_e32 v94, v94
	v_exp_f32_e32 v95, v95
	v_cvt_pk_bf16_f32 v90, v90, v91
	v_cvt_pk_bf16_f32 v91, v92, v93
	v_lshl_add_u64 v[92:93], v[132:133], 1, s[2:3]
	v_pk_mul_f32 v[84:85], v[84:85], v[122:123] op_sel_hi:[1,0]
	ds_write_b64 v166, v[90:91]
	v_add_f32_e32 v90, 1.0, v94
	v_add_f32_e32 v91, 1.0, v95
	v_mul_f32_e32 v92, 0xbfb8aa3b, v84
	v_mul_f32_e32 v93, 0xbfb8aa3b, v85
	v_rcp_f32_e32 v90, v90
	v_rcp_f32_e32 v91, v91
	v_exp_f32_e32 v92, v92
	v_exp_f32_e32 v93, v93
	v_pk_mul_f32 v[86:87], v[86:87], v[122:123] op_sel_hi:[1,0]
	v_pk_mul_f32 v[82:83], v[82:83], v[90:91]
	v_add_f32_e32 v90, 1.0, v92
	v_add_f32_e32 v91, 1.0, v93
	v_rcp_f32_e32 v90, v90
	v_rcp_f32_e32 v91, v91
	v_pk_mul_f32 v[82:83], v[86:87], v[82:83]
	v_pk_mul_f32 v[86:87], v[88:89], v[122:123] op_sel_hi:[1,0]
	v_add_u32_e32 v132, v100, v118
	v_pk_mul_f32 v[84:85], v[84:85], v[90:91]
	v_cvt_pk_bf16_f32 v82, v82, v83
	v_pk_mul_f32 v[84:85], v[86:87], v[84:85]
	v_pk_mul_f32 v[74:75], v[74:75], v[136:137] op_sel_hi:[1,0]
	v_cvt_pk_bf16_f32 v83, v84, v85
	v_lshl_add_u64 v[84:85], v[132:133], 1, s[2:3]
	ds_write_b64 v166, v[82:83] offset:2048
	v_mul_f32_e32 v82, 0xbfb8aa3b, v74
	v_mul_f32_e32 v83, 0xbfb8aa3b, v75
	v_exp_f32_e32 v82, v82
	v_exp_f32_e32 v83, v83
	v_pk_mul_f32 v[76:77], v[76:77], v[136:137] op_sel_hi:[1,0]
	v_pk_mul_f32 v[78:79], v[78:79], v[136:137] op_sel_hi:[1,0]
	v_add_f32_e32 v82, 1.0, v82
	v_add_f32_e32 v83, 1.0, v83
	v_mul_f32_e32 v85, 0xbfb8aa3b, v76
	v_mul_f32_e32 v86, 0xbfb8aa3b, v77
	v_rcp_f32_e32 v82, v82
	v_rcp_f32_e32 v83, v83
	v_exp_f32_e32 v85, v85
	v_exp_f32_e32 v86, v86
	v_pk_mul_f32 v[66:67], v[66:67], v[122:123] op_sel_hi:[1,0]
	v_pk_mul_f32 v[74:75], v[74:75], v[82:83]
	v_add_f32_e32 v82, 1.0, v85
	v_add_f32_e32 v83, 1.0, v86
	v_rcp_f32_e32 v82, v82
	v_rcp_f32_e32 v83, v83
	v_pk_mul_f32 v[74:75], v[78:79], v[74:75]
	v_pk_mul_f32 v[78:79], v[80:81], v[136:137] op_sel_hi:[1,0]
	v_or_b32_e32 v84, 48, v141
	v_pk_mul_f32 v[76:77], v[76:77], v[82:83]
	v_add_u32_e32 v132, v84, v123
	v_pk_mul_f32 v[76:77], v[78:79], v[76:77]
	v_mul_f32_e32 v78, 0xbfb8aa3b, v66
	v_mul_f32_e32 v79, 0xbfb8aa3b, v67
	v_exp_f32_e32 v78, v78
	v_exp_f32_e32 v79, v79
	v_cvt_pk_bf16_f32 v74, v74, v75
	v_cvt_pk_bf16_f32 v75, v76, v77
	v_lshl_add_u64 v[76:77], v[132:133], 1, s[2:3]
	v_pk_mul_f32 v[68:69], v[68:69], v[122:123] op_sel_hi:[1,0]
	ds_write_b64 v167, v[74:75]
	v_add_f32_e32 v74, 1.0, v78
	v_add_f32_e32 v75, 1.0, v79
	v_mul_f32_e32 v76, 0xbfb8aa3b, v68
	v_mul_f32_e32 v77, 0xbfb8aa3b, v69
	v_rcp_f32_e32 v74, v74
	v_rcp_f32_e32 v75, v75
	v_exp_f32_e32 v76, v76
	v_exp_f32_e32 v77, v77
	v_pk_mul_f32 v[70:71], v[70:71], v[122:123] op_sel_hi:[1,0]
	v_pk_mul_f32 v[66:67], v[66:67], v[74:75]
	v_add_f32_e32 v74, 1.0, v76
	v_add_f32_e32 v75, 1.0, v77
	v_rcp_f32_e32 v74, v74
	v_rcp_f32_e32 v75, v75
	v_pk_mul_f32 v[66:67], v[70:71], v[66:67]
	v_pk_mul_f32 v[70:71], v[72:73], v[122:123] op_sel_hi:[1,0]
	s_waitcnt lgkmcnt(0)
	v_pk_mul_f32 v[58:59], v[58:59], v[134:135] op_sel_hi:[1,0]
	v_pk_mul_f32 v[68:69], v[68:69], v[74:75]
	v_add_u32_e32 v132, v84, v118
	v_pk_mul_f32 v[68:69], v[70:71], v[68:69]
	v_mul_f32_e32 v70, 0xbfb8aa3b, v58
	v_mul_f32_e32 v71, 0xbfb8aa3b, v59
	v_exp_f32_e32 v70, v70
	v_exp_f32_e32 v71, v71
	v_cvt_pk_bf16_f32 v66, v66, v67
	v_cvt_pk_bf16_f32 v67, v68, v69
	v_lshl_add_u64 v[68:69], v[132:133], 1, s[2:3]
	v_pk_mul_f32 v[60:61], v[60:61], v[134:135] op_sel_hi:[1,0]
	ds_write_b64 v167, v[66:67] offset:2048
	s_waitcnt lgkmcnt(0)
	ds_read_b128 v[172:175], v168
	ds_read_b128 v[176:179], v168 offset:1024
	ds_read_b128 v[180:183], v168 offset:2048
	ds_read_b128 v[184:187], v168 offset:3072
	v_add_u32_e32 v204, 0x16000, v169
	v_add_u32_e32 v205, 0x2c000, v169
	v_add_u32_e32 v206, 0x42000, v169
	s_waitcnt lgkmcnt(3)
; DEVI float silu(float x) { return x * __builtin_amdgcn_rcpf(1.f + __expf(-x)); }
; template <int EPI, int NRM>
; DEVI void epilogue(acc_t& acc, int pn, int trow, const EpiArgs& e, const float* rl, bf16* shmx) {
;     ...
; #pragma unroll
;     for (int bj = 0; bj < 2; ++bj)
; #pragma unroll
;       for (int m = 0; m < 4; ++m)
; #pragma unroll
;         for (int n = 0; n < 2; ++n) {
;           float r[4];
; #pragma unroll
;           for (int j = 0; j < 4; ++j) r[j] = silu(acc[0][bj][m][n][j] * rs[bj][n]) * (acc[1][bj][m][n][j] * rs[bj][n]);
;           uint2 o; o.x = pack2(r[0], r[1]); o.y = pack2(r[2], r[3]);
;           const unsigned off = (unsigned)((tk0 + bj * 128 + n * 16) * DFF + pn * 128 + m * 16 + fl0);
;           *reinterpret_cast<uint2*>(e.o0 + off) = o;
;         }
	global_store_dwordx4 v169, v[172:175], s[2:3] nt
	s_waitcnt lgkmcnt(2)
	global_store_dwordx4 v204, v[176:179], s[2:3] nt
	s_waitcnt lgkmcnt(1)
	global_store_dwordx4 v205, v[180:183], s[2:3] nt
	s_waitcnt lgkmcnt(0)
	global_store_dwordx4 v206, v[184:187], s[2:3] nt
	v_add_f32_e32 v66, 1.0, v70
	v_add_f32_e32 v67, 1.0, v71
	v_mul_f32_e32 v68, 0xbfb8aa3b, v60
	v_mul_f32_e32 v69, 0xbfb8aa3b, v61
	v_rcp_f32_e32 v66, v66
	v_rcp_f32_e32 v67, v67
	v_exp_f32_e32 v68, v68
	v_exp_f32_e32 v69, v69
	v_pk_mul_f32 v[62:63], v[62:63], v[134:135] op_sel_hi:[1,0]
	v_pk_mul_f32 v[58:59], v[58:59], v[66:67]
	v_add_f32_e32 v66, 1.0, v68
	v_add_f32_e32 v67, 1.0, v69
	v_rcp_f32_e32 v66, v66
	v_rcp_f32_e32 v67, v67
	v_pk_mul_f32 v[58:59], v[62:63], v[58:59]
	v_pk_mul_f32 v[42:43], v[42:43], v[134:135] op_sel_hi:[1,0]
	v_cvt_pk_bf16_f32 v62, v58, v59
	v_pk_mul_f32 v[58:59], v[60:61], v[66:67]
	v_pk_mul_f32 v[60:61], v[64:65], v[134:135] op_sel_hi:[1,0]
	v_pk_mul_f32 v[44:45], v[44:45], v[134:135] op_sel_hi:[1,0]
	v_pk_mul_f32 v[58:59], v[60:61], v[58:59]
	v_pk_mul_f32 v[46:47], v[46:47], v[134:135] op_sel_hi:[1,0]
	v_cvt_pk_bf16_f32 v63, v58, v59
	v_add_u32_e32 v59, 0xb0000, v123
	v_mov_b32_e32 v58, v135
	v_pk_mul_f32 v[50:51], v[50:51], v[58:59] op_sel_hi:[1,0]
	v_add_u32_e32 v132, v59, v141
	v_mul_f32_e32 v64, 0xbfb8aa3b, v50
	v_mul_f32_e32 v65, 0xbfb8aa3b, v51
	v_exp_f32_e32 v64, v64
	v_exp_f32_e32 v65, v65
	v_lshl_add_u64 v[60:61], v[132:133], 1, s[2:3]
	v_pk_mul_f32 v[52:53], v[52:53], v[58:59] op_sel_hi:[1,0]
	ds_write_b64 v164, v[62:63] offset:4096
	v_add_f32_e32 v60, 1.0, v64
	v_add_f32_e32 v61, 1.0, v65
	v_mul_f32_e32 v62, 0xbfb8aa3b, v52
	v_mul_f32_e32 v63, 0xbfb8aa3b, v53
	v_rcp_f32_e32 v60, v60
	v_rcp_f32_e32 v61, v61
	v_exp_f32_e32 v62, v62
	v_exp_f32_e32 v63, v63
	v_pk_mul_f32 v[54:55], v[54:55], v[58:59] op_sel_hi:[1,0]
	v_pk_mul_f32 v[50:51], v[50:51], v[60:61]
	v_add_f32_e32 v60, 1.0, v62
	v_add_f32_e32 v61, 1.0, v63
	v_rcp_f32_e32 v60, v60
	v_rcp_f32_e32 v61, v61
	v_pk_mul_f32 v[50:51], v[54:55], v[50:51]
	v_pk_mul_f32 v[54:55], v[56:57], v[58:59] op_sel_hi:[1,0]
	v_mul_f32_e32 v56, 0xbfb8aa3b, v43
	v_pk_mul_f32 v[52:53], v[52:53], v[60:61]
	v_exp_f32_e32 v56, v56
	v_pk_mul_f32 v[52:53], v[54:55], v[52:53]
	v_mul_f32_e32 v55, 0xbfb8aa3b, v42
	v_exp_f32_e32 v55, v55
	v_add_u32_e32 v54, 0xc6000, v123
	v_add_u32_e32 v132, v54, v141
	v_cvt_pk_bf16_f32 v50, v50, v51
	v_cvt_pk_bf16_f32 v51, v52, v53
	v_lshl_add_u64 v[52:53], v[132:133], 1, s[2:3]
	ds_write_b64 v164, v[50:51] offset:6144
	v_add_f32_e32 v50, 1.0, v55
	v_add_f32_e32 v51, 1.0, v56
	v_mul_f32_e32 v52, 0xbfb8aa3b, v44
	v_mul_f32_e32 v53, 0xbfb8aa3b, v45
	v_rcp_f32_e32 v50, v50
	v_rcp_f32_e32 v51, v51
	v_exp_f32_e32 v52, v52
	v_exp_f32_e32 v53, v53
	v_pk_mul_f32 v[34:35], v[34:35], v[58:59] op_sel_hi:[1,0]
	v_pk_mul_f32 v[42:43], v[42:43], v[50:51]
	v_add_f32_e32 v50, 1.0, v52
	v_add_f32_e32 v51, 1.0, v53
	v_rcp_f32_e32 v50, v50
	v_rcp_f32_e32 v51, v51
	v_pk_mul_f32 v[42:43], v[46:47], v[42:43]
	v_pk_mul_f32 v[46:47], v[48:49], v[134:135] op_sel_hi:[1,0]
	v_add_u32_e32 v132, v116, v59
	v_pk_mul_f32 v[44:45], v[44:45], v[50:51]
	v_cvt_pk_bf16_f32 v42, v42, v43
	v_pk_mul_f32 v[44:45], v[46:47], v[44:45]
	v_mul_f32_e32 v46, 0xbfb8aa3b, v34
	v_mul_f32_e32 v47, 0xbfb8aa3b, v35
	v_exp_f32_e32 v46, v46
	v_exp_f32_e32 v47, v47
	v_cvt_pk_bf16_f32 v43, v44, v45
	v_lshl_add_u64 v[44:45], v[132:133], 1, s[2:3]
	v_pk_mul_f32 v[36:37], v[36:37], v[58:59] op_sel_hi:[1,0]
	ds_write_b64 v165, v[42:43] offset:4096
	v_add_f32_e32 v42, 1.0, v46
	v_add_f32_e32 v43, 1.0, v47
	v_mul_f32_e32 v44, 0xbfb8aa3b, v36
	v_mul_f32_e32 v45, 0xbfb8aa3b, v37
	v_rcp_f32_e32 v42, v42
	v_rcp_f32_e32 v43, v43
	v_exp_f32_e32 v44, v44
	v_exp_f32_e32 v45, v45
	v_pk_mul_f32 v[38:39], v[38:39], v[58:59] op_sel_hi:[1,0]
	v_pk_mul_f32 v[34:35], v[34:35], v[42:43]
	v_add_f32_e32 v42, 1.0, v44
	v_add_f32_e32 v43, 1.0, v45
	v_rcp_f32_e32 v42, v42
	v_rcp_f32_e32 v43, v43
	v_pk_mul_f32 v[34:35], v[38:39], v[34:35]
	v_pk_mul_f32 v[38:39], v[40:41], v[58:59] op_sel_hi:[1,0]
	v_pk_mul_f32 v[26:27], v[26:27], v[134:135] op_sel_hi:[1,0]
	v_pk_mul_f32 v[36:37], v[36:37], v[42:43]
	v_add_u32_e32 v132, v116, v54
	v_pk_mul_f32 v[36:37], v[38:39], v[36:37]
	v_mul_f32_e32 v38, 0xbfb8aa3b, v26
	v_mul_f32_e32 v39, 0xbfb8aa3b, v27
	v_exp_f32_e32 v38, v38
	v_exp_f32_e32 v39, v39
	v_cvt_pk_bf16_f32 v34, v34, v35
	v_cvt_pk_bf16_f32 v35, v36, v37
	v_lshl_add_u64 v[36:37], v[132:133], 1, s[2:3]
	v_pk_mul_f32 v[28:29], v[28:29], v[134:135] op_sel_hi:[1,0]
	ds_write_b64 v165, v[34:35] offset:6144
	v_add_f32_e32 v34, 1.0, v38
	v_add_f32_e32 v35, 1.0, v39
	v_mul_f32_e32 v36, 0xbfb8aa3b, v28
	v_mul_f32_e32 v37, 0xbfb8aa3b, v29
	v_rcp_f32_e32 v34, v34
	v_rcp_f32_e32 v35, v35
	v_exp_f32_e32 v36, v36
	v_exp_f32_e32 v37, v37
	v_pk_mul_f32 v[30:31], v[30:31], v[134:135] op_sel_hi:[1,0]
	v_pk_mul_f32 v[26:27], v[26:27], v[34:35]
	v_add_f32_e32 v34, 1.0, v36
	v_add_f32_e32 v35, 1.0, v37
	v_rcp_f32_e32 v34, v34
	v_rcp_f32_e32 v35, v35
	v_pk_mul_f32 v[26:27], v[30:31], v[26:27]
	v_pk_mul_f32 v[30:31], v[32:33], v[134:135] op_sel_hi:[1,0]
	v_pk_mul_f32 v[18:19], v[18:19], v[58:59] op_sel_hi:[1,0]
	v_pk_mul_f32 v[28:29], v[28:29], v[34:35]
	v_add_u32_e32 v132, v100, v59
	v_pk_mul_f32 v[28:29], v[30:31], v[28:29]
	v_mul_f32_e32 v30, 0xbfb8aa3b, v18
	v_mul_f32_e32 v31, 0xbfb8aa3b, v19
	v_exp_f32_e32 v30, v30
	v_exp_f32_e32 v31, v31
	v_cvt_pk_bf16_f32 v26, v26, v27
	v_cvt_pk_bf16_f32 v27, v28, v29
	v_lshl_add_u64 v[28:29], v[132:133], 1, s[2:3]
	v_pk_mul_f32 v[20:21], v[20:21], v[58:59] op_sel_hi:[1,0]
	ds_write_b64 v166, v[26:27] offset:4096
	v_add_f32_e32 v26, 1.0, v30
; DEVI float silu(float x) { return x * __builtin_amdgcn_rcpf(1.f + __expf(-x)); }
; template <int EPI, int NRM>
; DEVI void epilogue(acc_t& acc, int pn, int trow, const EpiArgs& e, const float* rl, bf16* shmx) {
;     ...
; #pragma unroll
;     for (int bj = 0; bj < 2; ++bj)
; #pragma unroll
;       for (int m = 0; m < 4; ++m)
; #pragma unroll
;         for (int n = 0; n < 2; ++n) {
;           float r[4];
; #pragma unroll
;           for (int j = 0; j < 4; ++j) r[j] = silu(acc[0][bj][m][n][j] * rs[bj][n]) * (acc[1][bj][m][n][j] * rs[bj][n]);
;           uint2 o; o.x = pack2(r[0], r[1]); o.y = pack2(r[2], r[3]);
;           const unsigned off = (unsigned)((tk0 + bj * 128 + n * 16) * DFF + pn * 128 + m * 16 + fl0);
;           *reinterpret_cast<uint2*>(e.o0 + off) = o;
;         }
	v_add_f32_e32 v27, 1.0, v31
	v_mul_f32_e32 v28, 0xbfb8aa3b, v20
	v_mul_f32_e32 v29, 0xbfb8aa3b, v21
	v_rcp_f32_e32 v26, v26
	v_rcp_f32_e32 v27, v27
	v_exp_f32_e32 v28, v28
	v_exp_f32_e32 v29, v29
	v_pk_mul_f32 v[22:23], v[22:23], v[58:59] op_sel_hi:[1,0]
	v_pk_mul_f32 v[18:19], v[18:19], v[26:27]
	v_add_f32_e32 v26, 1.0, v28
	v_add_f32_e32 v27, 1.0, v29
	v_rcp_f32_e32 v26, v26
	v_rcp_f32_e32 v27, v27
	v_pk_mul_f32 v[18:19], v[22:23], v[18:19]
	v_pk_mul_f32 v[22:23], v[24:25], v[58:59] op_sel_hi:[1,0]
	v_pk_mul_f32 v[10:11], v[10:11], v[134:135] op_sel_hi:[1,0]
	v_pk_mul_f32 v[20:21], v[20:21], v[26:27]
	v_add_u32_e32 v132, v100, v54
	v_pk_mul_f32 v[20:21], v[22:23], v[20:21]
	v_mul_f32_e32 v22, 0xbfb8aa3b, v10
	v_mul_f32_e32 v23, 0xbfb8aa3b, v11
	v_exp_f32_e32 v22, v22
	v_exp_f32_e32 v23, v23
	v_cvt_pk_bf16_f32 v18, v18, v19
	v_cvt_pk_bf16_f32 v19, v20, v21
	v_lshl_add_u64 v[20:21], v[132:133], 1, s[2:3]
	v_pk_mul_f32 v[12:13], v[12:13], v[134:135] op_sel_hi:[1,0]
	ds_write_b64 v166, v[18:19] offset:6144
	v_add_f32_e32 v18, 1.0, v22
	v_add_f32_e32 v19, 1.0, v23
	v_mul_f32_e32 v20, 0xbfb8aa3b, v12
	v_mul_f32_e32 v21, 0xbfb8aa3b, v13
	v_rcp_f32_e32 v18, v18
	v_rcp_f32_e32 v19, v19
	v_exp_f32_e32 v20, v20
	v_exp_f32_e32 v21, v21
	v_pk_mul_f32 v[14:15], v[14:15], v[134:135] op_sel_hi:[1,0]
	v_pk_mul_f32 v[10:11], v[10:11], v[18:19]
	v_add_f32_e32 v18, 1.0, v20
	v_add_f32_e32 v19, 1.0, v21
	v_rcp_f32_e32 v18, v18
	v_rcp_f32_e32 v19, v19
	v_pk_mul_f32 v[10:11], v[14:15], v[10:11]
	v_pk_mul_f32 v[14:15], v[16:17], v[134:135] op_sel_hi:[1,0]
	v_pk_mul_f32 v[2:3], v[2:3], v[58:59] op_sel_hi:[1,0]
	v_pk_mul_f32 v[12:13], v[12:13], v[18:19]
	v_add_u32_e32 v132, v84, v59
	v_pk_mul_f32 v[12:13], v[14:15], v[12:13]
	v_mul_f32_e32 v14, 0xbfb8aa3b, v2
	v_mul_f32_e32 v15, 0xbfb8aa3b, v3
	v_exp_f32_e32 v14, v14
	v_exp_f32_e32 v15, v15
	v_cvt_pk_bf16_f32 v10, v10, v11
	v_cvt_pk_bf16_f32 v11, v12, v13
	v_lshl_add_u64 v[12:13], v[132:133], 1, s[2:3]
	v_pk_mul_f32 v[4:5], v[4:5], v[58:59] op_sel_hi:[1,0]
	ds_write_b64 v167, v[10:11] offset:4096
	v_add_f32_e32 v10, 1.0, v14
	v_add_f32_e32 v11, 1.0, v15
	v_mul_f32_e32 v12, 0xbfb8aa3b, v4
	v_mul_f32_e32 v13, 0xbfb8aa3b, v5
	v_rcp_f32_e32 v10, v10
	v_rcp_f32_e32 v11, v11
	v_exp_f32_e32 v12, v12
	v_exp_f32_e32 v13, v13
	v_pk_mul_f32 v[6:7], v[6:7], v[58:59] op_sel_hi:[1,0]
	v_pk_mul_f32 v[2:3], v[2:3], v[10:11]
	v_add_f32_e32 v10, 1.0, v12
	v_add_f32_e32 v11, 1.0, v13
	v_rcp_f32_e32 v10, v10
	v_rcp_f32_e32 v11, v11
	v_pk_mul_f32 v[2:3], v[6:7], v[2:3]
	v_pk_mul_f32 v[6:7], v[8:9], v[58:59] op_sel_hi:[1,0]
	v_add_u32_e32 v132, v84, v54
	v_pk_mul_f32 v[4:5], v[4:5], v[10:11]
	v_cvt_pk_bf16_f32 v2, v2, v3
	v_pk_mul_f32 v[4:5], v[6:7], v[4:5]
	s_add_i32 s16, s16, 1
	v_cvt_pk_bf16_f32 v3, v4, v5
	v_lshl_add_u64 v[4:5], v[132:133], 1, s[2:3]
	s_andn2_b64 vcc, exec, s[4:5]
	s_mov_b32 s14, s8
	s_mov_b32 s12, s10
	ds_write_b64 v167, v[2:3] offset:6144
	s_waitcnt lgkmcnt(0)
	ds_read_b128 v[172:175], v168
	ds_read_b128 v[176:179], v168 offset:1024
	ds_read_b128 v[180:183], v168 offset:2048
	ds_read_b128 v[184:187], v168 offset:3072
	ds_read_b128 v[188:191], v168 offset:4096
	ds_read_b128 v[192:195], v168 offset:5120
	ds_read_b128 v[196:199], v168 offset:6144
	ds_read_b128 v[200:203], v168 offset:7168
	v_add_u32_e32 v204, 0x16000, v169
	v_add_u32_e32 v205, 0x2c000, v169
	v_add_u32_e32 v206, 0x42000, v169
	v_add_u32_e32 v207, 0x160000, v169
	v_add_u32_e32 v208, 0x176000, v169
	v_add_u32_e32 v209, 0x18c000, v169
	v_add_u32_e32 v210, 0x1a2000, v169
	s_waitcnt lgkmcnt(7)
	global_store_dwordx4 v169, v[172:175], s[2:3] nt
	s_waitcnt lgkmcnt(6)
	global_store_dwordx4 v204, v[176:179], s[2:3] nt
	s_waitcnt lgkmcnt(5)
	global_store_dwordx4 v205, v[180:183], s[2:3] nt
	s_waitcnt lgkmcnt(4)
	global_store_dwordx4 v206, v[184:187], s[2:3] nt
	s_waitcnt lgkmcnt(3)
	global_store_dwordx4 v207, v[188:191], s[2:3] nt
	s_waitcnt lgkmcnt(2)
	global_store_dwordx4 v208, v[192:195], s[2:3] nt
	s_waitcnt lgkmcnt(1)
	global_store_dwordx4 v209, v[196:199], s[2:3] nt
	s_waitcnt lgkmcnt(0)
	global_store_dwordx4 v210, v[200:203], s[2:3] nt
	s_cbranch_vccz .LBB0_2068
; #define STAGE(P, BASE, LD, br, kt) do { const int _so = (int)(((br) * (LD) + (kt) * BK) * 2); \
;     _Pragma("unroll") for (int _i = 0; _i < 2; ++_i) { \
;       __builtin_amdgcn_raw_ptr_buffer_load_lds(rs##BASE, (__attribute__((address_space(3))) unsigned*)((char*)(P) + tid_ * 16 + _i * 8192), 16, (int)off##LD[_i], _so, 0, 0); } } while (0)
; template <int K, int LDA, int LDB>
; DEVI void gemm_tile(const bf16* __restrict__ A, const bf16* __restrict__ Bt, bf16* shm, acc_t& acc) {
;     ...
;   __amdgpu_buffer_rsrc_t rsA = __builtin_amdgcn_make_buffer_rsrc((void*)A, 0, 0x7fffffff, 0x00020000);
;   __amdgpu_buffer_rsrc_t rsBt = __builtin_amdgcn_make_buffer_rsrc((void*)Bt, 0, 0x7fffffff, 0x00020000);
;   unsigned offLDA[2], offLDB[2];
; #pragma unroll
;   for (int _i = 0; _i < 2; ++_i) {
;     int _r, _c; stage_rc(tid_ * 16 + _i * 8192, _r, _c);
;     offLDA[_i] = (unsigned)(_r * LDA + _c) * 2u; offLDB[_i] = (unsigned)(_r * LDB + _c) * 2u;
;   }
;   STAGE(SB(0, 0), Bt, LDB, 0, 0); STAGE(SA(0, 0), A, LDA, 0, 0);
;   STAGE(SB(0, 1), Bt, LDB, HALF, 0); STAGE(SA(0, 1), A, LDA, HALF, 0);
; template <int K, int LDA, int LDB, int EPI, int GRP, int NRM, int nTk = TOK / 256>
; DEVI void gemm_phase(const bf16* W, const bf16* X, int nF, const EpiArgs& e, bf16* shm) {
;     ...
;       if (threadIdx.x < 256) rsl[(it & 1) * 256 + threadIdx.x] = nxt;
;     }
;     acc_t acc;
;     const bf16* Xp = X + (long)pm * 256 * LDB + (GRP ? (pn >> 1) * 512 : 0);
;     gemm_tile<K, LDA, LDB>(W + (long)pn * 256 * LDA, Xp, shm, acc);
	s_and_saveexec_b64 s[4:5], s[0:1]
	s_lshl_b32 s8, s16, 10
	s_and_b32 s8, s8, 0x400
	v_add_u32_e32 v2, s8, v131
	ds_write_b32 v2, v140
	s_or_b64 exec, exec, s[4:5]
	v_mov_b32_e32 v132, v1
	s_ashr_i32 s13, s12, 31
	v_bfe_i32 v4, v132, 27, 1
	v_lshlrev_b32_e32 v2, 4, v132
	v_lshrrev_b32_e32 v4, 22, v4
	v_add_u32_e32 v4, v2, v4
	v_and_b32_e32 v4, 0xfffffc00, v4
	v_sub_u32_e32 v4, v2, v4
	v_lshrrev_b32_e32 v5, 4, v4
	v_bitop3_b32 v4, v5, v4, 32 bitop3:0x6c
	s_waitcnt lgkmcnt(0)
	v_ashrrev_i32_e32 v3, 31, v132
	v_ashrrev_i32_e32 v6, 31, v4
	v_lshrrev_b32_e32 v3, 26, v3
	v_lshrrev_b32_e32 v6, 26, v6
	v_add_u32_e32 v3, v132, v3
	v_add_u32_e32 v6, v4, v6
	v_ashrrev_i32_e32 v3, 6, v3
	v_lshrrev_b32_e32 v7, 6, v6
	v_and_b32_e32 v6, 0xc0, v6
	v_lshlrev_b32_e32 v5, 3, v3
	v_lshlrev_b32_e32 v3, 5, v3
	v_sub_u32_e32 v4, v4, v6
	v_and_b32_e32 v5, 0xffff0, v5
	v_and_b32_e32 v3, 32, v3
	v_ashrrev_i16_sdwa v4, v139, sext(v4) dst_sel:DWORD dst_unused:UNUSED_PAD src0_sel:DWORD src1_sel:BYTE_0
	v_add_u32_sdwa v3, v3, sext(v4) dst_sel:DWORD dst_unused:UNUSED_PAD src0_sel:DWORD src1_sel:WORD_0
	v_add_lshl_u32 v4, v7, v5, 12
	v_lshl_add_u32 v141, v3, 1, v4
	v_add_u32_e32 v3, 0x2000, v2
	v_ashrrev_i32_e32 v4, 31, v3
	v_lshrrev_b32_e32 v4, 22, v4
	v_add_u32_e32 v4, v3, v4
	v_ashrrev_i32_e32 v4, 10, v4
	v_mul_i32_i24_e32 v5, 0x400, v4
	v_sub_u32_e32 v3, v3, v5
	v_lshrrev_b32_e32 v5, 4, v3
	v_bitop3_b32 v3, v5, v3, 32 bitop3:0x6c
	v_ashrrev_i32_e32 v6, 31, v3
	s_lshl_b64 s[4:5], s[12:13], 20
	v_lshrrev_b32_e32 v6, 26, v6
	s_add_u32 s4, s96, s4
	v_add_u32_e32 v6, v3, v6
	s_addc_u32 s5, s97, s5
	s_ashr_i32 s15, s14, 31
	v_lshrrev_b32_e32 v7, 6, v6
	v_and_b32_e32 v6, 0xc0, v6
	s_lshl_b64 s[8:9], s[14:15], 20
	v_lshlrev_b32_e32 v5, 3, v4
	v_lshlrev_b32_e32 v4, 5, v4
	v_sub_u32_e32 v3, v3, v6
	v_add_u32_e32 v145, s21, v2
	s_add_u32 s8, s19, s8
	v_and_b32_e32 v5, 0xffff0, v5
	v_and_b32_e32 v4, 32, v4
	v_ashrrev_i16_sdwa v3, v139, sext(v3) dst_sel:DWORD dst_unused:UNUSED_PAD src0_sel:DWORD src1_sel:BYTE_0
	v_readfirstlane_b32 s13, v145
	v_add_u32_e32 v146, 0x2000, v145
	s_addc_u32 s9, s20, s9
	v_add_u32_sdwa v3, v4, sext(v3) dst_sel:DWORD dst_unused:UNUSED_PAD src0_sel:DWORD src1_sel:WORD_0
	v_add_lshl_u32 v4, v7, v5, 12
	s_and_b32 s5, s5, 0xffff
	s_mov_b32 m0, s13
	v_readfirstlane_b32 s13, v146
	v_add_u32_e32 v147, 0, v2
	v_lshl_add_u32 v143, v3, 1, v4
	s_mov_b32 m0, s13
	v_readfirstlane_b32 s13, v147
	v_add_u32_e32 v148, 0x2000, v147
	s_and_b32 s9, s9, 0xffff
	s_mov_b32 s10, s6
	s_mov_b32 s11, s7
	s_mov_b32 m0, s13
	v_readfirstlane_b32 s13, v148
	v_add_u32_e32 v149, s22, v2
	s_mov_b32 m0, s13
	v_readfirstlane_b32 s13, v149
	v_add_u32_e32 v150, 0x2000, v149
	s_mov_b32 m0, s13
	v_readfirstlane_b32 s13, v150
	v_add_u32_e32 v151, 0x4000, v147
	s_mov_b32 m0, s13
	v_readfirstlane_b32 s13, v151
	v_add_u32_e32 v152, 0x6000, v147
	s_mov_b32 m0, s13
	v_readfirstlane_b32 s13, v152
	s_mov_b32 m0, s13
	v_ashrrev_i32_e32 v3, 8, v132
	s_branch .Lafter_loads_46466

; #define STAGE(P, BASE, LD, br, kt) do { const int _so = (int)(((br) * (LD) + (kt) * BK) * 2); \
;     _Pragma("unroll") for (int _i = 0; _i < 2; ++_i) { \
;       __builtin_amdgcn_raw_ptr_buffer_load_lds(rs##BASE, (__attribute__((address_space(3))) unsigned*)((char*)(P) + tid_ * 16 + _i * 8192), 16, (int)off##LD[_i], _so, 0, 0); } } while (0)
; template <int K, int LDA, int LDB>
; DEVI void gemm_tile(const bf16* __restrict__ A, const bf16* __restrict__ Bt, bf16* shm, acc_t& acc) {
;     ...
;   __amdgpu_buffer_rsrc_t rsA = __builtin_amdgcn_make_buffer_rsrc((void*)A, 0, 0x7fffffff, 0x00020000);
;   __amdgpu_buffer_rsrc_t rsBt = __builtin_amdgcn_make_buffer_rsrc((void*)Bt, 0, 0x7fffffff, 0x00020000);
;   unsigned offLDA[2], offLDB[2];
; #pragma unroll
;   for (int _i = 0; _i < 2; ++_i) {
;     int _r, _c; stage_rc(tid_ * 16 + _i * 8192, _r, _c);
;     offLDA[_i] = (unsigned)(_r * LDA + _c) * 2u; offLDB[_i] = (unsigned)(_r * LDB + _c) * 2u;
;   }
;   STAGE(SB(0, 0), Bt, LDB, 0, 0); STAGE(SA(0, 0), A, LDA, 0, 0);
;   STAGE(SB(0, 1), Bt, LDB, HALF, 0); STAGE(SA(0, 1), A, LDA, HALF, 0);
.LBB0_2064:
	s_or_b64 exec, exec, s[4:5]
	s_load_dword s4, s[84:85], 0x10
	s_waitcnt lgkmcnt(0)
	s_lshr_b32 s4, s4, 16
	s_cmp_lg_u32 s4, 0
	s_cselect_b64 s[4:5], -1, 0
	s_cmp_lg_u64 s[4:5], 0
	s_addc_u32 s42, s42, s33
	s_cmpk_gt_i32 s42, 0x15ff
	s_cselect_b64 s[4:5], -1, 0
	s_and_b64 vcc, exec, s[4:5]
	s_cbranch_vccnz .LBB0_2067
	s_ashr_i32 s8, s42, 31
	s_lshr_b32 s8, s8, 29
	s_add_i32 s8, s42, s8
	s_ashr_i32 s9, s8, 3
	s_and_b32 s8, s8, -8
	s_sub_i32 s8, s42, s8
	s_cmp_lt_i32 s8, 0
	s_cselect_b32 s10, s17, 0x2c0
	s_mul_i32 s8, s10, s8
	s_add_i32 s8, s8, s9
	s_mul_hi_i32 s9, s8, 0x2e8ba2e9
	s_lshr_b32 s10, s9, 31
	s_ashr_i32 s9, s9, 6
	s_add_i32 s9, s9, s10
	s_lshl_b32 s10, s9, 3
	s_mulk_i32 s9, 0x160
	s_sub_i32 s8, s8, s9
	s_bfe_u32 s9, s8, 0x3001c
	s_add_i32 s11, s8, s9
	s_and_b32 s9, s11, 0xfff8
	s_sub_i32 s8, s8, s9
	s_sext_i32_i16 s8, s8
	s_add_i32 s10, s10, s8
	v_mov_b32_e32 v132, v1
	v_bfe_i32 v215, v132, 27, 1
	v_lshlrev_b32_e32 v213, 4, v132
	v_lshrrev_b32_e32 v215, 22, v215
	v_add_u32_e32 v215, v213, v215
	v_and_b32_e32 v215, 0xfffffc00, v215
	v_sub_u32_e32 v215, v213, v215
	v_lshrrev_b32_e32 v216, 4, v215
	v_bitop3_b32 v215, v216, v215, 32 bitop3:0x6c
	v_ashrrev_i32_e32 v214, 31, v132
	v_ashrrev_i32_e32 v217, 31, v215
	v_lshrrev_b32_e32 v214, 26, v214
	v_lshrrev_b32_e32 v217, 26, v217
	v_add_u32_e32 v214, v132, v214
	v_add_u32_e32 v217, v215, v217
	v_ashrrev_i32_e32 v214, 6, v214
	v_lshrrev_b32_e32 v218, 6, v217
	v_and_b32_e32 v217, 0xc0, v217
	v_lshlrev_b32_e32 v216, 3, v214
	v_lshlrev_b32_e32 v214, 5, v214
	v_sub_u32_e32 v215, v215, v217
	v_and_b32_e32 v216, 0xffff0, v216
	v_and_b32_e32 v214, 32, v214
	v_ashrrev_i16_sdwa v215, v139, sext(v215) dst_sel:DWORD dst_unused:UNUSED_PAD src0_sel:DWORD src1_sel:BYTE_0
	v_add_u32_sdwa v214, v214, sext(v215) dst_sel:DWORD dst_unused:UNUSED_PAD src0_sel:DWORD src1_sel:WORD_0
	v_add_lshl_u32 v215, v218, v216, 12
	v_lshl_add_u32 v141, v214, 1, v215
	v_add_u32_e32 v214, 0x2000, v213
	v_ashrrev_i32_e32 v215, 31, v214
	v_lshrrev_b32_e32 v215, 22, v215
	v_add_u32_e32 v215, v214, v215
	v_ashrrev_i32_e32 v215, 10, v215
	v_mul_i32_i24_e32 v216, 0x400, v215
	v_sub_u32_e32 v214, v214, v216
	v_lshrrev_b32_e32 v216, 4, v214
	v_bitop3_b32 v214, v216, v214, 32 bitop3:0x6c
	v_ashrrev_i32_e32 v217, 31, v214
	v_lshrrev_b32_e32 v217, 26, v217
	v_add_u32_e32 v217, v214, v217
	v_lshrrev_b32_e32 v218, 6, v217
	v_and_b32_e32 v217, 0xc0, v217
	v_lshlrev_b32_e32 v216, 3, v215
	v_lshlrev_b32_e32 v215, 5, v215
	v_sub_u32_e32 v214, v214, v217
	v_add_u32_e32 v145, s21, v213
	v_and_b32_e32 v216, 0xffff0, v216
	v_and_b32_e32 v215, 32, v215
	v_ashrrev_i16_sdwa v214, v139, sext(v214) dst_sel:DWORD dst_unused:UNUSED_PAD src0_sel:DWORD src1_sel:BYTE_0
	v_add_u32_e32 v146, 0x2000, v145
	v_add_u32_sdwa v214, v215, sext(v214) dst_sel:DWORD dst_unused:UNUSED_PAD src0_sel:DWORD src1_sel:WORD_0
	v_add_lshl_u32 v215, v218, v216, 12
	v_add_u32_e32 v147, 0, v213
	v_lshl_add_u32 v143, v214, 1, v215
	v_add_u32_e32 v148, 0x2000, v147
	v_add_u32_e32 v149, s22, v213
	v_add_u32_e32 v150, 0x2000, v149
	v_add_u32_e32 v151, 0x4000, v147
	v_add_u32_e32 v152, 0x6000, v147
	v_ashrrev_i32_e32 v214, 8, v132
	s_sext_i32_i16 s46, s11
	s_ashr_i32 s46, s46, 3
	s_mov_b32 s48, s10
	s_ashr_i32 s49, s10, 31
	s_lshl_b64 s[48:49], s[48:49], 20
	s_add_u32 s48, s96, s48
	s_addc_u32 s49, s97, s49
	s_and_b32 s49, s49, 0xffff
	s_mov_b32 s50, s6
	s_mov_b32 s51, s7
	v_readfirstlane_b32 s45, v145
	s_mov_b32 m0, s45
	s_nop 0
	buffer_load_dwordx4 v141, s[48:51], 0 offen lds
	v_readfirstlane_b32 s45, v146
	s_mov_b32 m0, s45
	s_nop 0
	buffer_load_dwordx4 v143, s[48:51], 0 offen lds
	v_readfirstlane_b32 s45, v149
	s_mov_b32 m0, s45
	s_nop 0
	buffer_load_dwordx4 v141, s[48:51], s23 offen lds
	v_readfirstlane_b32 s45, v150
	s_mov_b32 m0, s45
	s_nop 0
	buffer_load_dwordx4 v143, s[48:51], s23 offen lds
	s_mov_b32 s48, s46
	s_ashr_i32 s49, s46, 31
	s_lshl_b64 s[48:49], s[48:49], 20
	s_add_u32 s48, s19, s48
	s_addc_u32 s49, s20, s49
	s_and_b32 s49, s49, 0xffff
	s_mov_b32 s50, s6
	s_mov_b32 s51, s7
	v_readfirstlane_b32 s45, v147
	s_mov_b32 m0, s45
	s_nop 0
	buffer_load_dwordx4 v141, s[48:51], 0 offen lds
	v_readfirstlane_b32 s45, v148
	s_mov_b32 m0, s45
	s_nop 0
	buffer_load_dwordx4 v143, s[48:51], 0 offen lds
	v_readfirstlane_b32 s45, v151
	s_mov_b32 m0, s45
	s_nop 0
	buffer_load_dwordx4 v141, s[48:51], s23 offen lds
	v_readfirstlane_b32 s45, v152
	s_mov_b32 m0, s45
	s_nop 0
	buffer_load_dwordx4 v143, s[48:51], s23 offen lds
	s_and_saveexec_b64 s[8:9], s[0:1]
	s_cbranch_execz .LBB0_2054
; template <int K, int LDA, int LDB, int EPI, int GRP, int NRM, int nTk = TOK / 256>
; DEVI void gemm_phase(const bf16* W, const bf16* X, int nF, const EpiArgs& e, bf16* shm) {
;     ...
;       if constexpr (NRM) {
;         if (threadIdx.x < 256) {
;           const int tok = pm2 * 256 + threadIdx.x;
;           float sum = 0.f;
; #pragma unroll
;           for (int i = 0; i < 16; ++i) sum += e.st[i * TOK + tok];
;           nxt = rsqrtf(sum * (1.f / DM) + 1e-6f);
;         }
;       }
	v_lshl_or_b32 v134, s10, 8, v1
	v_ashrrev_i32_e32 v135, 31, v134
	v_lshl_add_u64 v[134:135], v[134:135], 2, s[94:95]
	v_add_co_u32_e32 v136, vcc, 0x20000, v134
	s_nop 1
	v_addc_co_u32_e32 v137, vcc, 0, v135, vcc
	v_add_co_u32_e32 v140, vcc, 0x40000, v134
	s_nop 1
	v_addc_co_u32_e32 v141, vcc, 0, v135, vcc
	v_add_co_u32_e32 v142, vcc, 0x60000, v134
	s_nop 1
	v_addc_co_u32_e32 v143, vcc, 0, v135, vcc
	v_add_co_u32_e32 v144, vcc, s23, v134
	s_nop 1
	v_addc_co_u32_e32 v145, vcc, 0, v135, vcc
	v_add_co_u32_e32 v146, vcc, 0xa0000, v134
	s_nop 1
	v_addc_co_u32_e32 v147, vcc, 0, v135, vcc
	v_add_co_u32_e32 v148, vcc, 0xc0000, v134
	s_nop 1
	v_addc_co_u32_e32 v149, vcc, 0, v135, vcc
	v_add_co_u32_e32 v150, vcc, 0xe0000, v134
	s_nop 1
	v_addc_co_u32_e32 v151, vcc, 0, v135, vcc
	global_load_dword v132, v[134:135], off
	global_load_dword v152, v[136:137], off
	global_load_dword v153, v[140:141], off
	global_load_dword v154, v[142:143], off
	global_load_dword v155, v[144:145], off
	global_load_dword v156, v[146:147], off
	global_load_dword v157, v[148:149], off
	global_load_dword v158, v[150:151], off
	v_add_co_u32_e32 v136, vcc, 0x100000, v134
	s_waitcnt vmcnt(7)
	v_add_f32_e32 v132, 0, v132
	v_addc_co_u32_e32 v137, vcc, 0, v135, vcc
	v_add_co_u32_e32 v140, vcc, 0x120000, v134
	s_waitcnt vmcnt(6)
	v_add_f32_e32 v132, v132, v152
	v_addc_co_u32_e32 v141, vcc, 0, v135, vcc
	v_add_co_u32_e32 v142, vcc, 0x140000, v134
	s_waitcnt vmcnt(5)
	v_add_f32_e32 v132, v132, v153
	v_addc_co_u32_e32 v143, vcc, 0, v135, vcc
	v_add_co_u32_e32 v144, vcc, 0x160000, v134
	s_waitcnt vmcnt(4)
	v_add_f32_e32 v132, v132, v154
	v_addc_co_u32_e32 v145, vcc, 0, v135, vcc
	v_add_co_u32_e32 v146, vcc, 0x180000, v134
	s_waitcnt vmcnt(3)
	v_add_f32_e32 v132, v132, v155
	v_addc_co_u32_e32 v147, vcc, 0, v135, vcc
	v_add_co_u32_e32 v148, vcc, 0x1a0000, v134
	s_waitcnt vmcnt(2)
	v_add_f32_e32 v132, v132, v156
	v_addc_co_u32_e32 v149, vcc, 0, v135, vcc
	v_add_co_u32_e32 v150, vcc, 0x1c0000, v134
	s_waitcnt vmcnt(1)
	v_add_f32_e32 v132, v132, v157
	v_addc_co_u32_e32 v151, vcc, 0, v135, vcc
	v_add_co_u32_e32 v134, vcc, 0x1e0000, v134
	s_waitcnt vmcnt(0)
	v_add_f32_e32 v132, v132, v158
	v_addc_co_u32_e32 v135, vcc, 0, v135, vcc
	global_load_dword v136, v[136:137], off
	s_nop 0
	global_load_dword v137, v[140:141], off
	s_nop 0
	global_load_dword v140, v[142:143], off
	global_load_dword v141, v[144:145], off
	s_nop 0
	global_load_dword v142, v[146:147], off
	global_load_dword v143, v[148:149], off
	global_load_dword v144, v[150:151], off
	s_nop 0
	global_load_dword v134, v[134:135], off
	s_waitcnt vmcnt(7)
	v_add_f32_e32 v132, v132, v136
	s_waitcnt vmcnt(6)
	v_add_f32_e32 v132, v132, v137
	s_waitcnt vmcnt(5)
	v_add_f32_e32 v132, v132, v140
	s_waitcnt vmcnt(4)
	v_add_f32_e32 v132, v132, v141
	s_waitcnt vmcnt(3)
	v_add_f32_e32 v132, v132, v142
	s_waitcnt vmcnt(2)
	v_add_f32_e32 v132, v132, v143
	s_waitcnt vmcnt(1)
	v_add_f32_e32 v132, v132, v144
	s_waitcnt vmcnt(0)
	v_add_f32_e32 v132, v132, v134
	v_fmamk_f32 v132, v132, 0x3a000000, v138
	v_mul_f32_e32 v134, 0x4b800000, v132
	v_cmp_gt_f32_e32 vcc, s40, v132
	s_nop 1
	v_cndmask_b32_e32 v132, v132, v134, vcc
	v_rsq_f32_e32 v132, v132
	s_nop 0
	v_mul_f32_e32 v134, 0x45800000, v132
	v_cndmask_b32_e32 v140, v132, v134, vcc
	s_branch .LBB0_2054
